# forgetting attention: one static priority raise for the younger wave half (waves 4-7) for the whole section; GEMM K loops: the vmcnt and lgkmcnt waits in front of each barrier merged into one s_waitcn
# speedup vs baseline: 1.0032x; 1.0003x over previous
; #define PG8_STAGE(bufoff, gbase, voff) do { _Pragma("unroll") for (int _i = 0; _i < 2; ++_i) \
;         __builtin_amdgcn_global_load_lds((const unsigned*)((const char*)(gbase) + (voff)[_i]), (PG8_LAS unsigned*)(lds + (bufoff) + ldsw + _i * 8192), 16, 0, 0); } while (0)
; #define PG8_LDA(dst, b, h) do { _Pragma("unroll") for (int m = 0; m < 4; ++m) _Pragma("unroll") for (int k = 0; k < 2; ++k) dst[m][k] = *(const PG8_LAS bf16x8*)(lds + PG8_SA(b, h) + aoff + m * 2048 + k * 1024); } while (0)
; #define PG8_LDB(dst, b, h) do { _Pragma("unroll") for (int n = 0; n < 2; ++n) _Pragma("unroll") for (int k = 0; k < 2; ++k) dst[n][k] = *(const PG8_LAS bf16x8*)(lds + PG8_SB(b, h) + boff + n * 2048 + k * 1024); } while (0)
; #define PG8_WAIT_V(n) asm volatile("s_waitcnt vmcnt(" #n ")" ::: "memory")
; #define PG8_WAIT_L(n) asm volatile("s_waitcnt lgkmcnt(" #n ")" ::: "memory")
; #define PG8_BAR __builtin_amdgcn_s_barrier()
; #define PG8_SCHED __builtin_amdgcn_sched_barrier(0)
; template <class Epi, class Sched, bool ALIGN_EPI = false, bool SP2 = false>
; __device__ __forceinline__ void gemm_phase(PG8_LAS unsigned char* lds, const Gemm g, const Sched& S, const Epi& E) {
;     ...
;         const bool has_next = S.next(ui + 1, nxt);
;         const char* nA = has_next ? (const char*)g.A + (size_t)nxt.pm * tstep : cA; const char* nB = has_next ? (const char*)g.Bt + (size_t)nxt.pn * tstep : cB;
;         for (int t = 0; t < nt; t += 2) {
;             const bool last = (t == nt - 2);
;             const char* a1 = cA + (size_t)(t + 1) * kstep;
;             const char* a2 = last ? nA : cA + (size_t)(t + 2) * kstep; const char* b2 = last ? nB : cB + (size_t)(t + 2) * kstep;
;             const char* a3 = a2 + kstep; const char* b3 = b2 + kstep;
;             if (last && has_next) S.a_ready(nxt);
;             if constexpr (SP2) {
;             PG8_LDB(B0, 0, 0); PG8_LDB(B1, 0, 1); PG8_SCHED; PG8_LDA(At, 0, 0); PG8_STAGE(PG8_SA(1, 1), a1 + hstep, voffA);
;             PG8_WAIT_V(8); PG8_WAIT_L(0); PG8_BAR; PG8_MMA(0, 0, At, B0); PG8_MMA(0, 1, At, B1); PG8_BAR; PG8_SCHED;
;             PG8_LDA(At, 0, 1); PG8_STAGE(PG8_SB(0, 0), b2, voffB); PG8_STAGE(PG8_SB(0, 1), b2 + hstep, voffB); PG8_STAGE(PG8_SA(0, 0), a2, voffA);
;             PG8_WAIT_V(8); PG8_WAIT_L(0); PG8_BAR; PG8_MMA(1, 0, At, B0); PG8_MMA(1, 1, At, B1); PG8_BAR; PG8_SCHED;
.Lstg_done:
	s_ashr_i32 s27, s26, 31
	s_lshl_b64 s[12:13], s[26:27], 20
	s_add_u32 s94, s18, s12
	s_addc_u32 s95, s19, s13
	s_and_b64 s[12:13], s[46:47], exec
	s_cselect_b32 s27, s95, s69
	s_cselect_b32 s86, s94, s68
	s_ashr_i32 s17, s16, 31
	s_lshl_b64 s[12:13], s[16:17], 20
	v_readlane_b32 s14, v254, 38
	v_readlane_b32 s15, v254, 39
	s_add_u32 s14, s14, s12
	s_addc_u32 s15, s15, s13
	s_and_b64 s[12:13], s[46:47], exec
	s_cselect_b32 s17, s15, s11
	s_cselect_b32 s88, s14, s10
	s_add_u32 vcc_lo, s68, 0x80080
	s_addc_u32 vcc_hi, s69, 0
	s_add_u32 s21, s10, 0x100
	s_addc_u32 s12, s11, 0
	s_mov_b32 s13, -2
	v_add_u32_e32 v218, 0x10000, v194
	s_add_u32 s10, vcc_lo, 0xfff80080
	s_addc_u32 s11, vcc_hi, -1
	s_add_i32 s84, 0, 0x10000
	s_cmp_eq_u32 s13, 28
	s_cselect_b32 s69, s27, s11
	s_cselect_b32 s68, s86, s10
	s_cselect_b32 s11, s17, s12
	s_cselect_b32 s10, s88, s21
	s_add_i32 s93, 0, 0x14000
	ds_read_b128 v[114:117], v218
	ds_read_b128 v[118:121], v218 offset:1024
	ds_read_b128 v[130:133], v218 offset:2048
	ds_read_b128 v[138:141], v218 offset:3072
	ds_read_b128 v[146:149], v218 offset:16384
	ds_read_b128 v[156:159], v218 offset:17408
	ds_read_b128 v[160:163], v218 offset:18432
	ds_read_b128 v[164:167], v218 offset:19456
	s_add_i32 m0, s2, 0xc000
	ds_read_b128 v[168:171], v199
	ds_read_b128 v[172:175], v199 offset:1024
	ds_read_b128 v[176:179], v199 offset:2048
	ds_read_b128 v[180:183], v199 offset:3072
	ds_read_b128 v[184:187], v199 offset:4096
	ds_read_b128 v[188:191], v199 offset:5120
	ds_read_b128 v[200:203], v199 offset:6144
	ds_read_b128 v[204:207], v199 offset:7168
	global_load_lds_dwordx4 v152, vcc
	s_add_i32 m0, s2, 0xe000
	s_nop 0
	global_load_lds_dwordx4 v154, vcc
	s_waitcnt vmcnt(8) lgkmcnt(0)
	s_setprio 1
	s_barrier
	v_mfma_f32_16x16x32_bf16 v[142:145], v[114:117], v[168:171], 0
	v_mfma_f32_16x16x32_bf16 v[62:65], v[130:133], v[168:171], 0
	v_mfma_f32_16x16x32_bf16 v[122:125], v[114:117], v[176:179], 0
	v_mfma_f32_16x16x32_bf16 v[50:53], v[130:133], v[176:179], 0
	v_mfma_f32_16x16x32_bf16 v[106:109], v[114:117], v[184:187], 0
	v_mfma_f32_16x16x32_bf16 v[42:45], v[130:133], v[184:187], 0
	v_mfma_f32_16x16x32_bf16 v[98:101], v[114:117], v[200:203], 0
	v_mfma_f32_16x16x32_bf16 v[34:37], v[130:133], v[200:203], 0
	v_mfma_f32_16x16x32_bf16 v[142:145], v[118:121], v[172:175], v[142:145]
	v_mfma_f32_16x16x32_bf16 v[62:65], v[138:141], v[172:175], v[62:65]
	v_mfma_f32_16x16x32_bf16 v[122:125], v[118:121], v[180:183], v[122:125]
	v_mfma_f32_16x16x32_bf16 v[50:53], v[138:141], v[180:183], v[50:53]
	v_mfma_f32_16x16x32_bf16 v[106:109], v[118:121], v[188:191], v[106:109]
	v_mfma_f32_16x16x32_bf16 v[42:45], v[138:141], v[188:191], v[42:45]
	v_mfma_f32_16x16x32_bf16 v[98:101], v[118:121], v[204:207], v[98:101]
	v_mfma_f32_16x16x32_bf16 v[34:37], v[138:141], v[204:207], v[34:37]
	v_mfma_f32_16x16x32_bf16 v[134:137], v[146:149], v[168:171], 0
	v_mfma_f32_16x16x32_bf16 v[58:61], v[160:163], v[168:171], 0
	v_mfma_f32_16x16x32_bf16 v[126:129], v[146:149], v[176:179], 0
	v_mfma_f32_16x16x32_bf16 v[54:57], v[160:163], v[176:179], 0
	v_mfma_f32_16x16x32_bf16 v[110:113], v[146:149], v[184:187], 0
	v_mfma_f32_16x16x32_bf16 v[46:49], v[160:163], v[184:187], 0
	v_mfma_f32_16x16x32_bf16 v[102:105], v[146:149], v[200:203], 0
	v_mfma_f32_16x16x32_bf16 v[38:41], v[160:163], v[200:203], 0
	v_mfma_f32_16x16x32_bf16 v[134:137], v[156:159], v[172:175], v[134:137]
	v_mfma_f32_16x16x32_bf16 v[58:61], v[164:167], v[172:175], v[58:61]
	v_mfma_f32_16x16x32_bf16 v[126:129], v[156:159], v[180:183], v[126:129]
	v_mfma_f32_16x16x32_bf16 v[54:57], v[164:167], v[180:183], v[54:57]
	v_mfma_f32_16x16x32_bf16 v[110:113], v[156:159], v[188:191], v[110:113]
	v_mfma_f32_16x16x32_bf16 v[46:49], v[164:167], v[188:191], v[46:49]
	v_mfma_f32_16x16x32_bf16 v[102:105], v[156:159], v[204:207], v[102:105]
	v_mfma_f32_16x16x32_bf16 v[38:41], v[164:167], v[204:207], v[38:41]
	s_barrier
	s_setprio 0
	s_add_i32 s84, s84, s1
	s_add_u32 s100, s10, 0x80
	s_addc_u32 s101, s11, 0
	s_mov_b32 m0, s84
	ds_read_b128 v[168:171], v199 offset:16384
	ds_read_b128 v[172:175], v199 offset:17408
	ds_read_b128 v[176:179], v199 offset:18432
	ds_read_b128 v[180:183], v199 offset:19456
	ds_read_b128 v[184:187], v199 offset:20480
	ds_read_b128 v[188:191], v199 offset:21504
	ds_read_b128 v[200:203], v199 offset:22528
	ds_read_b128 v[204:207], v199 offset:23552
	global_load_lds_dwordx4 v0, s[10:11]
	s_add_i32 m0, s84, 0x2000
	s_add_u32 s84, s10, 0x80000
	s_addc_u32 s85, s11, 0
	s_add_i32 s93, s93, s1
	global_load_lds_dwordx4 v150, s[10:11]
	s_mov_b32 m0, s93
	s_add_u32 s98, s68, 0x80
	s_addc_u32 s99, s69, 0
	global_load_lds_dwordx4 v0, s[84:85]
	s_add_i32 m0, s93, 0x2000
	s_nop 0
	global_load_lds_dwordx4 v150, s[84:85]
	s_mov_b32 m0, s2
	s_nop 0
	global_load_lds_dwordx4 v0, s[68:69]
	s_mov_b32 m0, s4
	s_nop 0
	global_load_lds_dwordx4 v150, s[68:69]
	s_waitcnt vmcnt(8) lgkmcnt(0)
	s_setprio 1
	s_barrier
; #define PG8_STAGE(bufoff, gbase, voff) do { _Pragma("unroll") for (int _i = 0; _i < 2; ++_i) \
;         __builtin_amdgcn_global_load_lds((const unsigned*)((const char*)(gbase) + (voff)[_i]), (PG8_LAS unsigned*)(lds + (bufoff) + ldsw + _i * 8192), 16, 0, 0); } while (0)
; #define PG8_LDA(dst, b, h) do { _Pragma("unroll") for (int m = 0; m < 4; ++m) _Pragma("unroll") for (int k = 0; k < 2; ++k) dst[m][k] = *(const PG8_LAS bf16x8*)(lds + PG8_SA(b, h) + aoff + m * 2048 + k * 1024); } while (0)
; #define PG8_LDB(dst, b, h) do { _Pragma("unroll") for (int n = 0; n < 2; ++n) _Pragma("unroll") for (int k = 0; k < 2; ++k) dst[n][k] = *(const PG8_LAS bf16x8*)(lds + PG8_SB(b, h) + boff + n * 2048 + k * 1024); } while (0)
; #define PG8_MMA(ai, bj, At, Bt) do { __builtin_amdgcn_s_setprio(1); _Pragma("unroll") for (int m = 0; m < 4; ++m) _Pragma("unroll") for (int n = 0; n < 2; ++n) _Pragma("unroll") for (int k = 0; k < 2; ++k) \
;         acc[ai][bj][m][n] = __builtin_amdgcn_mfma_f32_16x16x32_bf16(Bt[n][k], At[m][k], acc[ai][bj][m][n], 0, 0, 0); __builtin_amdgcn_s_setprio(0); } while (0)
; #define PG8_WAIT_V(n) asm volatile("s_waitcnt vmcnt(" #n ")" ::: "memory")
; #define PG8_WAIT_L(n) asm volatile("s_waitcnt lgkmcnt(" #n ")" ::: "memory")
; #define PG8_BAR __builtin_amdgcn_s_barrier()
; #define PG8_SCHED __builtin_amdgcn_sched_barrier(0)
; template <class Epi, class Sched, bool ALIGN_EPI = false, bool SP2 = false>
; __device__ __forceinline__ void gemm_phase(PG8_LAS unsigned char* lds, const Gemm g, const Sched& S, const Epi& E) {
;     ...
;             PG8_WAIT_V(8); PG8_WAIT_L(0); PG8_BAR; PG8_MMA(1, 0, At, B0); PG8_MMA(1, 1, At, B1); PG8_BAR; PG8_SCHED;
;             PG8_LDB(B0, 1, 0); PG8_LDB(B1, 1, 1); PG8_SCHED; PG8_LDA(At, 1, 0); PG8_STAGE(PG8_SA(0, 1), a2 + hstep, voffA);
;             PG8_WAIT_V(8); PG8_WAIT_L(0); PG8_BAR; PG8_MMA(0, 0, At, B0); PG8_MMA(0, 1, At, B1); PG8_BAR; PG8_SCHED;
	v_mfma_f32_16x16x32_bf16 v[94:97], v[114:117], v[168:171], 0
	v_mfma_f32_16x16x32_bf16 v[30:33], v[130:133], v[168:171], 0
	v_mfma_f32_16x16x32_bf16 v[82:85], v[114:117], v[176:179], 0
	v_mfma_f32_16x16x32_bf16 v[18:21], v[130:133], v[176:179], 0
	v_mfma_f32_16x16x32_bf16 v[74:77], v[114:117], v[184:187], 0
	v_mfma_f32_16x16x32_bf16 v[10:13], v[130:133], v[184:187], 0
	v_mfma_f32_16x16x32_bf16 v[66:69], v[114:117], v[200:203], 0
	v_mfma_f32_16x16x32_bf16 v[2:5], v[130:133], v[200:203], 0
	v_mfma_f32_16x16x32_bf16 v[94:97], v[118:121], v[172:175], v[94:97]
	v_mfma_f32_16x16x32_bf16 v[30:33], v[138:141], v[172:175], v[30:33]
	v_mfma_f32_16x16x32_bf16 v[82:85], v[118:121], v[180:183], v[82:85]
	v_mfma_f32_16x16x32_bf16 v[18:21], v[138:141], v[180:183], v[18:21]
	v_mfma_f32_16x16x32_bf16 v[74:77], v[118:121], v[188:191], v[74:77]
	v_mfma_f32_16x16x32_bf16 v[10:13], v[138:141], v[188:191], v[10:13]
	v_mfma_f32_16x16x32_bf16 v[66:69], v[118:121], v[204:207], v[66:69]
	v_mfma_f32_16x16x32_bf16 v[2:5], v[138:141], v[204:207], v[2:5]
	v_mfma_f32_16x16x32_bf16 v[90:93], v[146:149], v[168:171], 0
	v_mfma_f32_16x16x32_bf16 v[26:29], v[160:163], v[168:171], 0
	v_mfma_f32_16x16x32_bf16 v[86:89], v[146:149], v[176:179], 0
	v_mfma_f32_16x16x32_bf16 v[22:25], v[160:163], v[176:179], 0
	v_mfma_f32_16x16x32_bf16 v[78:81], v[146:149], v[184:187], 0
	v_mfma_f32_16x16x32_bf16 v[14:17], v[160:163], v[184:187], 0
	v_mfma_f32_16x16x32_bf16 v[70:73], v[146:149], v[200:203], 0
	v_mfma_f32_16x16x32_bf16 v[6:9], v[160:163], v[200:203], 0
	v_mfma_f32_16x16x32_bf16 v[90:93], v[156:159], v[172:175], v[90:93]
	v_mfma_f32_16x16x32_bf16 v[26:29], v[164:167], v[172:175], v[26:29]
	v_mfma_f32_16x16x32_bf16 v[86:89], v[156:159], v[180:183], v[86:89]
	v_mfma_f32_16x16x32_bf16 v[22:25], v[164:167], v[180:183], v[22:25]
	v_mfma_f32_16x16x32_bf16 v[78:81], v[156:159], v[188:191], v[78:81]
	v_mfma_f32_16x16x32_bf16 v[14:17], v[164:167], v[188:191], v[14:17]
	v_mfma_f32_16x16x32_bf16 v[70:73], v[156:159], v[204:207], v[70:73]
	v_mfma_f32_16x16x32_bf16 v[6:9], v[164:167], v[204:207], v[6:9]
	s_barrier
	s_setprio 0
	s_add_i32 s84, 0, 0x18000
	s_add_i32 s85, 0, 0x1c000
	ds_read_b128 v[114:117], v218 offset:32768
	ds_read_b128 v[118:121], v218 offset:33792
	ds_read_b128 v[130:133], v218 offset:34816
	ds_read_b128 v[138:141], v218 offset:35840
	ds_read_b128 v[146:149], v218 offset:49152
	ds_read_b128 v[156:159], v218 offset:50176
	ds_read_b128 v[160:163], v218 offset:51200
	ds_read_b128 v[164:167], v218 offset:52224
	s_add_u32 s68, s68, 0x80000
	s_addc_u32 s69, s69, 0
	s_mov_b32 m0, s5
	ds_read_b128 v[168:171], v199 offset:32768
	ds_read_b128 v[172:175], v199 offset:33792
	ds_read_b128 v[176:179], v199 offset:34816
	ds_read_b128 v[180:183], v199 offset:35840
	ds_read_b128 v[184:187], v199 offset:36864
	ds_read_b128 v[188:191], v199 offset:37888
	ds_read_b128 v[200:203], v199 offset:38912
	ds_read_b128 v[204:207], v199 offset:39936
	global_load_lds_dwordx4 v0, s[68:69]
	s_mov_b32 m0, s6
	s_nop 0
	global_load_lds_dwordx4 v150, s[68:69]
	s_waitcnt vmcnt(8) lgkmcnt(0)
	s_setprio 1
	s_barrier
	v_mfma_f32_16x16x32_bf16 v[142:145], v[114:117], v[168:171], v[142:145]
	v_mfma_f32_16x16x32_bf16 v[62:65], v[130:133], v[168:171], v[62:65]
	v_mfma_f32_16x16x32_bf16 v[122:125], v[114:117], v[176:179], v[122:125]
	v_mfma_f32_16x16x32_bf16 v[50:53], v[130:133], v[176:179], v[50:53]
	v_mfma_f32_16x16x32_bf16 v[106:109], v[114:117], v[184:187], v[106:109]
	v_mfma_f32_16x16x32_bf16 v[42:45], v[130:133], v[184:187], v[42:45]
	v_mfma_f32_16x16x32_bf16 v[98:101], v[114:117], v[200:203], v[98:101]
	v_mfma_f32_16x16x32_bf16 v[34:37], v[130:133], v[200:203], v[34:37]
	v_mfma_f32_16x16x32_bf16 v[142:145], v[118:121], v[172:175], v[142:145]
	v_mfma_f32_16x16x32_bf16 v[62:65], v[138:141], v[172:175], v[62:65]
	v_mfma_f32_16x16x32_bf16 v[122:125], v[118:121], v[180:183], v[122:125]
	v_mfma_f32_16x16x32_bf16 v[50:53], v[138:141], v[180:183], v[50:53]
	v_mfma_f32_16x16x32_bf16 v[106:109], v[118:121], v[188:191], v[106:109]
	v_mfma_f32_16x16x32_bf16 v[42:45], v[138:141], v[188:191], v[42:45]
	v_mfma_f32_16x16x32_bf16 v[98:101], v[118:121], v[204:207], v[98:101]
	v_mfma_f32_16x16x32_bf16 v[34:37], v[138:141], v[204:207], v[34:37]
	v_mfma_f32_16x16x32_bf16 v[134:137], v[146:149], v[168:171], v[134:137]
	v_mfma_f32_16x16x32_bf16 v[58:61], v[160:163], v[168:171], v[58:61]
	v_mfma_f32_16x16x32_bf16 v[126:129], v[146:149], v[176:179], v[126:129]
	v_mfma_f32_16x16x32_bf16 v[54:57], v[160:163], v[176:179], v[54:57]
	v_mfma_f32_16x16x32_bf16 v[110:113], v[146:149], v[184:187], v[110:113]
	v_mfma_f32_16x16x32_bf16 v[46:49], v[160:163], v[184:187], v[46:49]
	v_mfma_f32_16x16x32_bf16 v[102:105], v[146:149], v[200:203], v[102:105]
	v_mfma_f32_16x16x32_bf16 v[38:41], v[160:163], v[200:203], v[38:41]
	v_mfma_f32_16x16x32_bf16 v[134:137], v[156:159], v[172:175], v[134:137]
	v_mfma_f32_16x16x32_bf16 v[58:61], v[164:167], v[172:175], v[58:61]
	v_mfma_f32_16x16x32_bf16 v[126:129], v[156:159], v[180:183], v[126:129]
	v_mfma_f32_16x16x32_bf16 v[54:57], v[164:167], v[180:183], v[54:57]
	v_mfma_f32_16x16x32_bf16 v[110:113], v[156:159], v[188:191], v[110:113]
	v_mfma_f32_16x16x32_bf16 v[46:49], v[164:167], v[188:191], v[46:49]
	v_mfma_f32_16x16x32_bf16 v[102:105], v[156:159], v[204:207], v[102:105]
	v_mfma_f32_16x16x32_bf16 v[38:41], v[164:167], v[204:207], v[38:41]
	s_barrier
; #define PG8_STAGE(bufoff, gbase, voff) do { _Pragma("unroll") for (int _i = 0; _i < 2; ++_i) \
;         __builtin_amdgcn_global_load_lds((const unsigned*)((const char*)(gbase) + (voff)[_i]), (PG8_LAS unsigned*)(lds + (bufoff) + ldsw + _i * 8192), 16, 0, 0); } while (0)
; #define PG8_LDA(dst, b, h) do { _Pragma("unroll") for (int m = 0; m < 4; ++m) _Pragma("unroll") for (int k = 0; k < 2; ++k) dst[m][k] = *(const PG8_LAS bf16x8*)(lds + PG8_SA(b, h) + aoff + m * 2048 + k * 1024); } while (0)
; #define PG8_LDB(dst, b, h) do { _Pragma("unroll") for (int n = 0; n < 2; ++n) _Pragma("unroll") for (int k = 0; k < 2; ++k) dst[n][k] = *(const PG8_LAS bf16x8*)(lds + PG8_SB(b, h) + boff + n * 2048 + k * 1024); } while (0)
; #define PG8_MMA(ai, bj, At, Bt) do { __builtin_amdgcn_s_setprio(1); _Pragma("unroll") for (int m = 0; m < 4; ++m) _Pragma("unroll") for (int n = 0; n < 2; ++n) _Pragma("unroll") for (int k = 0; k < 2; ++k) \
;         acc[ai][bj][m][n] = __builtin_amdgcn_mfma_f32_16x16x32_bf16(Bt[n][k], At[m][k], acc[ai][bj][m][n], 0, 0, 0); __builtin_amdgcn_s_setprio(0); } while (0)
; #define PG8_WAIT_V(n) asm volatile("s_waitcnt vmcnt(" #n ")" ::: "memory")
; #define PG8_WAIT_L(n) asm volatile("s_waitcnt lgkmcnt(" #n ")" ::: "memory")
; #define PG8_BAR __builtin_amdgcn_s_barrier()
; #define PG8_SCHED __builtin_amdgcn_sched_barrier(0)
; template <class Epi, class Sched, bool ALIGN_EPI = false, bool SP2 = false>
; __device__ __forceinline__ void gemm_phase(PG8_LAS unsigned char* lds, const Gemm g, const Sched& S, const Epi& E) {
;     ...
;             PG8_LDB(B0, 0, 0); PG8_LDB(B1, 0, 1); PG8_SCHED; PG8_LDA(At, 0, 0); PG8_STAGE(PG8_SA(1, 1), a1 + hstep, voffA);
;             PG8_WAIT_V(8); PG8_WAIT_L(0); PG8_BAR; PG8_MMA(0, 0, At, B0); PG8_MMA(0, 1, At, B1); PG8_BAR; PG8_SCHED;
;     ...
;             PG8_LDA(At, 1, 1); PG8_STAGE(PG8_SB(1, 0), b3, voffB); PG8_STAGE(PG8_SB(1, 1), b3 + hstep, voffB); PG8_STAGE(PG8_SA(1, 0), a3, voffA);
;             PG8_WAIT_V(8); PG8_WAIT_L(0); PG8_BAR; PG8_MMA(1, 0, At, B0); PG8_MMA(1, 1, At, B1); PG8_BAR; PG8_SCHED;
	s_setprio 0
	s_add_i32 s68, s84, s1
	s_mov_b32 m0, s68
	ds_read_b128 v[168:171], v199 offset:49152
	ds_read_b128 v[172:175], v199 offset:50176
	ds_read_b128 v[176:179], v199 offset:51200
	ds_read_b128 v[180:183], v199 offset:52224
	ds_read_b128 v[184:187], v199 offset:53248
	ds_read_b128 v[188:191], v199 offset:54272
	ds_read_b128 v[200:203], v199 offset:55296
	ds_read_b128 v[204:207], v199 offset:56320
	global_load_lds_dwordx4 v0, s[100:101]
	s_add_i32 m0, s68, 0x2000
	s_add_i32 s68, s85, s1
	global_load_lds_dwordx4 v150, s[100:101]
	s_add_u32 s10, s10, 0x80080
	s_addc_u32 s11, s11, 0
	s_mov_b32 m0, s68
	s_nop 0
	global_load_lds_dwordx4 v0, s[10:11]
	s_add_i32 m0, s68, 0x2000
	s_nop 0
	global_load_lds_dwordx4 v150, s[10:11]
	s_mov_b32 m0, s7
	s_nop 0
	global_load_lds_dwordx4 v0, s[98:99]
	s_mov_b32 m0, s30
	s_nop 0
	global_load_lds_dwordx4 v150, s[98:99]
	s_waitcnt vmcnt(8) lgkmcnt(0)
	s_setprio 1
	s_barrier
	v_mfma_f32_16x16x32_bf16 v[94:97], v[114:117], v[168:171], v[94:97]
	v_mfma_f32_16x16x32_bf16 v[30:33], v[130:133], v[168:171], v[30:33]
	v_mfma_f32_16x16x32_bf16 v[82:85], v[114:117], v[176:179], v[82:85]
	v_mfma_f32_16x16x32_bf16 v[18:21], v[130:133], v[176:179], v[18:21]
	v_mfma_f32_16x16x32_bf16 v[74:77], v[114:117], v[184:187], v[74:77]
	v_mfma_f32_16x16x32_bf16 v[10:13], v[130:133], v[184:187], v[10:13]
	v_mfma_f32_16x16x32_bf16 v[66:69], v[114:117], v[200:203], v[66:69]
	v_mfma_f32_16x16x32_bf16 v[2:5], v[130:133], v[200:203], v[2:5]
	v_mfma_f32_16x16x32_bf16 v[94:97], v[118:121], v[172:175], v[94:97]
	v_mfma_f32_16x16x32_bf16 v[30:33], v[138:141], v[172:175], v[30:33]
	v_mfma_f32_16x16x32_bf16 v[82:85], v[118:121], v[180:183], v[82:85]
	v_mfma_f32_16x16x32_bf16 v[18:21], v[138:141], v[180:183], v[18:21]
	v_mfma_f32_16x16x32_bf16 v[74:77], v[118:121], v[188:191], v[74:77]
	v_mfma_f32_16x16x32_bf16 v[10:13], v[138:141], v[188:191], v[10:13]
	v_mfma_f32_16x16x32_bf16 v[66:69], v[118:121], v[204:207], v[66:69]
	v_mfma_f32_16x16x32_bf16 v[2:5], v[138:141], v[204:207], v[2:5]
	v_mfma_f32_16x16x32_bf16 v[90:93], v[146:149], v[168:171], v[90:93]
	v_mfma_f32_16x16x32_bf16 v[26:29], v[160:163], v[168:171], v[26:29]
	v_mfma_f32_16x16x32_bf16 v[86:89], v[146:149], v[176:179], v[86:89]
	v_mfma_f32_16x16x32_bf16 v[22:25], v[160:163], v[176:179], v[22:25]
	v_mfma_f32_16x16x32_bf16 v[78:81], v[146:149], v[184:187], v[78:81]
	v_mfma_f32_16x16x32_bf16 v[14:17], v[160:163], v[184:187], v[14:17]
	v_mfma_f32_16x16x32_bf16 v[70:73], v[146:149], v[200:203], v[70:73]
	v_mfma_f32_16x16x32_bf16 v[6:9], v[160:163], v[200:203], v[6:9]
	v_mfma_f32_16x16x32_bf16 v[90:93], v[156:159], v[172:175], v[90:93]
	v_mfma_f32_16x16x32_bf16 v[26:29], v[164:167], v[172:175], v[26:29]
	v_mfma_f32_16x16x32_bf16 v[86:89], v[156:159], v[180:183], v[86:89]
	v_mfma_f32_16x16x32_bf16 v[22:25], v[164:167], v[180:183], v[22:25]
	v_mfma_f32_16x16x32_bf16 v[78:81], v[156:159], v[188:191], v[78:81]
	v_mfma_f32_16x16x32_bf16 v[14:17], v[164:167], v[188:191], v[14:17]
	v_mfma_f32_16x16x32_bf16 v[70:73], v[156:159], v[204:207], v[70:73]
	v_mfma_f32_16x16x32_bf16 v[6:9], v[164:167], v[204:207], v[6:9]
	s_barrier
	s_setprio 0
	s_add_i32 s13, s13, 2
	s_add_u32 vcc_lo, vcc_lo, 0x100
	s_addc_u32 vcc_hi, vcc_hi, 0
	s_add_u32 s21, s21, 0x100
	s_addc_u32 s12, s12, 0
.LBB0_38:
	s_add_u32 s10, vcc_lo, 0xfff80080
	s_addc_u32 s11, vcc_hi, -1
	s_add_i32 s84, 0, 0x10000
	s_cmp_eq_u32 s13, 28
	s_cselect_b32 s69, s27, s11
	s_cselect_b32 s68, s86, s10
	s_cselect_b32 s11, s17, s12
	s_cselect_b32 s10, s88, s21
	s_add_i32 s93, 0, 0x14000
	ds_read_b128 v[114:117], v218
	ds_read_b128 v[118:121], v218 offset:1024
	ds_read_b128 v[130:133], v218 offset:2048
	ds_read_b128 v[138:141], v218 offset:3072
	ds_read_b128 v[146:149], v218 offset:16384
	ds_read_b128 v[156:159], v218 offset:17408
	ds_read_b128 v[160:163], v218 offset:18432
	ds_read_b128 v[164:167], v218 offset:19456
	s_add_i32 m0, s2, 0xc000
	ds_read_b128 v[168:171], v199
	ds_read_b128 v[172:175], v199 offset:1024
	ds_read_b128 v[176:179], v199 offset:2048
	ds_read_b128 v[180:183], v199 offset:3072
	ds_read_b128 v[184:187], v199 offset:4096
	ds_read_b128 v[188:191], v199 offset:5120
	ds_read_b128 v[200:203], v199 offset:6144
	ds_read_b128 v[204:207], v199 offset:7168
	global_load_lds_dwordx4 v152, vcc
	s_add_i32 m0, s2, 0xe000
	s_nop 0
	global_load_lds_dwordx4 v154, vcc
	s_waitcnt vmcnt(8) lgkmcnt(0)
	s_setprio 1
	s_barrier
	v_mfma_f32_16x16x32_bf16 v[142:145], v[114:117], v[168:171], v[142:145]
	v_mfma_f32_16x16x32_bf16 v[62:65], v[130:133], v[168:171], v[62:65]
	v_mfma_f32_16x16x32_bf16 v[122:125], v[114:117], v[176:179], v[122:125]
	v_mfma_f32_16x16x32_bf16 v[50:53], v[130:133], v[176:179], v[50:53]
	v_mfma_f32_16x16x32_bf16 v[106:109], v[114:117], v[184:187], v[106:109]
	v_mfma_f32_16x16x32_bf16 v[42:45], v[130:133], v[184:187], v[42:45]
	v_mfma_f32_16x16x32_bf16 v[98:101], v[114:117], v[200:203], v[98:101]
	v_mfma_f32_16x16x32_bf16 v[34:37], v[130:133], v[200:203], v[34:37]
	v_mfma_f32_16x16x32_bf16 v[142:145], v[118:121], v[172:175], v[142:145]
	v_mfma_f32_16x16x32_bf16 v[62:65], v[138:141], v[172:175], v[62:65]
	v_mfma_f32_16x16x32_bf16 v[122:125], v[118:121], v[180:183], v[122:125]
	v_mfma_f32_16x16x32_bf16 v[50:53], v[138:141], v[180:183], v[50:53]
	v_mfma_f32_16x16x32_bf16 v[106:109], v[118:121], v[188:191], v[106:109]
	v_mfma_f32_16x16x32_bf16 v[42:45], v[138:141], v[188:191], v[42:45]
	v_mfma_f32_16x16x32_bf16 v[98:101], v[118:121], v[204:207], v[98:101]
	v_mfma_f32_16x16x32_bf16 v[34:37], v[138:141], v[204:207], v[34:37]
	v_mfma_f32_16x16x32_bf16 v[134:137], v[146:149], v[168:171], v[134:137]
	v_mfma_f32_16x16x32_bf16 v[58:61], v[160:163], v[168:171], v[58:61]
	v_mfma_f32_16x16x32_bf16 v[126:129], v[146:149], v[176:179], v[126:129]
	v_mfma_f32_16x16x32_bf16 v[54:57], v[160:163], v[176:179], v[54:57]
	v_mfma_f32_16x16x32_bf16 v[110:113], v[146:149], v[184:187], v[110:113]
	v_mfma_f32_16x16x32_bf16 v[46:49], v[160:163], v[184:187], v[46:49]
	v_mfma_f32_16x16x32_bf16 v[102:105], v[146:149], v[200:203], v[102:105]
	v_mfma_f32_16x16x32_bf16 v[38:41], v[160:163], v[200:203], v[38:41]
	v_mfma_f32_16x16x32_bf16 v[134:137], v[156:159], v[172:175], v[134:137]
	v_mfma_f32_16x16x32_bf16 v[58:61], v[164:167], v[172:175], v[58:61]
	v_mfma_f32_16x16x32_bf16 v[126:129], v[156:159], v[180:183], v[126:129]
	v_mfma_f32_16x16x32_bf16 v[54:57], v[164:167], v[180:183], v[54:57]
	v_mfma_f32_16x16x32_bf16 v[110:113], v[156:159], v[188:191], v[110:113]
	v_mfma_f32_16x16x32_bf16 v[46:49], v[164:167], v[188:191], v[46:49]
	v_mfma_f32_16x16x32_bf16 v[102:105], v[156:159], v[204:207], v[102:105]
	v_mfma_f32_16x16x32_bf16 v[38:41], v[164:167], v[204:207], v[38:41]
	s_barrier
; #define PG8_STAGE(bufoff, gbase, voff) do { _Pragma("unroll") for (int _i = 0; _i < 2; ++_i) \
;         __builtin_amdgcn_global_load_lds((const unsigned*)((const char*)(gbase) + (voff)[_i]), (PG8_LAS unsigned*)(lds + (bufoff) + ldsw + _i * 8192), 16, 0, 0); } while (0)
; #define PG8_LDA(dst, b, h) do { _Pragma("unroll") for (int m = 0; m < 4; ++m) _Pragma("unroll") for (int k = 0; k < 2; ++k) dst[m][k] = *(const PG8_LAS bf16x8*)(lds + PG8_SA(b, h) + aoff + m * 2048 + k * 1024); } while (0)
; #define PG8_LDB(dst, b, h) do { _Pragma("unroll") for (int n = 0; n < 2; ++n) _Pragma("unroll") for (int k = 0; k < 2; ++k) dst[n][k] = *(const PG8_LAS bf16x8*)(lds + PG8_SB(b, h) + boff + n * 2048 + k * 1024); } while (0)
; #define PG8_MMA(ai, bj, At, Bt) do { __builtin_amdgcn_s_setprio(1); _Pragma("unroll") for (int m = 0; m < 4; ++m) _Pragma("unroll") for (int n = 0; n < 2; ++n) _Pragma("unroll") for (int k = 0; k < 2; ++k) \
;         acc[ai][bj][m][n] = __builtin_amdgcn_mfma_f32_16x16x32_bf16(Bt[n][k], At[m][k], acc[ai][bj][m][n], 0, 0, 0); __builtin_amdgcn_s_setprio(0); } while (0)
; #define PG8_WAIT_V(n) asm volatile("s_waitcnt vmcnt(" #n ")" ::: "memory")
; #define PG8_WAIT_L(n) asm volatile("s_waitcnt lgkmcnt(" #n ")" ::: "memory")
; #define PG8_BAR __builtin_amdgcn_s_barrier()
; #define PG8_SCHED __builtin_amdgcn_sched_barrier(0)
; template <class Epi, class Sched, bool ALIGN_EPI = false, bool SP2 = false>
; __device__ __forceinline__ void gemm_phase(PG8_LAS unsigned char* lds, const Gemm g, const Sched& S, const Epi& E) {
;     ...
;             PG8_LDA(At, 0, 1); PG8_STAGE(PG8_SB(0, 0), b2, voffB); PG8_STAGE(PG8_SB(0, 1), b2 + hstep, voffB); PG8_STAGE(PG8_SA(0, 0), a2, voffA);
;             PG8_WAIT_V(8); PG8_WAIT_L(0); PG8_BAR; PG8_MMA(1, 0, At, B0); PG8_MMA(1, 1, At, B1); PG8_BAR; PG8_SCHED;
;             PG8_LDB(B0, 1, 0); PG8_LDB(B1, 1, 1); PG8_SCHED; PG8_LDA(At, 1, 0); PG8_STAGE(PG8_SA(0, 1), a2 + hstep, voffA);
;             PG8_WAIT_V(8); PG8_WAIT_L(0); PG8_BAR; PG8_MMA(0, 0, At, B0); PG8_MMA(0, 1, At, B1); PG8_BAR; PG8_SCHED;
	s_setprio 0
	s_add_i32 s84, s84, s1
	s_add_u32 s100, s10, 0x80
	s_addc_u32 s101, s11, 0
	s_mov_b32 m0, s84
	ds_read_b128 v[168:171], v199 offset:16384
	ds_read_b128 v[172:175], v199 offset:17408
	ds_read_b128 v[176:179], v199 offset:18432
	ds_read_b128 v[180:183], v199 offset:19456
	ds_read_b128 v[184:187], v199 offset:20480
	ds_read_b128 v[188:191], v199 offset:21504
	ds_read_b128 v[200:203], v199 offset:22528
	ds_read_b128 v[204:207], v199 offset:23552
	global_load_lds_dwordx4 v0, s[10:11]
	s_add_i32 m0, s84, 0x2000
	s_add_u32 s84, s10, 0x80000
	s_addc_u32 s85, s11, 0
	s_add_i32 s93, s93, s1
	global_load_lds_dwordx4 v150, s[10:11]
	s_mov_b32 m0, s93
	s_add_u32 s98, s68, 0x80
	s_addc_u32 s99, s69, 0
	global_load_lds_dwordx4 v0, s[84:85]
	s_add_i32 m0, s93, 0x2000
	s_nop 0
	global_load_lds_dwordx4 v150, s[84:85]
	s_mov_b32 m0, s2
	s_nop 0
	global_load_lds_dwordx4 v0, s[68:69]
	s_mov_b32 m0, s4
	s_nop 0
	global_load_lds_dwordx4 v150, s[68:69]
	s_waitcnt vmcnt(8) lgkmcnt(0)
	s_setprio 1
	s_barrier
	v_mfma_f32_16x16x32_bf16 v[94:97], v[114:117], v[168:171], v[94:97]
	v_mfma_f32_16x16x32_bf16 v[30:33], v[130:133], v[168:171], v[30:33]
	v_mfma_f32_16x16x32_bf16 v[82:85], v[114:117], v[176:179], v[82:85]
	v_mfma_f32_16x16x32_bf16 v[18:21], v[130:133], v[176:179], v[18:21]
	v_mfma_f32_16x16x32_bf16 v[74:77], v[114:117], v[184:187], v[74:77]
	v_mfma_f32_16x16x32_bf16 v[10:13], v[130:133], v[184:187], v[10:13]
	v_mfma_f32_16x16x32_bf16 v[66:69], v[114:117], v[200:203], v[66:69]
	v_mfma_f32_16x16x32_bf16 v[2:5], v[130:133], v[200:203], v[2:5]
	v_mfma_f32_16x16x32_bf16 v[94:97], v[118:121], v[172:175], v[94:97]
	v_mfma_f32_16x16x32_bf16 v[30:33], v[138:141], v[172:175], v[30:33]
	v_mfma_f32_16x16x32_bf16 v[82:85], v[118:121], v[180:183], v[82:85]
	v_mfma_f32_16x16x32_bf16 v[18:21], v[138:141], v[180:183], v[18:21]
	v_mfma_f32_16x16x32_bf16 v[74:77], v[118:121], v[188:191], v[74:77]
	v_mfma_f32_16x16x32_bf16 v[10:13], v[138:141], v[188:191], v[10:13]
	v_mfma_f32_16x16x32_bf16 v[66:69], v[118:121], v[204:207], v[66:69]
	v_mfma_f32_16x16x32_bf16 v[2:5], v[138:141], v[204:207], v[2:5]
	v_mfma_f32_16x16x32_bf16 v[90:93], v[146:149], v[168:171], v[90:93]
	v_mfma_f32_16x16x32_bf16 v[26:29], v[160:163], v[168:171], v[26:29]
	v_mfma_f32_16x16x32_bf16 v[86:89], v[146:149], v[176:179], v[86:89]
	v_mfma_f32_16x16x32_bf16 v[22:25], v[160:163], v[176:179], v[22:25]
	v_mfma_f32_16x16x32_bf16 v[78:81], v[146:149], v[184:187], v[78:81]
	v_mfma_f32_16x16x32_bf16 v[14:17], v[160:163], v[184:187], v[14:17]
	v_mfma_f32_16x16x32_bf16 v[70:73], v[146:149], v[200:203], v[70:73]
	v_mfma_f32_16x16x32_bf16 v[6:9], v[160:163], v[200:203], v[6:9]
	v_mfma_f32_16x16x32_bf16 v[90:93], v[156:159], v[172:175], v[90:93]
	v_mfma_f32_16x16x32_bf16 v[26:29], v[164:167], v[172:175], v[26:29]
	v_mfma_f32_16x16x32_bf16 v[86:89], v[156:159], v[180:183], v[86:89]
	v_mfma_f32_16x16x32_bf16 v[22:25], v[164:167], v[180:183], v[22:25]
	v_mfma_f32_16x16x32_bf16 v[78:81], v[156:159], v[188:191], v[78:81]
	v_mfma_f32_16x16x32_bf16 v[14:17], v[164:167], v[188:191], v[14:17]
	v_mfma_f32_16x16x32_bf16 v[70:73], v[156:159], v[204:207], v[70:73]
	v_mfma_f32_16x16x32_bf16 v[6:9], v[164:167], v[204:207], v[6:9]
	s_barrier
	s_setprio 0
	s_add_i32 s84, 0, 0x18000
	s_add_i32 s85, 0, 0x1c000
	ds_read_b128 v[114:117], v218 offset:32768
	ds_read_b128 v[118:121], v218 offset:33792
	ds_read_b128 v[130:133], v218 offset:34816
	ds_read_b128 v[138:141], v218 offset:35840
	ds_read_b128 v[146:149], v218 offset:49152
	ds_read_b128 v[156:159], v218 offset:50176
	ds_read_b128 v[160:163], v218 offset:51200
	ds_read_b128 v[164:167], v218 offset:52224
	s_add_u32 s68, s68, 0x80000
	s_addc_u32 s69, s69, 0
	s_mov_b32 m0, s5
	ds_read_b128 v[168:171], v199 offset:32768
	ds_read_b128 v[172:175], v199 offset:33792
	ds_read_b128 v[176:179], v199 offset:34816
	ds_read_b128 v[180:183], v199 offset:35840
	ds_read_b128 v[184:187], v199 offset:36864
	ds_read_b128 v[188:191], v199 offset:37888
	ds_read_b128 v[200:203], v199 offset:38912
	ds_read_b128 v[204:207], v199 offset:39936
	global_load_lds_dwordx4 v0, s[68:69]
	s_mov_b32 m0, s6
	s_nop 0
	global_load_lds_dwordx4 v150, s[68:69]
	s_waitcnt vmcnt(8) lgkmcnt(0)
	s_setprio 1
	s_barrier
; #define PG8_STAGE(bufoff, gbase, voff) do { _Pragma("unroll") for (int _i = 0; _i < 2; ++_i) \
;         __builtin_amdgcn_global_load_lds((const unsigned*)((const char*)(gbase) + (voff)[_i]), (PG8_LAS unsigned*)(lds + (bufoff) + ldsw + _i * 8192), 16, 0, 0); } while (0)
; #define PG8_LDA(dst, b, h) do { _Pragma("unroll") for (int m = 0; m < 4; ++m) _Pragma("unroll") for (int k = 0; k < 2; ++k) dst[m][k] = *(const PG8_LAS bf16x8*)(lds + PG8_SA(b, h) + aoff + m * 2048 + k * 1024); } while (0)
; #define PG8_MMA(ai, bj, At, Bt) do { __builtin_amdgcn_s_setprio(1); _Pragma("unroll") for (int m = 0; m < 4; ++m) _Pragma("unroll") for (int n = 0; n < 2; ++n) _Pragma("unroll") for (int k = 0; k < 2; ++k) \
;         acc[ai][bj][m][n] = __builtin_amdgcn_mfma_f32_16x16x32_bf16(Bt[n][k], At[m][k], acc[ai][bj][m][n], 0, 0, 0); __builtin_amdgcn_s_setprio(0); } while (0)
; #define PG8_WAIT_V(n) asm volatile("s_waitcnt vmcnt(" #n ")" ::: "memory")
; #define PG8_WAIT_L(n) asm volatile("s_waitcnt lgkmcnt(" #n ")" ::: "memory")
; #define PG8_BAR __builtin_amdgcn_s_barrier()
; #define PG8_SCHED __builtin_amdgcn_sched_barrier(0)
; template <class Epi, class Sched, bool ALIGN_EPI = false, bool SP2 = false>
; __device__ __forceinline__ void gemm_phase(PG8_LAS unsigned char* lds, const Gemm g, const Sched& S, const Epi& E) {
;     ...
;         for (int t = 0; t < nt; t += 2) {
;     ...
;             PG8_WAIT_V(8); PG8_WAIT_L(0); PG8_BAR; PG8_MMA(0, 0, At, B0); PG8_MMA(0, 1, At, B1); PG8_BAR; PG8_SCHED;
;             PG8_LDA(At, 1, 1); PG8_STAGE(PG8_SB(1, 0), b3, voffB); PG8_STAGE(PG8_SB(1, 1), b3 + hstep, voffB); PG8_STAGE(PG8_SA(1, 0), a3, voffA);
;             PG8_WAIT_V(8); PG8_WAIT_L(0); PG8_BAR; PG8_MMA(1, 0, At, B0); PG8_MMA(1, 1, At, B1); PG8_BAR; PG8_SCHED;
	v_mfma_f32_16x16x32_bf16 v[142:145], v[114:117], v[168:171], v[142:145]
	v_mfma_f32_16x16x32_bf16 v[62:65], v[130:133], v[168:171], v[62:65]
	v_mfma_f32_16x16x32_bf16 v[122:125], v[114:117], v[176:179], v[122:125]
	v_mfma_f32_16x16x32_bf16 v[50:53], v[130:133], v[176:179], v[50:53]
	v_mfma_f32_16x16x32_bf16 v[106:109], v[114:117], v[184:187], v[106:109]
	v_mfma_f32_16x16x32_bf16 v[42:45], v[130:133], v[184:187], v[42:45]
	v_mfma_f32_16x16x32_bf16 v[98:101], v[114:117], v[200:203], v[98:101]
	v_mfma_f32_16x16x32_bf16 v[34:37], v[130:133], v[200:203], v[34:37]
	v_mfma_f32_16x16x32_bf16 v[142:145], v[118:121], v[172:175], v[142:145]
	v_mfma_f32_16x16x32_bf16 v[62:65], v[138:141], v[172:175], v[62:65]
	v_mfma_f32_16x16x32_bf16 v[122:125], v[118:121], v[180:183], v[122:125]
	v_mfma_f32_16x16x32_bf16 v[50:53], v[138:141], v[180:183], v[50:53]
	v_mfma_f32_16x16x32_bf16 v[106:109], v[118:121], v[188:191], v[106:109]
	v_mfma_f32_16x16x32_bf16 v[42:45], v[138:141], v[188:191], v[42:45]
	v_mfma_f32_16x16x32_bf16 v[98:101], v[118:121], v[204:207], v[98:101]
	v_mfma_f32_16x16x32_bf16 v[34:37], v[138:141], v[204:207], v[34:37]
	v_mfma_f32_16x16x32_bf16 v[134:137], v[146:149], v[168:171], v[134:137]
	v_mfma_f32_16x16x32_bf16 v[58:61], v[160:163], v[168:171], v[58:61]
	v_mfma_f32_16x16x32_bf16 v[126:129], v[146:149], v[176:179], v[126:129]
	v_mfma_f32_16x16x32_bf16 v[54:57], v[160:163], v[176:179], v[54:57]
	v_mfma_f32_16x16x32_bf16 v[110:113], v[146:149], v[184:187], v[110:113]
	v_mfma_f32_16x16x32_bf16 v[46:49], v[160:163], v[184:187], v[46:49]
	v_mfma_f32_16x16x32_bf16 v[102:105], v[146:149], v[200:203], v[102:105]
	v_mfma_f32_16x16x32_bf16 v[38:41], v[160:163], v[200:203], v[38:41]
	v_mfma_f32_16x16x32_bf16 v[134:137], v[156:159], v[172:175], v[134:137]
	v_mfma_f32_16x16x32_bf16 v[58:61], v[164:167], v[172:175], v[58:61]
	v_mfma_f32_16x16x32_bf16 v[126:129], v[156:159], v[180:183], v[126:129]
	v_mfma_f32_16x16x32_bf16 v[54:57], v[164:167], v[180:183], v[54:57]
	v_mfma_f32_16x16x32_bf16 v[110:113], v[156:159], v[188:191], v[110:113]
	v_mfma_f32_16x16x32_bf16 v[46:49], v[164:167], v[188:191], v[46:49]
	v_mfma_f32_16x16x32_bf16 v[102:105], v[156:159], v[204:207], v[102:105]
	v_mfma_f32_16x16x32_bf16 v[38:41], v[164:167], v[204:207], v[38:41]
	s_barrier
	s_setprio 0
	s_add_i32 s68, s84, s1
	s_mov_b32 m0, s68
	ds_read_b128 v[168:171], v199 offset:49152
	ds_read_b128 v[172:175], v199 offset:50176
	ds_read_b128 v[176:179], v199 offset:51200
	ds_read_b128 v[180:183], v199 offset:52224
	ds_read_b128 v[184:187], v199 offset:53248
	ds_read_b128 v[188:191], v199 offset:54272
	ds_read_b128 v[200:203], v199 offset:55296
	ds_read_b128 v[204:207], v199 offset:56320
	global_load_lds_dwordx4 v0, s[100:101]
	s_add_i32 m0, s68, 0x2000
	s_add_i32 s68, s85, s1
	global_load_lds_dwordx4 v150, s[100:101]
	s_add_u32 s10, s10, 0x80080
	s_addc_u32 s11, s11, 0
	s_mov_b32 m0, s68
	s_nop 0
	global_load_lds_dwordx4 v0, s[10:11]
	s_add_i32 m0, s68, 0x2000
	s_nop 0
	global_load_lds_dwordx4 v150, s[10:11]
	s_mov_b32 m0, s7
	s_nop 0
	global_load_lds_dwordx4 v0, s[98:99]
	s_mov_b32 m0, s30
	s_nop 0
	global_load_lds_dwordx4 v150, s[98:99]
	s_waitcnt vmcnt(8) lgkmcnt(0)
	s_setprio 1
	s_barrier
	v_mfma_f32_16x16x32_bf16 v[94:97], v[114:117], v[168:171], v[94:97]
	v_mfma_f32_16x16x32_bf16 v[30:33], v[130:133], v[168:171], v[30:33]
	v_mfma_f32_16x16x32_bf16 v[82:85], v[114:117], v[176:179], v[82:85]
	v_mfma_f32_16x16x32_bf16 v[18:21], v[130:133], v[176:179], v[18:21]
	v_mfma_f32_16x16x32_bf16 v[74:77], v[114:117], v[184:187], v[74:77]
	v_mfma_f32_16x16x32_bf16 v[10:13], v[130:133], v[184:187], v[10:13]
	v_mfma_f32_16x16x32_bf16 v[66:69], v[114:117], v[200:203], v[66:69]
	v_mfma_f32_16x16x32_bf16 v[2:5], v[130:133], v[200:203], v[2:5]
	v_mfma_f32_16x16x32_bf16 v[94:97], v[118:121], v[172:175], v[94:97]
	v_mfma_f32_16x16x32_bf16 v[30:33], v[138:141], v[172:175], v[30:33]
	v_mfma_f32_16x16x32_bf16 v[82:85], v[118:121], v[180:183], v[82:85]
	v_mfma_f32_16x16x32_bf16 v[18:21], v[138:141], v[180:183], v[18:21]
	v_mfma_f32_16x16x32_bf16 v[74:77], v[118:121], v[188:191], v[74:77]
	v_mfma_f32_16x16x32_bf16 v[10:13], v[138:141], v[188:191], v[10:13]
	v_mfma_f32_16x16x32_bf16 v[66:69], v[118:121], v[204:207], v[66:69]
	v_mfma_f32_16x16x32_bf16 v[2:5], v[138:141], v[204:207], v[2:5]
	v_mfma_f32_16x16x32_bf16 v[90:93], v[146:149], v[168:171], v[90:93]
	v_mfma_f32_16x16x32_bf16 v[26:29], v[160:163], v[168:171], v[26:29]
	v_mfma_f32_16x16x32_bf16 v[86:89], v[146:149], v[176:179], v[86:89]
	v_mfma_f32_16x16x32_bf16 v[22:25], v[160:163], v[176:179], v[22:25]
	v_mfma_f32_16x16x32_bf16 v[78:81], v[146:149], v[184:187], v[78:81]
	v_mfma_f32_16x16x32_bf16 v[14:17], v[160:163], v[184:187], v[14:17]
	v_mfma_f32_16x16x32_bf16 v[70:73], v[146:149], v[200:203], v[70:73]
	v_mfma_f32_16x16x32_bf16 v[6:9], v[160:163], v[200:203], v[6:9]
	v_mfma_f32_16x16x32_bf16 v[90:93], v[156:159], v[172:175], v[90:93]
	v_mfma_f32_16x16x32_bf16 v[26:29], v[164:167], v[172:175], v[26:29]
	v_mfma_f32_16x16x32_bf16 v[86:89], v[156:159], v[180:183], v[86:89]
	v_mfma_f32_16x16x32_bf16 v[22:25], v[164:167], v[180:183], v[22:25]
	v_mfma_f32_16x16x32_bf16 v[78:81], v[156:159], v[188:191], v[78:81]
	v_mfma_f32_16x16x32_bf16 v[14:17], v[164:167], v[188:191], v[14:17]
	v_mfma_f32_16x16x32_bf16 v[70:73], v[156:159], v[204:207], v[70:73]
	v_mfma_f32_16x16x32_bf16 v[6:9], v[164:167], v[204:207], v[6:9]
	s_barrier
	s_setprio 0
	s_add_i32 s13, s13, 2
	s_add_u32 vcc_lo, vcc_lo, 0x100
	s_addc_u32 vcc_hi, vcc_hi, 0
	s_add_u32 s21, s21, 0x100
	s_addc_u32 s12, s12, 0
	s_cmp_gt_u32 s13, 29
	s_cbranch_scc0 .LBB0_38
	s_and_b64 vcc, exec, s[58:59]
	s_cbranch_vccz .LBB0_41
	s_barrier

; #define PG8_STAGE(bufoff, gbase, voff) do { _Pragma("unroll") for (int _i = 0; _i < 2; ++_i) \
;         __builtin_amdgcn_global_load_lds((const unsigned*)((const char*)(gbase) + (voff)[_i]), (PG8_LAS unsigned*)(lds + (bufoff) + ldsw + _i * 8192), 16, 0, 0); } while (0)
; #define PG8_LDA(dst, b, h) do { _Pragma("unroll") for (int m = 0; m < 4; ++m) _Pragma("unroll") for (int k = 0; k < 2; ++k) dst[m][k] = *(const PG8_LAS bf16x8*)(lds + PG8_SA(b, h) + aoff + m * 2048 + k * 1024); } while (0)
; #define PG8_LDB(dst, b, h) do { _Pragma("unroll") for (int n = 0; n < 2; ++n) _Pragma("unroll") for (int k = 0; k < 2; ++k) dst[n][k] = *(const PG8_LAS bf16x8*)(lds + PG8_SB(b, h) + boff + n * 2048 + k * 1024); } while (0)
; #define PG8_MMA(ai, bj, At, Bt) do { __builtin_amdgcn_s_setprio(1); _Pragma("unroll") for (int m = 0; m < 4; ++m) _Pragma("unroll") for (int n = 0; n < 2; ++n) _Pragma("unroll") for (int k = 0; k < 2; ++k) \
;         acc[ai][bj][m][n] = __builtin_amdgcn_mfma_f32_16x16x32_bf16(Bt[n][k], At[m][k], acc[ai][bj][m][n], 0, 0, 0); __builtin_amdgcn_s_setprio(0); } while (0)
; #define PG8_WAIT_V(n) asm volatile("s_waitcnt vmcnt(" #n ")" ::: "memory")
; #define PG8_WAIT_L(n) asm volatile("s_waitcnt lgkmcnt(" #n ")" ::: "memory")
; #define PG8_BAR __builtin_amdgcn_s_barrier()
; #define PG8_SCHED __builtin_amdgcn_sched_barrier(0)
; template <class Epi, class Sched, bool ALIGN_EPI = false, bool SP2 = false>
; __device__ __forceinline__ void gemm_phase(PG8_LAS unsigned char* lds, const Gemm g, const Sched& S, const Epi& E) {
;     ...
;             PG8_LDB(B0, 0, 0); PG8_LDB(B1, 0, 1); PG8_SCHED; PG8_LDA(At, 0, 0); PG8_STAGE(PG8_SA(1, 1), a1 + hstep, voffA);
;             PG8_WAIT_V(8); PG8_WAIT_L(0); PG8_BAR; PG8_MMA(0, 0, At, B0); PG8_MMA(0, 1, At, B1); PG8_BAR; PG8_SCHED;
;             PG8_LDA(At, 0, 1); PG8_STAGE(PG8_SB(0, 0), b2, voffB); PG8_STAGE(PG8_SB(0, 1), b2 + hstep, voffB); PG8_STAGE(PG8_SA(0, 0), a2, voffA);
;             PG8_WAIT_V(8); PG8_WAIT_L(0); PG8_BAR; PG8_MMA(1, 0, At, B0); PG8_MMA(1, 1, At, B1); PG8_BAR; PG8_SCHED;
.LBB0_169:
	s_add_u32 s10, s16, 0xfff80080
	s_addc_u32 s11, s17, -1
	s_add_i32 s21, 0, 0x10000
	s_cmp_eq_u32 s13, 28
	s_cselect_b32 s57, s43, s11
	s_cselect_b32 s56, s47, s10
	v_add_u32_e32 v148, s21, v151
	s_cselect_b32 s11, s45, s12
	s_cselect_b32 s10, s60, s61
	s_add_i32 s64, 0, 0x14000
	ds_read_b128 v[140:143], v148
	ds_read_b128 v[144:147], v148 offset:1024
	ds_read_b128 v[154:157], v148 offset:2048
	ds_read_b128 v[158:161], v148 offset:3072
	v_add_u32_e32 v148, s64, v151
	ds_read_b128 v[162:165], v148
	ds_read_b128 v[166:169], v148 offset:1024
	ds_read_b128 v[170:173], v148 offset:2048
	ds_read_b128 v[174:177], v148 offset:3072
	s_add_i32 m0, s2, 0xc000
	ds_read_b128 v[178:181], v153
	ds_read_b128 v[182:185], v153 offset:1024
	ds_read_b128 v[186:189], v153 offset:2048
	ds_read_b128 v[190:193], v153 offset:3072
	ds_read_b128 v[194:197], v153 offset:4096
	ds_read_b128 v[198:201], v153 offset:5120
	ds_read_b128 v[202:205], v153 offset:6144
	ds_read_b128 v[206:209], v153 offset:7168
	global_load_lds_dwordx4 v136, s[16:17]
	s_add_i32 m0, s2, 0xe000
	s_nop 0
	global_load_lds_dwordx4 v138, s[16:17]
	s_waitcnt vmcnt(8) lgkmcnt(0)
	s_setprio 1
	s_barrier
	v_mfma_f32_16x16x32_bf16 v[126:129], v[140:143], v[178:181], v[126:129]
	v_mfma_f32_16x16x32_bf16 v[122:125], v[154:157], v[178:181], v[122:125]
	v_mfma_f32_16x16x32_bf16 v[110:113], v[140:143], v[186:189], v[110:113]
	v_mfma_f32_16x16x32_bf16 v[106:109], v[154:157], v[186:189], v[106:109]
	v_mfma_f32_16x16x32_bf16 v[94:97], v[140:143], v[194:197], v[94:97]
	v_mfma_f32_16x16x32_bf16 v[90:93], v[154:157], v[194:197], v[90:93]
	v_mfma_f32_16x16x32_bf16 v[78:81], v[140:143], v[202:205], v[78:81]
	v_mfma_f32_16x16x32_bf16 v[74:77], v[154:157], v[202:205], v[74:77]
	v_mfma_f32_16x16x32_bf16 v[126:129], v[144:147], v[182:185], v[126:129]
	v_mfma_f32_16x16x32_bf16 v[122:125], v[158:161], v[182:185], v[122:125]
	v_mfma_f32_16x16x32_bf16 v[110:113], v[144:147], v[190:193], v[110:113]
	v_mfma_f32_16x16x32_bf16 v[106:109], v[158:161], v[190:193], v[106:109]
	v_mfma_f32_16x16x32_bf16 v[94:97], v[144:147], v[198:201], v[94:97]
	v_mfma_f32_16x16x32_bf16 v[90:93], v[158:161], v[198:201], v[90:93]
	v_mfma_f32_16x16x32_bf16 v[78:81], v[144:147], v[206:209], v[78:81]
	v_mfma_f32_16x16x32_bf16 v[74:77], v[158:161], v[206:209], v[74:77]
	v_mfma_f32_16x16x32_bf16 v[118:121], v[162:165], v[178:181], v[118:121]
	v_mfma_f32_16x16x32_bf16 v[114:117], v[170:173], v[178:181], v[114:117]
	v_mfma_f32_16x16x32_bf16 v[102:105], v[162:165], v[186:189], v[102:105]
	v_mfma_f32_16x16x32_bf16 v[98:101], v[170:173], v[186:189], v[98:101]
	v_mfma_f32_16x16x32_bf16 v[86:89], v[162:165], v[194:197], v[86:89]
	v_mfma_f32_16x16x32_bf16 v[82:85], v[170:173], v[194:197], v[82:85]
	v_mfma_f32_16x16x32_bf16 v[70:73], v[162:165], v[202:205], v[70:73]
	v_mfma_f32_16x16x32_bf16 v[66:69], v[170:173], v[202:205], v[66:69]
	v_mfma_f32_16x16x32_bf16 v[118:121], v[166:169], v[182:185], v[118:121]
	v_mfma_f32_16x16x32_bf16 v[114:117], v[174:177], v[182:185], v[114:117]
	v_mfma_f32_16x16x32_bf16 v[102:105], v[166:169], v[190:193], v[102:105]
	v_mfma_f32_16x16x32_bf16 v[98:101], v[174:177], v[190:193], v[98:101]
	v_mfma_f32_16x16x32_bf16 v[86:89], v[166:169], v[198:201], v[86:89]
	v_mfma_f32_16x16x32_bf16 v[82:85], v[174:177], v[198:201], v[82:85]
	v_mfma_f32_16x16x32_bf16 v[70:73], v[166:169], v[206:209], v[70:73]
	v_mfma_f32_16x16x32_bf16 v[66:69], v[174:177], v[206:209], v[66:69]
	s_barrier
	s_setprio 0
	s_add_i32 s21, s21, s1
	s_add_u32 s100, s10, 0x80
	s_addc_u32 s101, s11, 0
	s_mov_b32 m0, s21
	ds_read_b128 v[178:181], v153 offset:16384
	ds_read_b128 v[182:185], v153 offset:17408
	ds_read_b128 v[186:189], v153 offset:18432
	ds_read_b128 v[190:193], v153 offset:19456
	ds_read_b128 v[194:197], v153 offset:20480
	ds_read_b128 v[198:201], v153 offset:21504
	ds_read_b128 v[202:205], v153 offset:22528
	ds_read_b128 v[206:209], v153 offset:23552
	global_load_lds_dwordx4 v0, s[10:11]
	s_add_i32 m0, s21, 0x2000
	s_add_u32 s62, s10, 0x80000
	s_addc_u32 s63, s11, 0
	s_add_i32 s21, s64, s1
	global_load_lds_dwordx4 v134, s[10:11]
	s_mov_b32 m0, s21
	s_add_u32 s98, s56, 0x80
	s_addc_u32 s99, s57, 0
	global_load_lds_dwordx4 v0, s[62:63]
	s_add_i32 m0, s21, 0x2000
	s_nop 0
	global_load_lds_dwordx4 v134, s[62:63]
	s_mov_b32 m0, s2
	s_nop 0
	global_load_lds_dwordx4 v130, s[56:57]
	s_mov_b32 m0, s4
	s_nop 0
	global_load_lds_dwordx4 v132, s[56:57]
	s_waitcnt vmcnt(8) lgkmcnt(0)
	s_setprio 1
	s_barrier
	v_mfma_f32_16x16x32_bf16 v[62:65], v[140:143], v[178:181], v[62:65]
	v_mfma_f32_16x16x32_bf16 v[58:61], v[154:157], v[178:181], v[58:61]
	v_mfma_f32_16x16x32_bf16 v[46:49], v[140:143], v[186:189], v[46:49]
	v_mfma_f32_16x16x32_bf16 v[42:45], v[154:157], v[186:189], v[42:45]
	v_mfma_f32_16x16x32_bf16 v[30:33], v[140:143], v[194:197], v[30:33]
	v_mfma_f32_16x16x32_bf16 v[26:29], v[154:157], v[194:197], v[26:29]
	v_mfma_f32_16x16x32_bf16 v[14:17], v[140:143], v[202:205], v[14:17]
	v_mfma_f32_16x16x32_bf16 v[10:13], v[154:157], v[202:205], v[10:13]
	v_mfma_f32_16x16x32_bf16 v[62:65], v[144:147], v[182:185], v[62:65]
	v_mfma_f32_16x16x32_bf16 v[58:61], v[158:161], v[182:185], v[58:61]
	v_mfma_f32_16x16x32_bf16 v[46:49], v[144:147], v[190:193], v[46:49]
	v_mfma_f32_16x16x32_bf16 v[42:45], v[158:161], v[190:193], v[42:45]
	v_mfma_f32_16x16x32_bf16 v[30:33], v[144:147], v[198:201], v[30:33]
	v_mfma_f32_16x16x32_bf16 v[26:29], v[158:161], v[198:201], v[26:29]
	v_mfma_f32_16x16x32_bf16 v[14:17], v[144:147], v[206:209], v[14:17]
	v_mfma_f32_16x16x32_bf16 v[10:13], v[158:161], v[206:209], v[10:13]
	v_mfma_f32_16x16x32_bf16 v[54:57], v[162:165], v[178:181], v[54:57]
	v_mfma_f32_16x16x32_bf16 v[50:53], v[170:173], v[178:181], v[50:53]
	v_mfma_f32_16x16x32_bf16 v[38:41], v[162:165], v[186:189], v[38:41]
	v_mfma_f32_16x16x32_bf16 v[34:37], v[170:173], v[186:189], v[34:37]
	v_mfma_f32_16x16x32_bf16 v[22:25], v[162:165], v[194:197], v[22:25]
	v_mfma_f32_16x16x32_bf16 v[18:21], v[170:173], v[194:197], v[18:21]
	v_mfma_f32_16x16x32_bf16 v[6:9], v[162:165], v[202:205], v[6:9]
	v_mfma_f32_16x16x32_bf16 v[2:5], v[170:173], v[202:205], v[2:5]
	v_mfma_f32_16x16x32_bf16 v[54:57], v[166:169], v[182:185], v[54:57]
	v_mfma_f32_16x16x32_bf16 v[50:53], v[174:177], v[182:185], v[50:53]
	v_mfma_f32_16x16x32_bf16 v[38:41], v[166:169], v[190:193], v[38:41]
	v_mfma_f32_16x16x32_bf16 v[34:37], v[174:177], v[190:193], v[34:37]
	v_mfma_f32_16x16x32_bf16 v[22:25], v[166:169], v[198:201], v[22:25]
	v_mfma_f32_16x16x32_bf16 v[18:21], v[174:177], v[198:201], v[18:21]
	v_mfma_f32_16x16x32_bf16 v[6:9], v[166:169], v[206:209], v[6:9]
	v_mfma_f32_16x16x32_bf16 v[2:5], v[174:177], v[206:209], v[2:5]
	s_barrier
; #define PG8_STAGE(bufoff, gbase, voff) do { _Pragma("unroll") for (int _i = 0; _i < 2; ++_i) \
;         __builtin_amdgcn_global_load_lds((const unsigned*)((const char*)(gbase) + (voff)[_i]), (PG8_LAS unsigned*)(lds + (bufoff) + ldsw + _i * 8192), 16, 0, 0); } while (0)
; #define PG8_LDA(dst, b, h) do { _Pragma("unroll") for (int m = 0; m < 4; ++m) _Pragma("unroll") for (int k = 0; k < 2; ++k) dst[m][k] = *(const PG8_LAS bf16x8*)(lds + PG8_SA(b, h) + aoff + m * 2048 + k * 1024); } while (0)
; #define PG8_LDB(dst, b, h) do { _Pragma("unroll") for (int n = 0; n < 2; ++n) _Pragma("unroll") for (int k = 0; k < 2; ++k) dst[n][k] = *(const PG8_LAS bf16x8*)(lds + PG8_SB(b, h) + boff + n * 2048 + k * 1024); } while (0)
; #define PG8_MMA(ai, bj, At, Bt) do { __builtin_amdgcn_s_setprio(1); _Pragma("unroll") for (int m = 0; m < 4; ++m) _Pragma("unroll") for (int n = 0; n < 2; ++n) _Pragma("unroll") for (int k = 0; k < 2; ++k) \
;         acc[ai][bj][m][n] = __builtin_amdgcn_mfma_f32_16x16x32_bf16(Bt[n][k], At[m][k], acc[ai][bj][m][n], 0, 0, 0); __builtin_amdgcn_s_setprio(0); } while (0)
; #define PG8_WAIT_V(n) asm volatile("s_waitcnt vmcnt(" #n ")" ::: "memory")
; #define PG8_WAIT_L(n) asm volatile("s_waitcnt lgkmcnt(" #n ")" ::: "memory")
; #define PG8_BAR __builtin_amdgcn_s_barrier()
; #define PG8_SCHED __builtin_amdgcn_sched_barrier(0)
; template <class Epi, class Sched, bool ALIGN_EPI = false, bool SP2 = false>
; __device__ __forceinline__ void gemm_phase(PG8_LAS unsigned char* lds, const Gemm g, const Sched& S, const Epi& E) {
;     ...
;             PG8_LDB(B0, 1, 0); PG8_LDB(B1, 1, 1); PG8_SCHED; PG8_LDA(At, 1, 0); PG8_STAGE(PG8_SA(0, 1), a2 + hstep, voffA);
;             PG8_WAIT_V(8); PG8_WAIT_L(0); PG8_BAR; PG8_MMA(0, 0, At, B0); PG8_MMA(0, 1, At, B1); PG8_BAR; PG8_SCHED;
;             PG8_LDA(At, 1, 1); PG8_STAGE(PG8_SB(1, 0), b3, voffB); PG8_STAGE(PG8_SB(1, 1), b3 + hstep, voffB); PG8_STAGE(PG8_SA(1, 0), a3, voffA);
;             PG8_WAIT_V(8); PG8_WAIT_L(0); PG8_BAR; PG8_MMA(1, 0, At, B0); PG8_MMA(1, 1, At, B1); PG8_BAR; PG8_SCHED;
;     ...
;         if constexpr (ALIGN_EPI) { if (wr == 0) PG8_BAR; }
	s_setprio 0
	s_add_i32 s21, 0, 0x18000
	v_add_u32_e32 v148, s21, v151
	s_add_i32 s62, 0, 0x1c000
	ds_read_b128 v[140:143], v148
	ds_read_b128 v[144:147], v148 offset:1024
	ds_read_b128 v[154:157], v148 offset:2048
	ds_read_b128 v[158:161], v148 offset:3072
	v_add_u32_e32 v148, s62, v151
	ds_read_b128 v[162:165], v148
	ds_read_b128 v[166:169], v148 offset:1024
	ds_read_b128 v[170:173], v148 offset:2048
	ds_read_b128 v[174:177], v148 offset:3072
	s_add_u32 s56, s56, 0x80000
	s_addc_u32 s57, s57, 0
	s_mov_b32 m0, s5
	ds_read_b128 v[178:181], v153 offset:32768
	ds_read_b128 v[182:185], v153 offset:33792
	ds_read_b128 v[186:189], v153 offset:34816
	ds_read_b128 v[190:193], v153 offset:35840
	ds_read_b128 v[194:197], v153 offset:36864
	ds_read_b128 v[198:201], v153 offset:37888
	ds_read_b128 v[202:205], v153 offset:38912
	ds_read_b128 v[206:209], v153 offset:39936
	global_load_lds_dwordx4 v130, s[56:57]
	s_mov_b32 m0, s6
	s_nop 0
	global_load_lds_dwordx4 v132, s[56:57]
	s_waitcnt vmcnt(8) lgkmcnt(0)
	s_setprio 1
	s_barrier
	v_mfma_f32_16x16x32_bf16 v[126:129], v[140:143], v[178:181], v[126:129]
	v_mfma_f32_16x16x32_bf16 v[122:125], v[154:157], v[178:181], v[122:125]
	v_mfma_f32_16x16x32_bf16 v[110:113], v[140:143], v[186:189], v[110:113]
	v_mfma_f32_16x16x32_bf16 v[106:109], v[154:157], v[186:189], v[106:109]
	v_mfma_f32_16x16x32_bf16 v[94:97], v[140:143], v[194:197], v[94:97]
	v_mfma_f32_16x16x32_bf16 v[90:93], v[154:157], v[194:197], v[90:93]
	v_mfma_f32_16x16x32_bf16 v[78:81], v[140:143], v[202:205], v[78:81]
	v_mfma_f32_16x16x32_bf16 v[74:77], v[154:157], v[202:205], v[74:77]
	v_mfma_f32_16x16x32_bf16 v[126:129], v[144:147], v[182:185], v[126:129]
	v_mfma_f32_16x16x32_bf16 v[122:125], v[158:161], v[182:185], v[122:125]
	v_mfma_f32_16x16x32_bf16 v[110:113], v[144:147], v[190:193], v[110:113]
	v_mfma_f32_16x16x32_bf16 v[106:109], v[158:161], v[190:193], v[106:109]
	v_mfma_f32_16x16x32_bf16 v[94:97], v[144:147], v[198:201], v[94:97]
	v_mfma_f32_16x16x32_bf16 v[90:93], v[158:161], v[198:201], v[90:93]
	v_mfma_f32_16x16x32_bf16 v[78:81], v[144:147], v[206:209], v[78:81]
	v_mfma_f32_16x16x32_bf16 v[74:77], v[158:161], v[206:209], v[74:77]
	v_mfma_f32_16x16x32_bf16 v[118:121], v[162:165], v[178:181], v[118:121]
	v_mfma_f32_16x16x32_bf16 v[114:117], v[170:173], v[178:181], v[114:117]
	v_mfma_f32_16x16x32_bf16 v[102:105], v[162:165], v[186:189], v[102:105]
	v_mfma_f32_16x16x32_bf16 v[98:101], v[170:173], v[186:189], v[98:101]
	v_mfma_f32_16x16x32_bf16 v[86:89], v[162:165], v[194:197], v[86:89]
	v_mfma_f32_16x16x32_bf16 v[82:85], v[170:173], v[194:197], v[82:85]
	v_mfma_f32_16x16x32_bf16 v[70:73], v[162:165], v[202:205], v[70:73]
	v_mfma_f32_16x16x32_bf16 v[66:69], v[170:173], v[202:205], v[66:69]
	v_mfma_f32_16x16x32_bf16 v[118:121], v[166:169], v[182:185], v[118:121]
	v_mfma_f32_16x16x32_bf16 v[114:117], v[174:177], v[182:185], v[114:117]
	v_mfma_f32_16x16x32_bf16 v[102:105], v[166:169], v[190:193], v[102:105]
	v_mfma_f32_16x16x32_bf16 v[98:101], v[174:177], v[190:193], v[98:101]
	v_mfma_f32_16x16x32_bf16 v[86:89], v[166:169], v[198:201], v[86:89]
	v_mfma_f32_16x16x32_bf16 v[82:85], v[174:177], v[198:201], v[82:85]
	v_mfma_f32_16x16x32_bf16 v[70:73], v[166:169], v[206:209], v[70:73]
	v_mfma_f32_16x16x32_bf16 v[66:69], v[174:177], v[206:209], v[66:69]
	s_barrier
	s_setprio 0
	s_add_i32 s21, s21, s1
	s_mov_b32 m0, s21
	ds_read_b128 v[178:181], v153 offset:49152
	ds_read_b128 v[182:185], v153 offset:50176
	ds_read_b128 v[186:189], v153 offset:51200
	ds_read_b128 v[190:193], v153 offset:52224
	ds_read_b128 v[194:197], v153 offset:53248
	ds_read_b128 v[198:201], v153 offset:54272
	ds_read_b128 v[202:205], v153 offset:55296
	ds_read_b128 v[206:209], v153 offset:56320
	global_load_lds_dwordx4 v0, s[100:101]
	s_add_i32 m0, s21, 0x2000
	s_add_i32 s21, s62, s1
	global_load_lds_dwordx4 v134, s[100:101]
	s_add_u32 s10, s10, 0x80080
	s_addc_u32 s11, s11, 0
	s_mov_b32 m0, s21
	s_nop 0
	global_load_lds_dwordx4 v0, s[10:11]
	s_add_i32 m0, s21, 0x2000
	s_nop 0
	global_load_lds_dwordx4 v134, s[10:11]
	s_mov_b32 m0, s7
	s_nop 0
	global_load_lds_dwordx4 v130, s[98:99]
	s_mov_b32 m0, s30
	s_nop 0
	global_load_lds_dwordx4 v132, s[98:99]
	s_waitcnt vmcnt(8) lgkmcnt(0)
	s_setprio 1
	s_barrier
	v_mfma_f32_16x16x32_bf16 v[62:65], v[140:143], v[178:181], v[62:65]
	v_mfma_f32_16x16x32_bf16 v[58:61], v[154:157], v[178:181], v[58:61]
	v_mfma_f32_16x16x32_bf16 v[46:49], v[140:143], v[186:189], v[46:49]
	v_mfma_f32_16x16x32_bf16 v[42:45], v[154:157], v[186:189], v[42:45]
	v_mfma_f32_16x16x32_bf16 v[30:33], v[140:143], v[194:197], v[30:33]
	v_mfma_f32_16x16x32_bf16 v[26:29], v[154:157], v[194:197], v[26:29]
	v_mfma_f32_16x16x32_bf16 v[14:17], v[140:143], v[202:205], v[14:17]
	v_mfma_f32_16x16x32_bf16 v[10:13], v[154:157], v[202:205], v[10:13]
	v_mfma_f32_16x16x32_bf16 v[62:65], v[144:147], v[182:185], v[62:65]
	v_mfma_f32_16x16x32_bf16 v[58:61], v[158:161], v[182:185], v[58:61]
	v_mfma_f32_16x16x32_bf16 v[46:49], v[144:147], v[190:193], v[46:49]
	v_mfma_f32_16x16x32_bf16 v[42:45], v[158:161], v[190:193], v[42:45]
	v_mfma_f32_16x16x32_bf16 v[30:33], v[144:147], v[198:201], v[30:33]
	v_mfma_f32_16x16x32_bf16 v[26:29], v[158:161], v[198:201], v[26:29]
	v_mfma_f32_16x16x32_bf16 v[14:17], v[144:147], v[206:209], v[14:17]
	v_mfma_f32_16x16x32_bf16 v[10:13], v[158:161], v[206:209], v[10:13]
	v_mfma_f32_16x16x32_bf16 v[54:57], v[162:165], v[178:181], v[54:57]
	v_mfma_f32_16x16x32_bf16 v[50:53], v[170:173], v[178:181], v[50:53]
	v_mfma_f32_16x16x32_bf16 v[38:41], v[162:165], v[186:189], v[38:41]
	v_mfma_f32_16x16x32_bf16 v[34:37], v[170:173], v[186:189], v[34:37]
	v_mfma_f32_16x16x32_bf16 v[22:25], v[162:165], v[194:197], v[22:25]
	v_mfma_f32_16x16x32_bf16 v[18:21], v[170:173], v[194:197], v[18:21]
	v_mfma_f32_16x16x32_bf16 v[6:9], v[162:165], v[202:205], v[6:9]
	v_mfma_f32_16x16x32_bf16 v[2:5], v[170:173], v[202:205], v[2:5]
	v_mfma_f32_16x16x32_bf16 v[54:57], v[166:169], v[182:185], v[54:57]
	v_mfma_f32_16x16x32_bf16 v[50:53], v[174:177], v[182:185], v[50:53]
	v_mfma_f32_16x16x32_bf16 v[38:41], v[166:169], v[190:193], v[38:41]
	v_mfma_f32_16x16x32_bf16 v[34:37], v[174:177], v[190:193], v[34:37]
	v_mfma_f32_16x16x32_bf16 v[22:25], v[166:169], v[198:201], v[22:25]
	v_mfma_f32_16x16x32_bf16 v[18:21], v[174:177], v[198:201], v[18:21]
	v_mfma_f32_16x16x32_bf16 v[6:9], v[166:169], v[206:209], v[6:9]
	v_mfma_f32_16x16x32_bf16 v[2:5], v[174:177], v[206:209], v[2:5]
	s_barrier
	s_setprio 0
	s_add_i32 s13, s13, 2
	s_add_u32 s16, s16, 0x100
	s_addc_u32 s17, s17, 0
	s_add_u32 s61, s61, 0x100
	s_addc_u32 s12, s12, 0
	s_cmp_gt_u32 s13, 29
	s_cbranch_scc0 .LBB0_169
	s_and_b64 vcc, exec, s[22:23]
	s_cbranch_vccz .LBB0_172
	s_barrier

; #define PG8_STAGE(bufoff, gbase, voff) do { _Pragma("unroll") for (int _i = 0; _i < 2; ++_i) \
;         __builtin_amdgcn_global_load_lds((const unsigned*)((const char*)(gbase) + (voff)[_i]), (PG8_LAS unsigned*)(lds + (bufoff) + ldsw + _i * 8192), 16, 0, 0); } while (0)
; #define PG8_LDA(dst, b, h) do { _Pragma("unroll") for (int m = 0; m < 4; ++m) _Pragma("unroll") for (int k = 0; k < 2; ++k) dst[m][k] = *(const PG8_LAS bf16x8*)(lds + PG8_SA(b, h) + aoff + m * 2048 + k * 1024); } while (0)
; #define PG8_LDB(dst, b, h) do { _Pragma("unroll") for (int n = 0; n < 2; ++n) _Pragma("unroll") for (int k = 0; k < 2; ++k) dst[n][k] = *(const PG8_LAS bf16x8*)(lds + PG8_SB(b, h) + boff + n * 2048 + k * 1024); } while (0)
; #define PG8_WAIT_V(n) asm volatile("s_waitcnt vmcnt(" #n ")" ::: "memory")
; #define PG8_WAIT_L(n) asm volatile("s_waitcnt lgkmcnt(" #n ")" ::: "memory")
; #define PG8_BAR __builtin_amdgcn_s_barrier()
; #define PG8_SCHED __builtin_amdgcn_sched_barrier(0)
; template <class Epi, class Sched, bool ALIGN_EPI = false, bool SP2 = false>
; __device__ __forceinline__ void gemm_phase(PG8_LAS unsigned char* lds, const Gemm g, const Sched& S, const Epi& E) {
;     ...
;         const char* nA = has_next ? (const char*)g.A + (size_t)nxt.pm * tstep : cA; const char* nB = has_next ? (const char*)g.Bt + (size_t)nxt.pn * tstep : cB;
;         for (int t = 0; t < nt; t += 2) {
;             const bool last = (t == nt - 2);
;             const char* a1 = cA + (size_t)(t + 1) * kstep;
;             const char* a2 = last ? nA : cA + (size_t)(t + 2) * kstep; const char* b2 = last ? nB : cB + (size_t)(t + 2) * kstep;
;             const char* a3 = a2 + kstep; const char* b3 = b2 + kstep;
;             if (last && has_next) S.a_ready(nxt);
;             if constexpr (SP2) {
;             PG8_LDB(B0, 0, 0); PG8_LDB(B1, 0, 1); PG8_SCHED; PG8_LDA(At, 0, 0); PG8_STAGE(PG8_SA(1, 1), a1 + hstep, voffA);
;             PG8_WAIT_V(8); PG8_WAIT_L(0); PG8_BAR; PG8_MMA(0, 0, At, B0); PG8_MMA(0, 1, At, B1); PG8_BAR; PG8_SCHED;
;             PG8_LDA(At, 0, 1); PG8_STAGE(PG8_SB(0, 0), b2, voffB); PG8_STAGE(PG8_SB(0, 1), b2 + hstep, voffB); PG8_STAGE(PG8_SA(0, 0), a2, voffA);
;             PG8_WAIT_V(8); PG8_WAIT_L(0); PG8_BAR; PG8_MMA(1, 0, At, B0); PG8_MMA(1, 1, At, B1); PG8_BAR; PG8_SCHED;
.LBB0_222:
	s_add_u32 s8, s8, 0x80
	s_addc_u32 s9, s9, 0
	s_add_u32 s12, s10, 0x100
	s_addc_u32 s13, s11, 0
	s_mov_b32 s10, 0
	s_waitcnt lgkmcnt(0)
	v_add_u32_e32 v218, 0x10000, v145
	s_add_i32 s14, s10, 2
	s_add_u32 s15, s8, 0x80
	s_addc_u32 s11, s9, 0
	s_add_i32 s64, 0, 0x10000
	s_cmp_eq_u32 s57, s10
	s_cselect_b32 s11, s51, s11
	s_cselect_b32 s10, s50, s15
	s_cselect_b32 s45, s53, s13
	s_cselect_b32 s44, s52, s12
	s_add_i32 s15, 0, 0x14000
	ds_read_b128 v[140:143], v218
	ds_read_b128 v[148:151], v218 offset:1024
	ds_read_b128 v[152:155], v218 offset:2048
	ds_read_b128 v[156:159], v218 offset:3072
	ds_read_b128 v[160:163], v218 offset:16384
	ds_read_b128 v[164:167], v218 offset:17408
	ds_read_b128 v[168:171], v218 offset:18432
	ds_read_b128 v[172:175], v218 offset:19456
	s_add_i32 m0, s21, 0xc000
	ds_read_b128 v[176:179], v147
	ds_read_b128 v[180:183], v147 offset:1024
	ds_read_b128 v[184:187], v147 offset:2048
	ds_read_b128 v[188:191], v147 offset:3072
	ds_read_b128 v[192:195], v147 offset:4096
	ds_read_b128 v[196:199], v147 offset:5120
	ds_read_b128 v[200:203], v147 offset:6144
	ds_read_b128 v[204:207], v147 offset:7168
	global_load_lds_dwordx4 v136, s[8:9]
	s_add_i32 m0, s21, 0xe000
	s_nop 0
	global_load_lds_dwordx4 v138, s[8:9]
	s_waitcnt vmcnt(8) lgkmcnt(0)
	s_setprio 1
	s_barrier
	v_mfma_f32_16x16x32_bf16 v[126:129], v[140:143], v[176:179], 0
	v_mfma_f32_16x16x32_bf16 v[122:125], v[152:155], v[176:179], 0
	v_mfma_f32_16x16x32_bf16 v[110:113], v[140:143], v[184:187], 0
	v_mfma_f32_16x16x32_bf16 v[106:109], v[152:155], v[184:187], 0
	v_mfma_f32_16x16x32_bf16 v[94:97], v[140:143], v[192:195], 0
	v_mfma_f32_16x16x32_bf16 v[90:93], v[152:155], v[192:195], 0
	v_mfma_f32_16x16x32_bf16 v[78:81], v[140:143], v[200:203], 0
	v_mfma_f32_16x16x32_bf16 v[74:77], v[152:155], v[200:203], 0
	v_mfma_f32_16x16x32_bf16 v[126:129], v[148:151], v[180:183], v[126:129]
	v_mfma_f32_16x16x32_bf16 v[122:125], v[156:159], v[180:183], v[122:125]
	v_mfma_f32_16x16x32_bf16 v[110:113], v[148:151], v[188:191], v[110:113]
	v_mfma_f32_16x16x32_bf16 v[106:109], v[156:159], v[188:191], v[106:109]
	v_mfma_f32_16x16x32_bf16 v[94:97], v[148:151], v[196:199], v[94:97]
	v_mfma_f32_16x16x32_bf16 v[90:93], v[156:159], v[196:199], v[90:93]
	v_mfma_f32_16x16x32_bf16 v[78:81], v[148:151], v[204:207], v[78:81]
	v_mfma_f32_16x16x32_bf16 v[74:77], v[156:159], v[204:207], v[74:77]
	v_mfma_f32_16x16x32_bf16 v[118:121], v[160:163], v[176:179], 0
	v_mfma_f32_16x16x32_bf16 v[114:117], v[168:171], v[176:179], 0
	v_mfma_f32_16x16x32_bf16 v[102:105], v[160:163], v[184:187], 0
	v_mfma_f32_16x16x32_bf16 v[98:101], v[168:171], v[184:187], 0
	v_mfma_f32_16x16x32_bf16 v[86:89], v[160:163], v[192:195], 0
	v_mfma_f32_16x16x32_bf16 v[82:85], v[168:171], v[192:195], 0
	v_mfma_f32_16x16x32_bf16 v[70:73], v[160:163], v[200:203], 0
	v_mfma_f32_16x16x32_bf16 v[66:69], v[168:171], v[200:203], 0
	v_mfma_f32_16x16x32_bf16 v[118:121], v[164:167], v[180:183], v[118:121]
	v_mfma_f32_16x16x32_bf16 v[114:117], v[172:175], v[180:183], v[114:117]
	v_mfma_f32_16x16x32_bf16 v[102:105], v[164:167], v[188:191], v[102:105]
	v_mfma_f32_16x16x32_bf16 v[98:101], v[172:175], v[188:191], v[98:101]
	v_mfma_f32_16x16x32_bf16 v[86:89], v[164:167], v[196:199], v[86:89]
	v_mfma_f32_16x16x32_bf16 v[82:85], v[172:175], v[196:199], v[82:85]
	v_mfma_f32_16x16x32_bf16 v[70:73], v[164:167], v[204:207], v[70:73]
	v_mfma_f32_16x16x32_bf16 v[66:69], v[172:175], v[204:207], v[66:69]
	s_barrier
	s_setprio 0
	s_add_i32 s64, s64, s7
	s_add_u32 s98, s44, 0x80
	s_addc_u32 s99, s45, 0
	s_mov_b32 m0, s64
	ds_read_b128 v[176:179], v147 offset:16384
	ds_read_b128 v[180:183], v147 offset:17408
	ds_read_b128 v[184:187], v147 offset:18432
	ds_read_b128 v[188:191], v147 offset:19456
	ds_read_b128 v[192:195], v147 offset:20480
	ds_read_b128 v[196:199], v147 offset:21504
	ds_read_b128 v[200:203], v147 offset:22528
	ds_read_b128 v[204:207], v147 offset:23552
	global_load_lds_dwordx4 v0, s[44:45]
	s_add_i32 m0, s64, 0x2000
	s_add_i32 s15, s15, s7
	global_load_lds_dwordx4 v134, s[44:45]
	s_add_u32 s44, s44, s30
	s_addc_u32 s45, s45, 0
	s_add_u32 s100, s44, 0x80
	s_addc_u32 s101, s45, 0
	s_mov_b32 m0, s15
	s_add_u32 vcc_lo, s10, 0x80
	s_addc_u32 vcc_hi, s11, 0
	global_load_lds_dwordx4 v0, s[44:45]
	s_add_i32 m0, s15, 0x2000
	s_nop 0
	global_load_lds_dwordx4 v134, s[44:45]
	s_mov_b32 m0, s21
	s_nop 0
	global_load_lds_dwordx4 v130, s[10:11]
	s_mov_b32 m0, s26
	s_nop 0
	global_load_lds_dwordx4 v132, s[10:11]
	s_waitcnt vmcnt(8) lgkmcnt(0)
	s_setprio 1
	s_barrier
	v_mfma_f32_16x16x32_bf16 v[62:65], v[140:143], v[176:179], 0
	v_mfma_f32_16x16x32_bf16 v[58:61], v[152:155], v[176:179], 0
	v_mfma_f32_16x16x32_bf16 v[46:49], v[140:143], v[184:187], 0
	v_mfma_f32_16x16x32_bf16 v[42:45], v[152:155], v[184:187], 0
	v_mfma_f32_16x16x32_bf16 v[30:33], v[140:143], v[192:195], 0
	v_mfma_f32_16x16x32_bf16 v[26:29], v[152:155], v[192:195], 0
	v_mfma_f32_16x16x32_bf16 v[14:17], v[140:143], v[200:203], 0
	v_mfma_f32_16x16x32_bf16 v[10:13], v[152:155], v[200:203], 0
	v_mfma_f32_16x16x32_bf16 v[62:65], v[148:151], v[180:183], v[62:65]
	v_mfma_f32_16x16x32_bf16 v[58:61], v[156:159], v[180:183], v[58:61]
	v_mfma_f32_16x16x32_bf16 v[46:49], v[148:151], v[188:191], v[46:49]
	v_mfma_f32_16x16x32_bf16 v[42:45], v[156:159], v[188:191], v[42:45]
	v_mfma_f32_16x16x32_bf16 v[30:33], v[148:151], v[196:199], v[30:33]
	v_mfma_f32_16x16x32_bf16 v[26:29], v[156:159], v[196:199], v[26:29]
	v_mfma_f32_16x16x32_bf16 v[14:17], v[148:151], v[204:207], v[14:17]
	v_mfma_f32_16x16x32_bf16 v[10:13], v[156:159], v[204:207], v[10:13]
	v_mfma_f32_16x16x32_bf16 v[54:57], v[160:163], v[176:179], 0
	v_mfma_f32_16x16x32_bf16 v[50:53], v[168:171], v[176:179], 0
	v_mfma_f32_16x16x32_bf16 v[38:41], v[160:163], v[184:187], 0
	v_mfma_f32_16x16x32_bf16 v[34:37], v[168:171], v[184:187], 0
	v_mfma_f32_16x16x32_bf16 v[22:25], v[160:163], v[192:195], 0
	v_mfma_f32_16x16x32_bf16 v[18:21], v[168:171], v[192:195], 0
	v_mfma_f32_16x16x32_bf16 v[6:9], v[160:163], v[200:203], 0
	v_mfma_f32_16x16x32_bf16 v[2:5], v[168:171], v[200:203], 0
	v_mfma_f32_16x16x32_bf16 v[54:57], v[164:167], v[180:183], v[54:57]
	v_mfma_f32_16x16x32_bf16 v[50:53], v[172:175], v[180:183], v[50:53]
	v_mfma_f32_16x16x32_bf16 v[38:41], v[164:167], v[188:191], v[38:41]
	v_mfma_f32_16x16x32_bf16 v[34:37], v[172:175], v[188:191], v[34:37]
	v_mfma_f32_16x16x32_bf16 v[22:25], v[164:167], v[196:199], v[22:25]
	v_mfma_f32_16x16x32_bf16 v[18:21], v[172:175], v[196:199], v[18:21]
	v_mfma_f32_16x16x32_bf16 v[6:9], v[164:167], v[204:207], v[6:9]
	v_mfma_f32_16x16x32_bf16 v[2:5], v[172:175], v[204:207], v[2:5]
	s_barrier
; #define PG8_STAGE(bufoff, gbase, voff) do { _Pragma("unroll") for (int _i = 0; _i < 2; ++_i) \
;         __builtin_amdgcn_global_load_lds((const unsigned*)((const char*)(gbase) + (voff)[_i]), (PG8_LAS unsigned*)(lds + (bufoff) + ldsw + _i * 8192), 16, 0, 0); } while (0)
; #define PG8_LDA(dst, b, h) do { _Pragma("unroll") for (int m = 0; m < 4; ++m) _Pragma("unroll") for (int k = 0; k < 2; ++k) dst[m][k] = *(const PG8_LAS bf16x8*)(lds + PG8_SA(b, h) + aoff + m * 2048 + k * 1024); } while (0)
; #define PG8_LDB(dst, b, h) do { _Pragma("unroll") for (int n = 0; n < 2; ++n) _Pragma("unroll") for (int k = 0; k < 2; ++k) dst[n][k] = *(const PG8_LAS bf16x8*)(lds + PG8_SB(b, h) + boff + n * 2048 + k * 1024); } while (0)
; #define PG8_MMA(ai, bj, At, Bt) do { __builtin_amdgcn_s_setprio(1); _Pragma("unroll") for (int m = 0; m < 4; ++m) _Pragma("unroll") for (int n = 0; n < 2; ++n) _Pragma("unroll") for (int k = 0; k < 2; ++k) \
;         acc[ai][bj][m][n] = __builtin_amdgcn_mfma_f32_16x16x32_bf16(Bt[n][k], At[m][k], acc[ai][bj][m][n], 0, 0, 0); __builtin_amdgcn_s_setprio(0); } while (0)
; #define PG8_WAIT_V(n) asm volatile("s_waitcnt vmcnt(" #n ")" ::: "memory")
; #define PG8_WAIT_L(n) asm volatile("s_waitcnt lgkmcnt(" #n ")" ::: "memory")
; #define PG8_BAR __builtin_amdgcn_s_barrier()
; #define PG8_SCHED __builtin_amdgcn_sched_barrier(0)
; template <class Epi, class Sched, bool ALIGN_EPI = false, bool SP2 = false>
; __device__ __forceinline__ void gemm_phase(PG8_LAS unsigned char* lds, const Gemm g, const Sched& S, const Epi& E) {
;     ...
;             PG8_LDB(B0, 1, 0); PG8_LDB(B1, 1, 1); PG8_SCHED; PG8_LDA(At, 1, 0); PG8_STAGE(PG8_SA(0, 1), a2 + hstep, voffA);
;             PG8_WAIT_V(8); PG8_WAIT_L(0); PG8_BAR; PG8_MMA(0, 0, At, B0); PG8_MMA(0, 1, At, B1); PG8_BAR; PG8_SCHED;
;             PG8_LDA(At, 1, 1); PG8_STAGE(PG8_SB(1, 0), b3, voffB); PG8_STAGE(PG8_SB(1, 1), b3 + hstep, voffB); PG8_STAGE(PG8_SA(1, 0), a3, voffA);
;             PG8_WAIT_V(8); PG8_WAIT_L(0); PG8_BAR; PG8_MMA(1, 0, At, B0); PG8_MMA(1, 1, At, B1); PG8_BAR; PG8_SCHED;
	s_setprio 0
	s_add_i32 s15, 0, 0x18000
	s_add_i32 s44, 0, 0x1c000
	ds_read_b128 v[140:143], v218 offset:32768
	ds_read_b128 v[148:151], v218 offset:33792
	ds_read_b128 v[152:155], v218 offset:34816
	ds_read_b128 v[156:159], v218 offset:35840
	ds_read_b128 v[160:163], v218 offset:49152
	ds_read_b128 v[164:167], v218 offset:50176
	ds_read_b128 v[168:171], v218 offset:51200
	ds_read_b128 v[172:175], v218 offset:52224
	s_add_u32 s10, s10, s30
	s_addc_u32 s11, s11, 0
	s_mov_b32 m0, s27
	ds_read_b128 v[176:179], v147 offset:32768
	ds_read_b128 v[180:183], v147 offset:33792
	ds_read_b128 v[184:187], v147 offset:34816
	ds_read_b128 v[188:191], v147 offset:35840
	ds_read_b128 v[192:195], v147 offset:36864
	ds_read_b128 v[196:199], v147 offset:37888
	ds_read_b128 v[200:203], v147 offset:38912
	ds_read_b128 v[204:207], v147 offset:39936
	global_load_lds_dwordx4 v130, s[10:11]
	s_mov_b32 m0, s54
	s_nop 0
	global_load_lds_dwordx4 v132, s[10:11]
	s_waitcnt vmcnt(8) lgkmcnt(0)
	s_setprio 1
	s_barrier
	v_mfma_f32_16x16x32_bf16 v[126:129], v[140:143], v[176:179], v[126:129]
	v_mfma_f32_16x16x32_bf16 v[122:125], v[152:155], v[176:179], v[122:125]
	v_mfma_f32_16x16x32_bf16 v[110:113], v[140:143], v[184:187], v[110:113]
	v_mfma_f32_16x16x32_bf16 v[106:109], v[152:155], v[184:187], v[106:109]
	v_mfma_f32_16x16x32_bf16 v[94:97], v[140:143], v[192:195], v[94:97]
	v_mfma_f32_16x16x32_bf16 v[90:93], v[152:155], v[192:195], v[90:93]
	v_mfma_f32_16x16x32_bf16 v[78:81], v[140:143], v[200:203], v[78:81]
	v_mfma_f32_16x16x32_bf16 v[74:77], v[152:155], v[200:203], v[74:77]
	v_mfma_f32_16x16x32_bf16 v[126:129], v[148:151], v[180:183], v[126:129]
	v_mfma_f32_16x16x32_bf16 v[122:125], v[156:159], v[180:183], v[122:125]
	v_mfma_f32_16x16x32_bf16 v[110:113], v[148:151], v[188:191], v[110:113]
	v_mfma_f32_16x16x32_bf16 v[106:109], v[156:159], v[188:191], v[106:109]
	v_mfma_f32_16x16x32_bf16 v[94:97], v[148:151], v[196:199], v[94:97]
	v_mfma_f32_16x16x32_bf16 v[90:93], v[156:159], v[196:199], v[90:93]
	v_mfma_f32_16x16x32_bf16 v[78:81], v[148:151], v[204:207], v[78:81]
	v_mfma_f32_16x16x32_bf16 v[74:77], v[156:159], v[204:207], v[74:77]
	v_mfma_f32_16x16x32_bf16 v[118:121], v[160:163], v[176:179], v[118:121]
	v_mfma_f32_16x16x32_bf16 v[114:117], v[168:171], v[176:179], v[114:117]
	v_mfma_f32_16x16x32_bf16 v[102:105], v[160:163], v[184:187], v[102:105]
	v_mfma_f32_16x16x32_bf16 v[98:101], v[168:171], v[184:187], v[98:101]
	v_mfma_f32_16x16x32_bf16 v[86:89], v[160:163], v[192:195], v[86:89]
	v_mfma_f32_16x16x32_bf16 v[82:85], v[168:171], v[192:195], v[82:85]
	v_mfma_f32_16x16x32_bf16 v[70:73], v[160:163], v[200:203], v[70:73]
	v_mfma_f32_16x16x32_bf16 v[66:69], v[168:171], v[200:203], v[66:69]
	v_mfma_f32_16x16x32_bf16 v[118:121], v[164:167], v[180:183], v[118:121]
	v_mfma_f32_16x16x32_bf16 v[114:117], v[172:175], v[180:183], v[114:117]
	v_mfma_f32_16x16x32_bf16 v[102:105], v[164:167], v[188:191], v[102:105]
	v_mfma_f32_16x16x32_bf16 v[98:101], v[172:175], v[188:191], v[98:101]
	v_mfma_f32_16x16x32_bf16 v[86:89], v[164:167], v[196:199], v[86:89]
	v_mfma_f32_16x16x32_bf16 v[82:85], v[172:175], v[196:199], v[82:85]
	v_mfma_f32_16x16x32_bf16 v[70:73], v[164:167], v[204:207], v[70:73]
	v_mfma_f32_16x16x32_bf16 v[66:69], v[172:175], v[204:207], v[66:69]
	s_barrier
	s_setprio 0
	s_add_i32 s10, s15, s7
	s_mov_b32 m0, s10
	ds_read_b128 v[176:179], v147 offset:49152
	ds_read_b128 v[180:183], v147 offset:50176
	ds_read_b128 v[184:187], v147 offset:51200
	ds_read_b128 v[188:191], v147 offset:52224
	ds_read_b128 v[192:195], v147 offset:53248
	ds_read_b128 v[196:199], v147 offset:54272
	ds_read_b128 v[200:203], v147 offset:55296
	ds_read_b128 v[204:207], v147 offset:56320
	global_load_lds_dwordx4 v0, s[98:99]
	s_add_i32 m0, s10, 0x2000
	s_add_i32 s10, s44, s7
	global_load_lds_dwordx4 v134, s[98:99]
	s_mov_b32 m0, s10
	s_nop 0
	global_load_lds_dwordx4 v0, s[100:101]
	s_add_i32 m0, s10, 0x2000
	s_nop 0
	global_load_lds_dwordx4 v134, s[100:101]
	s_mov_b32 m0, s16
	s_nop 0
	global_load_lds_dwordx4 v130, vcc
	s_mov_b32 m0, s17
	s_nop 0
	global_load_lds_dwordx4 v132, vcc
	s_waitcnt vmcnt(8) lgkmcnt(0)
	s_setprio 1
	s_barrier
	v_mfma_f32_16x16x32_bf16 v[62:65], v[140:143], v[176:179], v[62:65]
	v_mfma_f32_16x16x32_bf16 v[58:61], v[152:155], v[176:179], v[58:61]
	v_mfma_f32_16x16x32_bf16 v[46:49], v[140:143], v[184:187], v[46:49]
	v_mfma_f32_16x16x32_bf16 v[42:45], v[152:155], v[184:187], v[42:45]
	v_mfma_f32_16x16x32_bf16 v[30:33], v[140:143], v[192:195], v[30:33]
	v_mfma_f32_16x16x32_bf16 v[26:29], v[152:155], v[192:195], v[26:29]
	v_mfma_f32_16x16x32_bf16 v[14:17], v[140:143], v[200:203], v[14:17]
	v_mfma_f32_16x16x32_bf16 v[10:13], v[152:155], v[200:203], v[10:13]
	v_mfma_f32_16x16x32_bf16 v[62:65], v[148:151], v[180:183], v[62:65]
	v_mfma_f32_16x16x32_bf16 v[58:61], v[156:159], v[180:183], v[58:61]
	v_mfma_f32_16x16x32_bf16 v[46:49], v[148:151], v[188:191], v[46:49]
	v_mfma_f32_16x16x32_bf16 v[42:45], v[156:159], v[188:191], v[42:45]
	v_mfma_f32_16x16x32_bf16 v[30:33], v[148:151], v[196:199], v[30:33]
	v_mfma_f32_16x16x32_bf16 v[26:29], v[156:159], v[196:199], v[26:29]
	v_mfma_f32_16x16x32_bf16 v[14:17], v[148:151], v[204:207], v[14:17]
	v_mfma_f32_16x16x32_bf16 v[10:13], v[156:159], v[204:207], v[10:13]
	v_mfma_f32_16x16x32_bf16 v[54:57], v[160:163], v[176:179], v[54:57]
	v_mfma_f32_16x16x32_bf16 v[50:53], v[168:171], v[176:179], v[50:53]
	v_mfma_f32_16x16x32_bf16 v[38:41], v[160:163], v[184:187], v[38:41]
	v_mfma_f32_16x16x32_bf16 v[34:37], v[168:171], v[184:187], v[34:37]
	v_mfma_f32_16x16x32_bf16 v[22:25], v[160:163], v[192:195], v[22:25]
	v_mfma_f32_16x16x32_bf16 v[18:21], v[168:171], v[192:195], v[18:21]
	v_mfma_f32_16x16x32_bf16 v[6:9], v[160:163], v[200:203], v[6:9]
	v_mfma_f32_16x16x32_bf16 v[2:5], v[168:171], v[200:203], v[2:5]
	v_mfma_f32_16x16x32_bf16 v[54:57], v[164:167], v[180:183], v[54:57]
	v_mfma_f32_16x16x32_bf16 v[50:53], v[172:175], v[180:183], v[50:53]
	v_mfma_f32_16x16x32_bf16 v[38:41], v[164:167], v[188:191], v[38:41]
	v_mfma_f32_16x16x32_bf16 v[34:37], v[172:175], v[188:191], v[34:37]
	v_mfma_f32_16x16x32_bf16 v[22:25], v[164:167], v[196:199], v[22:25]
	v_mfma_f32_16x16x32_bf16 v[18:21], v[172:175], v[196:199], v[18:21]
	v_mfma_f32_16x16x32_bf16 v[6:9], v[164:167], v[204:207], v[6:9]
	v_mfma_f32_16x16x32_bf16 v[2:5], v[172:175], v[204:207], v[2:5]
	s_barrier
	s_setprio 0
	s_add_u32 s8, s8, 0x100
	s_addc_u32 s9, s9, 0
	s_add_u32 s12, s12, 0x100
	s_addc_u32 s13, s13, 0
	s_mov_b32 s10, s14
; #define PG8_STAGE(bufoff, gbase, voff) do { _Pragma("unroll") for (int _i = 0; _i < 2; ++_i) \
;         __builtin_amdgcn_global_load_lds((const unsigned*)((const char*)(gbase) + (voff)[_i]), (PG8_LAS unsigned*)(lds + (bufoff) + ldsw + _i * 8192), 16, 0, 0); } while (0)
; #define PG8_LDA(dst, b, h) do { _Pragma("unroll") for (int m = 0; m < 4; ++m) _Pragma("unroll") for (int k = 0; k < 2; ++k) dst[m][k] = *(const PG8_LAS bf16x8*)(lds + PG8_SA(b, h) + aoff + m * 2048 + k * 1024); } while (0)
; #define PG8_LDB(dst, b, h) do { _Pragma("unroll") for (int n = 0; n < 2; ++n) _Pragma("unroll") for (int k = 0; k < 2; ++k) dst[n][k] = *(const PG8_LAS bf16x8*)(lds + PG8_SB(b, h) + boff + n * 2048 + k * 1024); } while (0)
; #define PG8_WAIT_V(n) asm volatile("s_waitcnt vmcnt(" #n ")" ::: "memory")
; #define PG8_WAIT_L(n) asm volatile("s_waitcnt lgkmcnt(" #n ")" ::: "memory")
; #define PG8_BAR __builtin_amdgcn_s_barrier()
; #define PG8_SCHED __builtin_amdgcn_sched_barrier(0)
; template <class Epi, class Sched, bool ALIGN_EPI = false, bool SP2 = false>
; __device__ __forceinline__ void gemm_phase(PG8_LAS unsigned char* lds, const Gemm g, const Sched& S, const Epi& E) {
;     ...
;         const char* nA = has_next ? (const char*)g.A + (size_t)nxt.pm * tstep : cA; const char* nB = has_next ? (const char*)g.Bt + (size_t)nxt.pn * tstep : cB;
;         for (int t = 0; t < nt; t += 2) {
;             const bool last = (t == nt - 2);
;             const char* a1 = cA + (size_t)(t + 1) * kstep;
;             const char* a2 = last ? nA : cA + (size_t)(t + 2) * kstep; const char* b2 = last ? nB : cB + (size_t)(t + 2) * kstep;
;             const char* a3 = a2 + kstep; const char* b3 = b2 + kstep;
;             if (last && has_next) S.a_ready(nxt);
;             if constexpr (SP2) {
;             PG8_LDB(B0, 0, 0); PG8_LDB(B1, 0, 1); PG8_SCHED; PG8_LDA(At, 0, 0); PG8_STAGE(PG8_SA(1, 1), a1 + hstep, voffA);
;             PG8_WAIT_V(8); PG8_WAIT_L(0); PG8_BAR; PG8_MMA(0, 0, At, B0); PG8_MMA(0, 1, At, B1); PG8_BAR; PG8_SCHED;
;             PG8_LDA(At, 0, 1); PG8_STAGE(PG8_SB(0, 0), b2, voffB); PG8_STAGE(PG8_SB(0, 1), b2 + hstep, voffB); PG8_STAGE(PG8_SA(0, 0), a2, voffA);
;             PG8_WAIT_V(8); PG8_WAIT_L(0); PG8_BAR; PG8_MMA(1, 0, At, B0); PG8_MMA(1, 1, At, B1); PG8_BAR; PG8_SCHED;
.LBB0_223:
	s_add_i32 s14, s10, 2
	s_add_u32 s15, s8, 0x80
	s_addc_u32 s11, s9, 0
	s_add_i32 s64, 0, 0x10000
	s_cmp_eq_u32 s57, s10
	s_cselect_b32 s11, s51, s11
	s_cselect_b32 s10, s50, s15
	s_cselect_b32 s45, s53, s13
	s_cselect_b32 s44, s52, s12
	s_add_i32 s15, 0, 0x14000
	ds_read_b128 v[140:143], v218
	ds_read_b128 v[148:151], v218 offset:1024
	ds_read_b128 v[152:155], v218 offset:2048
	ds_read_b128 v[156:159], v218 offset:3072
	ds_read_b128 v[160:163], v218 offset:16384
	ds_read_b128 v[164:167], v218 offset:17408
	ds_read_b128 v[168:171], v218 offset:18432
	ds_read_b128 v[172:175], v218 offset:19456
	s_add_i32 m0, s21, 0xc000
	ds_read_b128 v[176:179], v147
	ds_read_b128 v[180:183], v147 offset:1024
	ds_read_b128 v[184:187], v147 offset:2048
	ds_read_b128 v[188:191], v147 offset:3072
	ds_read_b128 v[192:195], v147 offset:4096
	ds_read_b128 v[196:199], v147 offset:5120
	ds_read_b128 v[200:203], v147 offset:6144
	ds_read_b128 v[204:207], v147 offset:7168
	global_load_lds_dwordx4 v136, s[8:9]
	s_add_i32 m0, s21, 0xe000
	s_nop 0
	global_load_lds_dwordx4 v138, s[8:9]
	s_waitcnt vmcnt(8) lgkmcnt(0)
	s_setprio 1
	s_barrier
	v_mfma_f32_16x16x32_bf16 v[126:129], v[140:143], v[176:179], v[126:129]
	v_mfma_f32_16x16x32_bf16 v[122:125], v[152:155], v[176:179], v[122:125]
	v_mfma_f32_16x16x32_bf16 v[110:113], v[140:143], v[184:187], v[110:113]
	v_mfma_f32_16x16x32_bf16 v[106:109], v[152:155], v[184:187], v[106:109]
	v_mfma_f32_16x16x32_bf16 v[94:97], v[140:143], v[192:195], v[94:97]
	v_mfma_f32_16x16x32_bf16 v[90:93], v[152:155], v[192:195], v[90:93]
	v_mfma_f32_16x16x32_bf16 v[78:81], v[140:143], v[200:203], v[78:81]
	v_mfma_f32_16x16x32_bf16 v[74:77], v[152:155], v[200:203], v[74:77]
	v_mfma_f32_16x16x32_bf16 v[126:129], v[148:151], v[180:183], v[126:129]
	v_mfma_f32_16x16x32_bf16 v[122:125], v[156:159], v[180:183], v[122:125]
	v_mfma_f32_16x16x32_bf16 v[110:113], v[148:151], v[188:191], v[110:113]
	v_mfma_f32_16x16x32_bf16 v[106:109], v[156:159], v[188:191], v[106:109]
	v_mfma_f32_16x16x32_bf16 v[94:97], v[148:151], v[196:199], v[94:97]
	v_mfma_f32_16x16x32_bf16 v[90:93], v[156:159], v[196:199], v[90:93]
	v_mfma_f32_16x16x32_bf16 v[78:81], v[148:151], v[204:207], v[78:81]
	v_mfma_f32_16x16x32_bf16 v[74:77], v[156:159], v[204:207], v[74:77]
	v_mfma_f32_16x16x32_bf16 v[118:121], v[160:163], v[176:179], v[118:121]
	v_mfma_f32_16x16x32_bf16 v[114:117], v[168:171], v[176:179], v[114:117]
	v_mfma_f32_16x16x32_bf16 v[102:105], v[160:163], v[184:187], v[102:105]
	v_mfma_f32_16x16x32_bf16 v[98:101], v[168:171], v[184:187], v[98:101]
	v_mfma_f32_16x16x32_bf16 v[86:89], v[160:163], v[192:195], v[86:89]
	v_mfma_f32_16x16x32_bf16 v[82:85], v[168:171], v[192:195], v[82:85]
	v_mfma_f32_16x16x32_bf16 v[70:73], v[160:163], v[200:203], v[70:73]
	v_mfma_f32_16x16x32_bf16 v[66:69], v[168:171], v[200:203], v[66:69]
	v_mfma_f32_16x16x32_bf16 v[118:121], v[164:167], v[180:183], v[118:121]
	v_mfma_f32_16x16x32_bf16 v[114:117], v[172:175], v[180:183], v[114:117]
	v_mfma_f32_16x16x32_bf16 v[102:105], v[164:167], v[188:191], v[102:105]
	v_mfma_f32_16x16x32_bf16 v[98:101], v[172:175], v[188:191], v[98:101]
	v_mfma_f32_16x16x32_bf16 v[86:89], v[164:167], v[196:199], v[86:89]
	v_mfma_f32_16x16x32_bf16 v[82:85], v[172:175], v[196:199], v[82:85]
	v_mfma_f32_16x16x32_bf16 v[70:73], v[164:167], v[204:207], v[70:73]
	v_mfma_f32_16x16x32_bf16 v[66:69], v[172:175], v[204:207], v[66:69]
	s_barrier
	s_setprio 0
	s_add_i32 s64, s64, s7
	s_add_u32 s98, s44, 0x80
	s_addc_u32 s99, s45, 0
	s_mov_b32 m0, s64
	ds_read_b128 v[176:179], v147 offset:16384
	ds_read_b128 v[180:183], v147 offset:17408
	ds_read_b128 v[184:187], v147 offset:18432
	ds_read_b128 v[188:191], v147 offset:19456
	ds_read_b128 v[192:195], v147 offset:20480
	ds_read_b128 v[196:199], v147 offset:21504
	ds_read_b128 v[200:203], v147 offset:22528
	ds_read_b128 v[204:207], v147 offset:23552
	global_load_lds_dwordx4 v0, s[44:45]
	s_add_i32 m0, s64, 0x2000
	s_add_i32 s15, s15, s7
	global_load_lds_dwordx4 v134, s[44:45]
	s_add_u32 s44, s44, s30
	s_addc_u32 s45, s45, 0
	s_add_u32 s100, s44, 0x80
	s_addc_u32 s101, s45, 0
	s_mov_b32 m0, s15
	s_add_u32 vcc_lo, s10, 0x80
	s_addc_u32 vcc_hi, s11, 0
	global_load_lds_dwordx4 v0, s[44:45]
	s_add_i32 m0, s15, 0x2000
	s_nop 0
	global_load_lds_dwordx4 v134, s[44:45]
	s_mov_b32 m0, s21
	s_nop 0
	global_load_lds_dwordx4 v130, s[10:11]
	s_mov_b32 m0, s26
	s_nop 0
	global_load_lds_dwordx4 v132, s[10:11]
	s_waitcnt vmcnt(8) lgkmcnt(0)
	s_setprio 1
	s_barrier
	v_mfma_f32_16x16x32_bf16 v[62:65], v[140:143], v[176:179], v[62:65]
	v_mfma_f32_16x16x32_bf16 v[58:61], v[152:155], v[176:179], v[58:61]
	v_mfma_f32_16x16x32_bf16 v[46:49], v[140:143], v[184:187], v[46:49]
	v_mfma_f32_16x16x32_bf16 v[42:45], v[152:155], v[184:187], v[42:45]
	v_mfma_f32_16x16x32_bf16 v[30:33], v[140:143], v[192:195], v[30:33]
	v_mfma_f32_16x16x32_bf16 v[26:29], v[152:155], v[192:195], v[26:29]
	v_mfma_f32_16x16x32_bf16 v[14:17], v[140:143], v[200:203], v[14:17]
	v_mfma_f32_16x16x32_bf16 v[10:13], v[152:155], v[200:203], v[10:13]
	v_mfma_f32_16x16x32_bf16 v[62:65], v[148:151], v[180:183], v[62:65]
	v_mfma_f32_16x16x32_bf16 v[58:61], v[156:159], v[180:183], v[58:61]
	v_mfma_f32_16x16x32_bf16 v[46:49], v[148:151], v[188:191], v[46:49]
	v_mfma_f32_16x16x32_bf16 v[42:45], v[156:159], v[188:191], v[42:45]
	v_mfma_f32_16x16x32_bf16 v[30:33], v[148:151], v[196:199], v[30:33]
	v_mfma_f32_16x16x32_bf16 v[26:29], v[156:159], v[196:199], v[26:29]
	v_mfma_f32_16x16x32_bf16 v[14:17], v[148:151], v[204:207], v[14:17]
	v_mfma_f32_16x16x32_bf16 v[10:13], v[156:159], v[204:207], v[10:13]
	v_mfma_f32_16x16x32_bf16 v[54:57], v[160:163], v[176:179], v[54:57]
	v_mfma_f32_16x16x32_bf16 v[50:53], v[168:171], v[176:179], v[50:53]
	v_mfma_f32_16x16x32_bf16 v[38:41], v[160:163], v[184:187], v[38:41]
	v_mfma_f32_16x16x32_bf16 v[34:37], v[168:171], v[184:187], v[34:37]
	v_mfma_f32_16x16x32_bf16 v[22:25], v[160:163], v[192:195], v[22:25]
	v_mfma_f32_16x16x32_bf16 v[18:21], v[168:171], v[192:195], v[18:21]
	v_mfma_f32_16x16x32_bf16 v[6:9], v[160:163], v[200:203], v[6:9]
	v_mfma_f32_16x16x32_bf16 v[2:5], v[168:171], v[200:203], v[2:5]
	v_mfma_f32_16x16x32_bf16 v[54:57], v[164:167], v[180:183], v[54:57]
	v_mfma_f32_16x16x32_bf16 v[50:53], v[172:175], v[180:183], v[50:53]
	v_mfma_f32_16x16x32_bf16 v[38:41], v[164:167], v[188:191], v[38:41]
	v_mfma_f32_16x16x32_bf16 v[34:37], v[172:175], v[188:191], v[34:37]
	v_mfma_f32_16x16x32_bf16 v[22:25], v[164:167], v[196:199], v[22:25]
	v_mfma_f32_16x16x32_bf16 v[18:21], v[172:175], v[196:199], v[18:21]
	v_mfma_f32_16x16x32_bf16 v[6:9], v[164:167], v[204:207], v[6:9]
	v_mfma_f32_16x16x32_bf16 v[2:5], v[172:175], v[204:207], v[2:5]
	s_barrier
; #define PG8_STAGE(bufoff, gbase, voff) do { _Pragma("unroll") for (int _i = 0; _i < 2; ++_i) \
;         __builtin_amdgcn_global_load_lds((const unsigned*)((const char*)(gbase) + (voff)[_i]), (PG8_LAS unsigned*)(lds + (bufoff) + ldsw + _i * 8192), 16, 0, 0); } while (0)
; #define PG8_LDA(dst, b, h) do { _Pragma("unroll") for (int m = 0; m < 4; ++m) _Pragma("unroll") for (int k = 0; k < 2; ++k) dst[m][k] = *(const PG8_LAS bf16x8*)(lds + PG8_SA(b, h) + aoff + m * 2048 + k * 1024); } while (0)
; #define PG8_LDB(dst, b, h) do { _Pragma("unroll") for (int n = 0; n < 2; ++n) _Pragma("unroll") for (int k = 0; k < 2; ++k) dst[n][k] = *(const PG8_LAS bf16x8*)(lds + PG8_SB(b, h) + boff + n * 2048 + k * 1024); } while (0)
; #define PG8_MMA(ai, bj, At, Bt) do { __builtin_amdgcn_s_setprio(1); _Pragma("unroll") for (int m = 0; m < 4; ++m) _Pragma("unroll") for (int n = 0; n < 2; ++n) _Pragma("unroll") for (int k = 0; k < 2; ++k) \
;         acc[ai][bj][m][n] = __builtin_amdgcn_mfma_f32_16x16x32_bf16(Bt[n][k], At[m][k], acc[ai][bj][m][n], 0, 0, 0); __builtin_amdgcn_s_setprio(0); } while (0)
; #define PG8_WAIT_V(n) asm volatile("s_waitcnt vmcnt(" #n ")" ::: "memory")
; #define PG8_WAIT_L(n) asm volatile("s_waitcnt lgkmcnt(" #n ")" ::: "memory")
; #define PG8_BAR __builtin_amdgcn_s_barrier()
; #define PG8_SCHED __builtin_amdgcn_sched_barrier(0)
; template <class Epi, class Sched, bool ALIGN_EPI = false, bool SP2 = false>
; __device__ __forceinline__ void gemm_phase(PG8_LAS unsigned char* lds, const Gemm g, const Sched& S, const Epi& E) {
;     ...
;             PG8_LDB(B0, 1, 0); PG8_LDB(B1, 1, 1); PG8_SCHED; PG8_LDA(At, 1, 0); PG8_STAGE(PG8_SA(0, 1), a2 + hstep, voffA);
;             PG8_WAIT_V(8); PG8_WAIT_L(0); PG8_BAR; PG8_MMA(0, 0, At, B0); PG8_MMA(0, 1, At, B1); PG8_BAR; PG8_SCHED;
;             PG8_LDA(At, 1, 1); PG8_STAGE(PG8_SB(1, 0), b3, voffB); PG8_STAGE(PG8_SB(1, 1), b3 + hstep, voffB); PG8_STAGE(PG8_SA(1, 0), a3, voffA);
;             PG8_WAIT_V(8); PG8_WAIT_L(0); PG8_BAR; PG8_MMA(1, 0, At, B0); PG8_MMA(1, 1, At, B1); PG8_BAR; PG8_SCHED;
;     ...
;         if constexpr (ALIGN_EPI) { if (wr == 0) PG8_BAR; }
	s_setprio 0
	s_add_i32 s15, 0, 0x18000
	s_add_i32 s44, 0, 0x1c000
	ds_read_b128 v[140:143], v218 offset:32768
	ds_read_b128 v[148:151], v218 offset:33792
	ds_read_b128 v[152:155], v218 offset:34816
	ds_read_b128 v[156:159], v218 offset:35840
	ds_read_b128 v[160:163], v218 offset:49152
	ds_read_b128 v[164:167], v218 offset:50176
	ds_read_b128 v[168:171], v218 offset:51200
	ds_read_b128 v[172:175], v218 offset:52224
	s_add_u32 s10, s10, s30
	s_addc_u32 s11, s11, 0
	s_mov_b32 m0, s27
	ds_read_b128 v[176:179], v147 offset:32768
	ds_read_b128 v[180:183], v147 offset:33792
	ds_read_b128 v[184:187], v147 offset:34816
	ds_read_b128 v[188:191], v147 offset:35840
	ds_read_b128 v[192:195], v147 offset:36864
	ds_read_b128 v[196:199], v147 offset:37888
	ds_read_b128 v[200:203], v147 offset:38912
	ds_read_b128 v[204:207], v147 offset:39936
	global_load_lds_dwordx4 v130, s[10:11]
	s_mov_b32 m0, s54
	s_nop 0
	global_load_lds_dwordx4 v132, s[10:11]
	s_waitcnt vmcnt(8) lgkmcnt(0)
	s_setprio 1
	s_barrier
	v_mfma_f32_16x16x32_bf16 v[126:129], v[140:143], v[176:179], v[126:129]
	v_mfma_f32_16x16x32_bf16 v[122:125], v[152:155], v[176:179], v[122:125]
	v_mfma_f32_16x16x32_bf16 v[110:113], v[140:143], v[184:187], v[110:113]
	v_mfma_f32_16x16x32_bf16 v[106:109], v[152:155], v[184:187], v[106:109]
	v_mfma_f32_16x16x32_bf16 v[94:97], v[140:143], v[192:195], v[94:97]
	v_mfma_f32_16x16x32_bf16 v[90:93], v[152:155], v[192:195], v[90:93]
	v_mfma_f32_16x16x32_bf16 v[78:81], v[140:143], v[200:203], v[78:81]
	v_mfma_f32_16x16x32_bf16 v[74:77], v[152:155], v[200:203], v[74:77]
	v_mfma_f32_16x16x32_bf16 v[126:129], v[148:151], v[180:183], v[126:129]
	v_mfma_f32_16x16x32_bf16 v[122:125], v[156:159], v[180:183], v[122:125]
	v_mfma_f32_16x16x32_bf16 v[110:113], v[148:151], v[188:191], v[110:113]
	v_mfma_f32_16x16x32_bf16 v[106:109], v[156:159], v[188:191], v[106:109]
	v_mfma_f32_16x16x32_bf16 v[94:97], v[148:151], v[196:199], v[94:97]
	v_mfma_f32_16x16x32_bf16 v[90:93], v[156:159], v[196:199], v[90:93]
	v_mfma_f32_16x16x32_bf16 v[78:81], v[148:151], v[204:207], v[78:81]
	v_mfma_f32_16x16x32_bf16 v[74:77], v[156:159], v[204:207], v[74:77]
	v_mfma_f32_16x16x32_bf16 v[118:121], v[160:163], v[176:179], v[118:121]
	v_mfma_f32_16x16x32_bf16 v[114:117], v[168:171], v[176:179], v[114:117]
	v_mfma_f32_16x16x32_bf16 v[102:105], v[160:163], v[184:187], v[102:105]
	v_mfma_f32_16x16x32_bf16 v[98:101], v[168:171], v[184:187], v[98:101]
	v_mfma_f32_16x16x32_bf16 v[86:89], v[160:163], v[192:195], v[86:89]
	v_mfma_f32_16x16x32_bf16 v[82:85], v[168:171], v[192:195], v[82:85]
	v_mfma_f32_16x16x32_bf16 v[70:73], v[160:163], v[200:203], v[70:73]
	v_mfma_f32_16x16x32_bf16 v[66:69], v[168:171], v[200:203], v[66:69]
	v_mfma_f32_16x16x32_bf16 v[118:121], v[164:167], v[180:183], v[118:121]
	v_mfma_f32_16x16x32_bf16 v[114:117], v[172:175], v[180:183], v[114:117]
	v_mfma_f32_16x16x32_bf16 v[102:105], v[164:167], v[188:191], v[102:105]
	v_mfma_f32_16x16x32_bf16 v[98:101], v[172:175], v[188:191], v[98:101]
	v_mfma_f32_16x16x32_bf16 v[86:89], v[164:167], v[196:199], v[86:89]
	v_mfma_f32_16x16x32_bf16 v[82:85], v[172:175], v[196:199], v[82:85]
	v_mfma_f32_16x16x32_bf16 v[70:73], v[164:167], v[204:207], v[70:73]
	v_mfma_f32_16x16x32_bf16 v[66:69], v[172:175], v[204:207], v[66:69]
	s_barrier
	s_setprio 0
	s_add_i32 s10, s15, s7
	s_mov_b32 m0, s10
	ds_read_b128 v[176:179], v147 offset:49152
	ds_read_b128 v[180:183], v147 offset:50176
	ds_read_b128 v[184:187], v147 offset:51200
	ds_read_b128 v[188:191], v147 offset:52224
	ds_read_b128 v[192:195], v147 offset:53248
	ds_read_b128 v[196:199], v147 offset:54272
	ds_read_b128 v[200:203], v147 offset:55296
	ds_read_b128 v[204:207], v147 offset:56320
	global_load_lds_dwordx4 v0, s[98:99]
	s_add_i32 m0, s10, 0x2000
	s_add_i32 s10, s44, s7
	global_load_lds_dwordx4 v134, s[98:99]
	s_mov_b32 m0, s10
	s_nop 0
	global_load_lds_dwordx4 v0, s[100:101]
	s_add_i32 m0, s10, 0x2000
	s_nop 0
	global_load_lds_dwordx4 v134, s[100:101]
	s_mov_b32 m0, s16
	s_nop 0
	global_load_lds_dwordx4 v130, vcc
	s_mov_b32 m0, s17
	s_nop 0
	global_load_lds_dwordx4 v132, vcc
	s_waitcnt vmcnt(8) lgkmcnt(0)
	s_setprio 1
	s_barrier
	v_mfma_f32_16x16x32_bf16 v[62:65], v[140:143], v[176:179], v[62:65]
	v_mfma_f32_16x16x32_bf16 v[58:61], v[152:155], v[176:179], v[58:61]
	v_mfma_f32_16x16x32_bf16 v[46:49], v[140:143], v[184:187], v[46:49]
	v_mfma_f32_16x16x32_bf16 v[42:45], v[152:155], v[184:187], v[42:45]
	v_mfma_f32_16x16x32_bf16 v[30:33], v[140:143], v[192:195], v[30:33]
	v_mfma_f32_16x16x32_bf16 v[26:29], v[152:155], v[192:195], v[26:29]
	v_mfma_f32_16x16x32_bf16 v[14:17], v[140:143], v[200:203], v[14:17]
	v_mfma_f32_16x16x32_bf16 v[10:13], v[152:155], v[200:203], v[10:13]
	v_mfma_f32_16x16x32_bf16 v[62:65], v[148:151], v[180:183], v[62:65]
	v_mfma_f32_16x16x32_bf16 v[58:61], v[156:159], v[180:183], v[58:61]
	v_mfma_f32_16x16x32_bf16 v[46:49], v[148:151], v[188:191], v[46:49]
	v_mfma_f32_16x16x32_bf16 v[42:45], v[156:159], v[188:191], v[42:45]
	v_mfma_f32_16x16x32_bf16 v[30:33], v[148:151], v[196:199], v[30:33]
	v_mfma_f32_16x16x32_bf16 v[26:29], v[156:159], v[196:199], v[26:29]
	v_mfma_f32_16x16x32_bf16 v[14:17], v[148:151], v[204:207], v[14:17]
	v_mfma_f32_16x16x32_bf16 v[10:13], v[156:159], v[204:207], v[10:13]
	v_mfma_f32_16x16x32_bf16 v[54:57], v[160:163], v[176:179], v[54:57]
	v_mfma_f32_16x16x32_bf16 v[50:53], v[168:171], v[176:179], v[50:53]
	v_mfma_f32_16x16x32_bf16 v[38:41], v[160:163], v[184:187], v[38:41]
	v_mfma_f32_16x16x32_bf16 v[34:37], v[168:171], v[184:187], v[34:37]
	v_mfma_f32_16x16x32_bf16 v[22:25], v[160:163], v[192:195], v[22:25]
	v_mfma_f32_16x16x32_bf16 v[18:21], v[168:171], v[192:195], v[18:21]
	v_mfma_f32_16x16x32_bf16 v[6:9], v[160:163], v[200:203], v[6:9]
	v_mfma_f32_16x16x32_bf16 v[2:5], v[168:171], v[200:203], v[2:5]
	v_mfma_f32_16x16x32_bf16 v[54:57], v[164:167], v[180:183], v[54:57]
	v_mfma_f32_16x16x32_bf16 v[50:53], v[172:175], v[180:183], v[50:53]
	v_mfma_f32_16x16x32_bf16 v[38:41], v[164:167], v[188:191], v[38:41]
	v_mfma_f32_16x16x32_bf16 v[34:37], v[172:175], v[188:191], v[34:37]
	v_mfma_f32_16x16x32_bf16 v[22:25], v[164:167], v[196:199], v[22:25]
	v_mfma_f32_16x16x32_bf16 v[18:21], v[172:175], v[196:199], v[18:21]
	v_mfma_f32_16x16x32_bf16 v[6:9], v[164:167], v[204:207], v[6:9]
	v_mfma_f32_16x16x32_bf16 v[2:5], v[172:175], v[204:207], v[2:5]
	s_barrier
	s_setprio 0
	s_add_u32 s8, s8, 0x100
	s_addc_u32 s9, s9, 0
	s_add_u32 s12, s12, 0x100
	s_addc_u32 s13, s13, 0
	s_cmp_ge_u32 s14, s56
	s_mov_b32 s10, s14
	s_cbranch_scc0 .LBB0_223
	s_and_b64 vcc, exec, s[46:47]
	s_cbranch_vccz .LBB0_226
	s_barrier

; __global__ void __launch_bounds__(NTHR, 2) fwd_mega(Args args) {
;     ...
;             if (!(in_rep && PROBE_SUB == 2)) {
;                 static_assert(attn_body::ATTN_LDS_BYTES <= LDS_BARW, "attention LDS");
;                 for (int i = 0; i < 4; ++i) {
;                     int bh, qb;
;                     if (G == 256) { const int s = vcu & 7; bh = vcu >> 3; qb = (i == 0) ? s : (i == 1) ? 15 - s : (i == 2) ? 16 + s : 31 - s; }
;                     else { const int u = vcu + i * G; if (u >= 1024) break; bh = u >> 5; qb = u & 31; }
;                     int ts = 0;
;                     { const int NTf = 4 * (qb + 1); const float* cg = C2 + (size_t)bh * SEQ; const float* og = OFFS + (size_t)(bh >> 3) * 64 * 8 + (bh & 7);
;                       const float* qn = NRM + bh * 128 + 4 * qb; const float* kn = NRM + 4096 + bh * 128;
;                       const float Qn = fmaxf(fmaxf(qn[0], qn[1]), fmaxf(qn[2], qn[3])) * 1.01f;
;                       const int t0_ = lane, t1_ = lane + 64;
;                       const float k0_ = (t0_ < NTf) ? kn[t0_] : 0.f, k1_ = (t1_ < NTf) ? kn[t1_] : 0.f;
;                       float kmax = fmaxf(k0_, k1_);
; #pragma unroll
;                       for (int o = 1; o < 64; o <<= 1) kmax = fmaxf(kmax, __shfl_xor(kmax, o));
;                       kmax *= 1.01f;
;                       const int q0_ = 256 * qb; const float Cq = cg[q0_] + og[(q0_ >> 7) * 8];
;                       const float thr = -Qn * kmax - 150.f;
;                       bool keep0 = true, keep1 = true;
;                       if (t0_ < NTf) { const int e = 64 * t0_ + 63; keep0 = !(Qn * k0_ * 1.01f + (Cq - (cg[e] + og[(e >> 7) * 8])) < thr); }
;                       if (t1_ < NTf) { const int e = 64 * t1_ + 63; keep1 = !(Qn * k1_ * 1.01f + (Cq - (cg[e] + og[(e >> 7) * 8])) < thr); }
;                       const unsigned long long b0 = __ballot(keep0), b1 = __ballot(keep1);
;                       const int first = b0 ? __builtin_ctzll(b0) : 64 + (b1 ? __builtin_ctzll(b1) : 0);
;                       ts = first & ~1; if (ts > NTf - 4) ts = NTf - 4; if (ts < 0) ts = 0;
;                       ts = __builtin_amdgcn_readfirstlane(ts); }
;                     attn_body::attn_unit<40>(bh >> 3, bh & 7, qb, (const attn_body::bf16*)(PROJ + O_QB), (const attn_body::bf16*)(PROJ + O_KB), (const attn_body::bf16*)(PROJ + O_VB),
.LBB0_282:
	v_readfirstlane_b32 s98, v227
	s_lshr_b32 s98, s98, 6
	s_cmp_ge_u32 s98, 4
	s_cbranch_scc0 .Lfox_prio_done
	s_setprio 1

; #define PG8_STAGE(bufoff, gbase, voff) do { _Pragma("unroll") for (int _i = 0; _i < 2; ++_i) \
;         __builtin_amdgcn_global_load_lds((const unsigned*)((const char*)(gbase) + (voff)[_i]), (PG8_LAS unsigned*)(lds + (bufoff) + ldsw + _i * 8192), 16, 0, 0); } while (0)
; #define PG8_LDA(dst, b, h) do { _Pragma("unroll") for (int m = 0; m < 4; ++m) _Pragma("unroll") for (int k = 0; k < 2; ++k) dst[m][k] = *(const PG8_LAS bf16x8*)(lds + PG8_SA(b, h) + aoff + m * 2048 + k * 1024); } while (0)
; #define PG8_LDB(dst, b, h) do { _Pragma("unroll") for (int n = 0; n < 2; ++n) _Pragma("unroll") for (int k = 0; k < 2; ++k) dst[n][k] = *(const PG8_LAS bf16x8*)(lds + PG8_SB(b, h) + boff + n * 2048 + k * 1024); } while (0)
; #define PG8_WAIT_V(n) asm volatile("s_waitcnt vmcnt(" #n ")" ::: "memory")
; #define PG8_WAIT_L(n) asm volatile("s_waitcnt lgkmcnt(" #n ")" ::: "memory")
; #define PG8_BAR __builtin_amdgcn_s_barrier()
; #define PG8_SCHED __builtin_amdgcn_sched_barrier(0)
; template <class Epi, class Sched, bool ALIGN_EPI = false, bool SP2 = false>
; __device__ __forceinline__ void gemm_phase(PG8_LAS unsigned char* lds, const Gemm g, const Sched& S, const Epi& E) {
;     ...
;         const bool has_next = S.next(ui + 1, nxt);
;         const char* nA = has_next ? (const char*)g.A + (size_t)nxt.pm * tstep : cA; const char* nB = has_next ? (const char*)g.Bt + (size_t)nxt.pn * tstep : cB;
;         for (int t = 0; t < nt; t += 2) {
;             const bool last = (t == nt - 2);
;             const char* a1 = cA + (size_t)(t + 1) * kstep;
;             const char* a2 = last ? nA : cA + (size_t)(t + 2) * kstep; const char* b2 = last ? nB : cB + (size_t)(t + 2) * kstep;
;             const char* a3 = a2 + kstep; const char* b3 = b2 + kstep;
;             if (last && has_next) S.a_ready(nxt);
;             if constexpr (SP2) {
;             PG8_LDB(B0, 0, 0); PG8_LDB(B1, 0, 1); PG8_SCHED; PG8_LDA(At, 0, 0); PG8_STAGE(PG8_SA(1, 1), a1 + hstep, voffA);
;             PG8_WAIT_V(8); PG8_WAIT_L(0); PG8_BAR; PG8_MMA(0, 0, At, B0); PG8_MMA(0, 1, At, B1); PG8_BAR; PG8_SCHED;
;             PG8_LDA(At, 0, 1); PG8_STAGE(PG8_SB(0, 0), b2, voffB); PG8_STAGE(PG8_SB(0, 1), b2 + hstep, voffB); PG8_STAGE(PG8_SA(0, 0), a2, voffA);
;             PG8_WAIT_V(8); PG8_WAIT_L(0); PG8_BAR; PG8_MMA(1, 0, At, B0); PG8_MMA(1, 1, At, B1); PG8_BAR; PG8_SCHED;
.Lstg4_done:
	s_ashr_i32 s37, s36, 31
	s_lshl_b64 s[26:27], s[36:37], 20
	s_add_u32 s26, s18, s26
	s_addc_u32 s27, s19, s27
	s_and_b64 s[44:45], s[40:41], exec
	s_cselect_b32 s37, s27, s51
	s_cselect_b32 s43, s26, s50
	s_ashr_i32 s23, s22, 31
	s_lshl_b64 s[44:45], s[22:23], 20
	s_add_u32 s44, s96, s44
	s_addc_u32 s45, s97, s45
	s_and_b64 s[52:53], s[40:41], exec
	s_cselect_b32 s23, s45, s11
	s_cselect_b32 s56, s44, s10
	s_add_u32 s50, s50, 0x80080
	s_addc_u32 s51, s51, 0
	s_add_u32 s57, s10, 0x100
	s_addc_u32 s58, s11, 0
	s_mov_b32 s59, -2
	v_add_u32_e32 v248, 0x10000, v149
	s_add_u32 s10, s50, 0xfff80080
	s_addc_u32 s11, s51, -1
	s_add_i32 s60, 0, 0x10000
	s_cmp_eq_u32 s59, 28
	s_cselect_b32 s53, s37, s11
	s_cselect_b32 s52, s43, s10
	s_cselect_b32 s11, s23, s58
	s_cselect_b32 s10, s56, s57
	s_add_i32 s62, 0, 0x14000
	ds_read_b128 v[140:143], v248
	ds_read_b128 v[152:155], v248 offset:1024
	ds_read_b128 v[156:159], v248 offset:2048
	ds_read_b128 v[160:163], v248 offset:3072
	ds_read_b128 v[164:167], v248 offset:16384
	ds_read_b128 v[168:171], v248 offset:17408
	ds_read_b128 v[172:175], v248 offset:18432
	ds_read_b128 v[176:179], v248 offset:19456
	s_add_i32 m0, s5, 0xc000
	ds_read_b128 v[180:183], v151
	ds_read_b128 v[184:187], v151 offset:1024
	ds_read_b128 v[188:191], v151 offset:2048
	ds_read_b128 v[192:195], v151 offset:3072
	ds_read_b128 v[196:199], v151 offset:4096
	ds_read_b128 v[200:203], v151 offset:5120
	ds_read_b128 v[204:207], v151 offset:6144
	ds_read_b128 v[208:211], v151 offset:7168
	global_load_lds_dwordx4 v136, s[50:51]
	s_add_i32 m0, s5, 0xe000
	s_nop 0
	global_load_lds_dwordx4 v138, s[50:51]
	s_waitcnt vmcnt(8) lgkmcnt(0)
	s_setprio 1
	s_barrier
	v_mfma_f32_16x16x32_bf16 v[126:129], v[140:143], v[180:183], 0
	v_mfma_f32_16x16x32_bf16 v[122:125], v[156:159], v[180:183], 0
	v_mfma_f32_16x16x32_bf16 v[110:113], v[140:143], v[188:191], 0
	v_mfma_f32_16x16x32_bf16 v[106:109], v[156:159], v[188:191], 0
	v_mfma_f32_16x16x32_bf16 v[94:97], v[140:143], v[196:199], 0
	v_mfma_f32_16x16x32_bf16 v[90:93], v[156:159], v[196:199], 0
	v_mfma_f32_16x16x32_bf16 v[78:81], v[140:143], v[204:207], 0
	v_mfma_f32_16x16x32_bf16 v[74:77], v[156:159], v[204:207], 0
	v_mfma_f32_16x16x32_bf16 v[126:129], v[152:155], v[184:187], v[126:129]
	v_mfma_f32_16x16x32_bf16 v[122:125], v[160:163], v[184:187], v[122:125]
	v_mfma_f32_16x16x32_bf16 v[110:113], v[152:155], v[192:195], v[110:113]
	v_mfma_f32_16x16x32_bf16 v[106:109], v[160:163], v[192:195], v[106:109]
	v_mfma_f32_16x16x32_bf16 v[94:97], v[152:155], v[200:203], v[94:97]
	v_mfma_f32_16x16x32_bf16 v[90:93], v[160:163], v[200:203], v[90:93]
	v_mfma_f32_16x16x32_bf16 v[78:81], v[152:155], v[208:211], v[78:81]
	v_mfma_f32_16x16x32_bf16 v[74:77], v[160:163], v[208:211], v[74:77]
	v_mfma_f32_16x16x32_bf16 v[118:121], v[164:167], v[180:183], 0
	v_mfma_f32_16x16x32_bf16 v[114:117], v[172:175], v[180:183], 0
	v_mfma_f32_16x16x32_bf16 v[102:105], v[164:167], v[188:191], 0
	v_mfma_f32_16x16x32_bf16 v[98:101], v[172:175], v[188:191], 0
	v_mfma_f32_16x16x32_bf16 v[86:89], v[164:167], v[196:199], 0
	v_mfma_f32_16x16x32_bf16 v[82:85], v[172:175], v[196:199], 0
	v_mfma_f32_16x16x32_bf16 v[70:73], v[164:167], v[204:207], 0
	v_mfma_f32_16x16x32_bf16 v[66:69], v[172:175], v[204:207], 0
	v_mfma_f32_16x16x32_bf16 v[118:121], v[168:171], v[184:187], v[118:121]
	v_mfma_f32_16x16x32_bf16 v[114:117], v[176:179], v[184:187], v[114:117]
	v_mfma_f32_16x16x32_bf16 v[102:105], v[168:171], v[192:195], v[102:105]
	v_mfma_f32_16x16x32_bf16 v[98:101], v[176:179], v[192:195], v[98:101]
	v_mfma_f32_16x16x32_bf16 v[86:89], v[168:171], v[200:203], v[86:89]
	v_mfma_f32_16x16x32_bf16 v[82:85], v[176:179], v[200:203], v[82:85]
	v_mfma_f32_16x16x32_bf16 v[70:73], v[168:171], v[208:211], v[70:73]
	v_mfma_f32_16x16x32_bf16 v[66:69], v[176:179], v[208:211], v[66:69]
	s_barrier
	s_setprio 0
	s_add_i32 s60, s60, s4
	s_add_u32 s100, s10, 0x80
	s_addc_u32 s101, s11, 0
	s_mov_b32 m0, s60
	ds_read_b128 v[180:183], v151 offset:16384
	ds_read_b128 v[184:187], v151 offset:17408
	ds_read_b128 v[188:191], v151 offset:18432
	ds_read_b128 v[192:195], v151 offset:19456
	ds_read_b128 v[196:199], v151 offset:20480
	ds_read_b128 v[200:203], v151 offset:21504
	ds_read_b128 v[204:207], v151 offset:22528
	ds_read_b128 v[208:211], v151 offset:23552
	global_load_lds_dwordx4 v0, s[10:11]
	s_add_i32 m0, s60, 0x2000
	s_add_u32 s60, s10, 0x80000
	s_addc_u32 s61, s11, 0
	s_add_i32 s62, s62, s4
	global_load_lds_dwordx4 v134, s[10:11]
	s_mov_b32 m0, s62
	s_add_u32 s98, s52, 0x80
	s_addc_u32 s99, s53, 0
	global_load_lds_dwordx4 v0, s[60:61]
	s_add_i32 m0, s62, 0x2000
	s_nop 0
	global_load_lds_dwordx4 v134, s[60:61]
	s_mov_b32 m0, s5
	s_nop 0
	global_load_lds_dwordx4 v130, s[52:53]
	s_mov_b32 m0, s6
	s_nop 0
	global_load_lds_dwordx4 v132, s[52:53]
	s_waitcnt vmcnt(8) lgkmcnt(0)
	s_setprio 1
	s_barrier
; #define PG8_STAGE(bufoff, gbase, voff) do { _Pragma("unroll") for (int _i = 0; _i < 2; ++_i) \
;         __builtin_amdgcn_global_load_lds((const unsigned*)((const char*)(gbase) + (voff)[_i]), (PG8_LAS unsigned*)(lds + (bufoff) + ldsw + _i * 8192), 16, 0, 0); } while (0)
; #define PG8_LDA(dst, b, h) do { _Pragma("unroll") for (int m = 0; m < 4; ++m) _Pragma("unroll") for (int k = 0; k < 2; ++k) dst[m][k] = *(const PG8_LAS bf16x8*)(lds + PG8_SA(b, h) + aoff + m * 2048 + k * 1024); } while (0)
; #define PG8_LDB(dst, b, h) do { _Pragma("unroll") for (int n = 0; n < 2; ++n) _Pragma("unroll") for (int k = 0; k < 2; ++k) dst[n][k] = *(const PG8_LAS bf16x8*)(lds + PG8_SB(b, h) + boff + n * 2048 + k * 1024); } while (0)
; #define PG8_MMA(ai, bj, At, Bt) do { __builtin_amdgcn_s_setprio(1); _Pragma("unroll") for (int m = 0; m < 4; ++m) _Pragma("unroll") for (int n = 0; n < 2; ++n) _Pragma("unroll") for (int k = 0; k < 2; ++k) \
;         acc[ai][bj][m][n] = __builtin_amdgcn_mfma_f32_16x16x32_bf16(Bt[n][k], At[m][k], acc[ai][bj][m][n], 0, 0, 0); __builtin_amdgcn_s_setprio(0); } while (0)
; #define PG8_WAIT_V(n) asm volatile("s_waitcnt vmcnt(" #n ")" ::: "memory")
; #define PG8_WAIT_L(n) asm volatile("s_waitcnt lgkmcnt(" #n ")" ::: "memory")
; #define PG8_BAR __builtin_amdgcn_s_barrier()
; #define PG8_SCHED __builtin_amdgcn_sched_barrier(0)
; template <class Epi, class Sched, bool ALIGN_EPI = false, bool SP2 = false>
; __device__ __forceinline__ void gemm_phase(PG8_LAS unsigned char* lds, const Gemm g, const Sched& S, const Epi& E) {
;     ...
;             PG8_WAIT_V(8); PG8_WAIT_L(0); PG8_BAR; PG8_MMA(0, 0, At, B0); PG8_MMA(0, 1, At, B1); PG8_BAR; PG8_SCHED;
;             PG8_LDA(At, 0, 1); PG8_STAGE(PG8_SB(0, 0), b2, voffB); PG8_STAGE(PG8_SB(0, 1), b2 + hstep, voffB); PG8_STAGE(PG8_SA(0, 0), a2, voffA);
;             PG8_WAIT_V(8); PG8_WAIT_L(0); PG8_BAR; PG8_MMA(1, 0, At, B0); PG8_MMA(1, 1, At, B1); PG8_BAR; PG8_SCHED;
;             PG8_LDB(B0, 1, 0); PG8_LDB(B1, 1, 1); PG8_SCHED; PG8_LDA(At, 1, 0); PG8_STAGE(PG8_SA(0, 1), a2 + hstep, voffA);
;             PG8_WAIT_V(8); PG8_WAIT_L(0); PG8_BAR; PG8_MMA(0, 0, At, B0); PG8_MMA(0, 1, At, B1); PG8_BAR; PG8_SCHED;
	v_mfma_f32_16x16x32_bf16 v[62:65], v[140:143], v[180:183], 0
	v_mfma_f32_16x16x32_bf16 v[58:61], v[156:159], v[180:183], 0
	v_mfma_f32_16x16x32_bf16 v[46:49], v[140:143], v[188:191], 0
	v_mfma_f32_16x16x32_bf16 v[42:45], v[156:159], v[188:191], 0
	v_mfma_f32_16x16x32_bf16 v[30:33], v[140:143], v[196:199], 0
	v_mfma_f32_16x16x32_bf16 v[26:29], v[156:159], v[196:199], 0
	v_mfma_f32_16x16x32_bf16 v[14:17], v[140:143], v[204:207], 0
	v_mfma_f32_16x16x32_bf16 v[10:13], v[156:159], v[204:207], 0
	v_mfma_f32_16x16x32_bf16 v[62:65], v[152:155], v[184:187], v[62:65]
	v_mfma_f32_16x16x32_bf16 v[58:61], v[160:163], v[184:187], v[58:61]
	v_mfma_f32_16x16x32_bf16 v[46:49], v[152:155], v[192:195], v[46:49]
	v_mfma_f32_16x16x32_bf16 v[42:45], v[160:163], v[192:195], v[42:45]
	v_mfma_f32_16x16x32_bf16 v[30:33], v[152:155], v[200:203], v[30:33]
	v_mfma_f32_16x16x32_bf16 v[26:29], v[160:163], v[200:203], v[26:29]
	v_mfma_f32_16x16x32_bf16 v[14:17], v[152:155], v[208:211], v[14:17]
	v_mfma_f32_16x16x32_bf16 v[10:13], v[160:163], v[208:211], v[10:13]
	v_mfma_f32_16x16x32_bf16 v[54:57], v[164:167], v[180:183], 0
	v_mfma_f32_16x16x32_bf16 v[50:53], v[172:175], v[180:183], 0
	v_mfma_f32_16x16x32_bf16 v[38:41], v[164:167], v[188:191], 0
	v_mfma_f32_16x16x32_bf16 v[34:37], v[172:175], v[188:191], 0
	v_mfma_f32_16x16x32_bf16 v[22:25], v[164:167], v[196:199], 0
	v_mfma_f32_16x16x32_bf16 v[18:21], v[172:175], v[196:199], 0
	v_mfma_f32_16x16x32_bf16 v[6:9], v[164:167], v[204:207], 0
	v_mfma_f32_16x16x32_bf16 v[2:5], v[172:175], v[204:207], 0
	v_mfma_f32_16x16x32_bf16 v[54:57], v[168:171], v[184:187], v[54:57]
	v_mfma_f32_16x16x32_bf16 v[50:53], v[176:179], v[184:187], v[50:53]
	v_mfma_f32_16x16x32_bf16 v[38:41], v[168:171], v[192:195], v[38:41]
	v_mfma_f32_16x16x32_bf16 v[34:37], v[176:179], v[192:195], v[34:37]
	v_mfma_f32_16x16x32_bf16 v[22:25], v[168:171], v[200:203], v[22:25]
	v_mfma_f32_16x16x32_bf16 v[18:21], v[176:179], v[200:203], v[18:21]
	v_mfma_f32_16x16x32_bf16 v[6:9], v[168:171], v[208:211], v[6:9]
	v_mfma_f32_16x16x32_bf16 v[2:5], v[176:179], v[208:211], v[2:5]
	s_barrier
	s_setprio 0
	s_add_i32 s60, 0, 0x18000
	s_add_i32 s61, 0, 0x1c000
	ds_read_b128 v[140:143], v248 offset:32768
	ds_read_b128 v[152:155], v248 offset:33792
	ds_read_b128 v[156:159], v248 offset:34816
	ds_read_b128 v[160:163], v248 offset:35840
	ds_read_b128 v[164:167], v248 offset:49152
	ds_read_b128 v[168:171], v248 offset:50176
	ds_read_b128 v[172:175], v248 offset:51200
	ds_read_b128 v[176:179], v248 offset:52224
	s_add_u32 s52, s52, 0x80000
	s_addc_u32 s53, s53, 0
	s_mov_b32 m0, s7
	ds_read_b128 v[180:183], v151 offset:32768
	ds_read_b128 v[184:187], v151 offset:33792
	ds_read_b128 v[188:191], v151 offset:34816
	ds_read_b128 v[192:195], v151 offset:35840
	ds_read_b128 v[196:199], v151 offset:36864
	ds_read_b128 v[200:203], v151 offset:37888
	ds_read_b128 v[204:207], v151 offset:38912
	ds_read_b128 v[208:211], v151 offset:39936
	global_load_lds_dwordx4 v130, s[52:53]
	s_mov_b32 m0, s17
	s_nop 0
	global_load_lds_dwordx4 v132, s[52:53]
	s_waitcnt vmcnt(8) lgkmcnt(0)
	s_setprio 1
	s_barrier
	v_mfma_f32_16x16x32_bf16 v[126:129], v[140:143], v[180:183], v[126:129]
	v_mfma_f32_16x16x32_bf16 v[122:125], v[156:159], v[180:183], v[122:125]
	v_mfma_f32_16x16x32_bf16 v[110:113], v[140:143], v[188:191], v[110:113]
	v_mfma_f32_16x16x32_bf16 v[106:109], v[156:159], v[188:191], v[106:109]
	v_mfma_f32_16x16x32_bf16 v[94:97], v[140:143], v[196:199], v[94:97]
	v_mfma_f32_16x16x32_bf16 v[90:93], v[156:159], v[196:199], v[90:93]
	v_mfma_f32_16x16x32_bf16 v[78:81], v[140:143], v[204:207], v[78:81]
	v_mfma_f32_16x16x32_bf16 v[74:77], v[156:159], v[204:207], v[74:77]
	v_mfma_f32_16x16x32_bf16 v[126:129], v[152:155], v[184:187], v[126:129]
	v_mfma_f32_16x16x32_bf16 v[122:125], v[160:163], v[184:187], v[122:125]
	v_mfma_f32_16x16x32_bf16 v[110:113], v[152:155], v[192:195], v[110:113]
	v_mfma_f32_16x16x32_bf16 v[106:109], v[160:163], v[192:195], v[106:109]
	v_mfma_f32_16x16x32_bf16 v[94:97], v[152:155], v[200:203], v[94:97]
	v_mfma_f32_16x16x32_bf16 v[90:93], v[160:163], v[200:203], v[90:93]
	v_mfma_f32_16x16x32_bf16 v[78:81], v[152:155], v[208:211], v[78:81]
	v_mfma_f32_16x16x32_bf16 v[74:77], v[160:163], v[208:211], v[74:77]
	v_mfma_f32_16x16x32_bf16 v[118:121], v[164:167], v[180:183], v[118:121]
	v_mfma_f32_16x16x32_bf16 v[114:117], v[172:175], v[180:183], v[114:117]
	v_mfma_f32_16x16x32_bf16 v[102:105], v[164:167], v[188:191], v[102:105]
	v_mfma_f32_16x16x32_bf16 v[98:101], v[172:175], v[188:191], v[98:101]
	v_mfma_f32_16x16x32_bf16 v[86:89], v[164:167], v[196:199], v[86:89]
	v_mfma_f32_16x16x32_bf16 v[82:85], v[172:175], v[196:199], v[82:85]
	v_mfma_f32_16x16x32_bf16 v[70:73], v[164:167], v[204:207], v[70:73]
	v_mfma_f32_16x16x32_bf16 v[66:69], v[172:175], v[204:207], v[66:69]
	v_mfma_f32_16x16x32_bf16 v[118:121], v[168:171], v[184:187], v[118:121]
	v_mfma_f32_16x16x32_bf16 v[114:117], v[176:179], v[184:187], v[114:117]
	v_mfma_f32_16x16x32_bf16 v[102:105], v[168:171], v[192:195], v[102:105]
	v_mfma_f32_16x16x32_bf16 v[98:101], v[176:179], v[192:195], v[98:101]
	v_mfma_f32_16x16x32_bf16 v[86:89], v[168:171], v[200:203], v[86:89]
	v_mfma_f32_16x16x32_bf16 v[82:85], v[176:179], v[200:203], v[82:85]
	v_mfma_f32_16x16x32_bf16 v[70:73], v[168:171], v[208:211], v[70:73]
	v_mfma_f32_16x16x32_bf16 v[66:69], v[176:179], v[208:211], v[66:69]
	s_barrier
; #define PG8_STAGE(bufoff, gbase, voff) do { _Pragma("unroll") for (int _i = 0; _i < 2; ++_i) \
;         __builtin_amdgcn_global_load_lds((const unsigned*)((const char*)(gbase) + (voff)[_i]), (PG8_LAS unsigned*)(lds + (bufoff) + ldsw + _i * 8192), 16, 0, 0); } while (0)
; #define PG8_LDA(dst, b, h) do { _Pragma("unroll") for (int m = 0; m < 4; ++m) _Pragma("unroll") for (int k = 0; k < 2; ++k) dst[m][k] = *(const PG8_LAS bf16x8*)(lds + PG8_SA(b, h) + aoff + m * 2048 + k * 1024); } while (0)
; #define PG8_LDB(dst, b, h) do { _Pragma("unroll") for (int n = 0; n < 2; ++n) _Pragma("unroll") for (int k = 0; k < 2; ++k) dst[n][k] = *(const PG8_LAS bf16x8*)(lds + PG8_SB(b, h) + boff + n * 2048 + k * 1024); } while (0)
; #define PG8_MMA(ai, bj, At, Bt) do { __builtin_amdgcn_s_setprio(1); _Pragma("unroll") for (int m = 0; m < 4; ++m) _Pragma("unroll") for (int n = 0; n < 2; ++n) _Pragma("unroll") for (int k = 0; k < 2; ++k) \
;         acc[ai][bj][m][n] = __builtin_amdgcn_mfma_f32_16x16x32_bf16(Bt[n][k], At[m][k], acc[ai][bj][m][n], 0, 0, 0); __builtin_amdgcn_s_setprio(0); } while (0)
; #define PG8_WAIT_V(n) asm volatile("s_waitcnt vmcnt(" #n ")" ::: "memory")
; template <class Epi, class Sched, bool ALIGN_EPI = false, bool SP2 = false>
; __device__ __forceinline__ void gemm_phase(PG8_LAS unsigned char* lds, const Gemm g, const Sched& S, const Epi& E) {
;     ...
;             PG8_LDB(B0, 0, 0); PG8_LDB(B1, 0, 1); PG8_SCHED; PG8_LDA(At, 0, 0); PG8_STAGE(PG8_SA(1, 1), a1 + hstep, voffA);
;             PG8_WAIT_V(8); PG8_WAIT_L(0); PG8_BAR; PG8_MMA(0, 0, At, B0); PG8_MMA(0, 1, At, B1); PG8_BAR; PG8_SCHED;
;             PG8_LDA(At, 0, 1); PG8_STAGE(PG8_SB(0, 0), b2, voffB); PG8_STAGE(PG8_SB(0, 1), b2 + hstep, voffB); PG8_STAGE(PG8_SA(0, 0), a2, voffA);
;             PG8_WAIT_V(8); PG8_WAIT_L(0); PG8_BAR; PG8_MMA(1, 0, At, B0); PG8_MMA(1, 1, At, B1); PG8_BAR; PG8_SCHED;
;             PG8_LDB(B0, 1, 0); PG8_LDB(B1, 1, 1); PG8_SCHED; PG8_LDA(At, 1, 0); PG8_STAGE(PG8_SA(0, 1), a2 + hstep, voffA);
;             PG8_WAIT_V(8); PG8_WAIT_L(0); PG8_BAR; PG8_MMA(0, 0, At, B0); PG8_MMA(0, 1, At, B1); PG8_BAR; PG8_SCHED;
;             PG8_LDA(At, 1, 1); PG8_STAGE(PG8_SB(1, 0), b3, voffB); PG8_STAGE(PG8_SB(1, 1), b3 + hstep, voffB); PG8_STAGE(PG8_SA(1, 0), a3, voffA);
;             PG8_WAIT_V(8); PG8_WAIT_L(0); PG8_BAR; PG8_MMA(1, 0, At, B0); PG8_MMA(1, 1, At, B1); PG8_BAR; PG8_SCHED;
	s_setprio 0
	s_add_i32 s52, s60, s4
	s_mov_b32 m0, s52
	ds_read_b128 v[180:183], v151 offset:49152
	ds_read_b128 v[184:187], v151 offset:50176
	ds_read_b128 v[188:191], v151 offset:51200
	ds_read_b128 v[192:195], v151 offset:52224
	ds_read_b128 v[196:199], v151 offset:53248
	ds_read_b128 v[200:203], v151 offset:54272
	ds_read_b128 v[204:207], v151 offset:55296
	ds_read_b128 v[208:211], v151 offset:56320
	global_load_lds_dwordx4 v0, s[100:101]
	s_add_i32 m0, s52, 0x2000
	s_add_i32 s52, s61, s4
	global_load_lds_dwordx4 v134, s[100:101]
	s_add_u32 s10, s10, 0x80080
	s_addc_u32 s11, s11, 0
	s_mov_b32 m0, s52
	s_nop 0
	global_load_lds_dwordx4 v0, s[10:11]
	s_add_i32 m0, s52, 0x2000
	s_nop 0
	global_load_lds_dwordx4 v134, s[10:11]
	s_mov_b32 m0, s30
	s_nop 0
	global_load_lds_dwordx4 v130, s[98:99]
	s_mov_b32 m0, s47
	s_nop 0
	global_load_lds_dwordx4 v132, s[98:99]
	s_waitcnt vmcnt(8) lgkmcnt(0)
	s_setprio 1
	s_barrier
	v_mfma_f32_16x16x32_bf16 v[62:65], v[140:143], v[180:183], v[62:65]
	v_mfma_f32_16x16x32_bf16 v[58:61], v[156:159], v[180:183], v[58:61]
	v_mfma_f32_16x16x32_bf16 v[46:49], v[140:143], v[188:191], v[46:49]
	v_mfma_f32_16x16x32_bf16 v[42:45], v[156:159], v[188:191], v[42:45]
	v_mfma_f32_16x16x32_bf16 v[30:33], v[140:143], v[196:199], v[30:33]
	v_mfma_f32_16x16x32_bf16 v[26:29], v[156:159], v[196:199], v[26:29]
	v_mfma_f32_16x16x32_bf16 v[14:17], v[140:143], v[204:207], v[14:17]
	v_mfma_f32_16x16x32_bf16 v[10:13], v[156:159], v[204:207], v[10:13]
	v_mfma_f32_16x16x32_bf16 v[62:65], v[152:155], v[184:187], v[62:65]
	v_mfma_f32_16x16x32_bf16 v[58:61], v[160:163], v[184:187], v[58:61]
	v_mfma_f32_16x16x32_bf16 v[46:49], v[152:155], v[192:195], v[46:49]
	v_mfma_f32_16x16x32_bf16 v[42:45], v[160:163], v[192:195], v[42:45]
	v_mfma_f32_16x16x32_bf16 v[30:33], v[152:155], v[200:203], v[30:33]
	v_mfma_f32_16x16x32_bf16 v[26:29], v[160:163], v[200:203], v[26:29]
	v_mfma_f32_16x16x32_bf16 v[14:17], v[152:155], v[208:211], v[14:17]
	v_mfma_f32_16x16x32_bf16 v[10:13], v[160:163], v[208:211], v[10:13]
	v_mfma_f32_16x16x32_bf16 v[54:57], v[164:167], v[180:183], v[54:57]
	v_mfma_f32_16x16x32_bf16 v[50:53], v[172:175], v[180:183], v[50:53]
	v_mfma_f32_16x16x32_bf16 v[38:41], v[164:167], v[188:191], v[38:41]
	v_mfma_f32_16x16x32_bf16 v[34:37], v[172:175], v[188:191], v[34:37]
	v_mfma_f32_16x16x32_bf16 v[22:25], v[164:167], v[196:199], v[22:25]
	v_mfma_f32_16x16x32_bf16 v[18:21], v[172:175], v[196:199], v[18:21]
	v_mfma_f32_16x16x32_bf16 v[6:9], v[164:167], v[204:207], v[6:9]
	v_mfma_f32_16x16x32_bf16 v[2:5], v[172:175], v[204:207], v[2:5]
	v_mfma_f32_16x16x32_bf16 v[54:57], v[168:171], v[184:187], v[54:57]
	v_mfma_f32_16x16x32_bf16 v[50:53], v[176:179], v[184:187], v[50:53]
	v_mfma_f32_16x16x32_bf16 v[38:41], v[168:171], v[192:195], v[38:41]
	v_mfma_f32_16x16x32_bf16 v[34:37], v[176:179], v[192:195], v[34:37]
	v_mfma_f32_16x16x32_bf16 v[22:25], v[168:171], v[200:203], v[22:25]
	v_mfma_f32_16x16x32_bf16 v[18:21], v[176:179], v[200:203], v[18:21]
	v_mfma_f32_16x16x32_bf16 v[6:9], v[168:171], v[208:211], v[6:9]
	v_mfma_f32_16x16x32_bf16 v[2:5], v[176:179], v[208:211], v[2:5]
	s_barrier
	s_setprio 0
	s_add_i32 s59, s59, 2
	s_add_u32 s50, s50, 0x100
	s_addc_u32 s51, s51, 0
	s_add_u32 s57, s57, 0x100
	s_addc_u32 s58, s58, 0
.LBB0_559:
	s_add_u32 s10, s50, 0xfff80080
	s_addc_u32 s11, s51, -1
	s_add_i32 s60, 0, 0x10000
	s_cmp_eq_u32 s59, 28
	s_cselect_b32 s53, s37, s11
	s_cselect_b32 s52, s43, s10
	s_cselect_b32 s11, s23, s58
	s_cselect_b32 s10, s56, s57
	s_add_i32 s62, 0, 0x14000
	ds_read_b128 v[140:143], v248
	ds_read_b128 v[152:155], v248 offset:1024
	ds_read_b128 v[156:159], v248 offset:2048
	ds_read_b128 v[160:163], v248 offset:3072
	ds_read_b128 v[164:167], v248 offset:16384
	ds_read_b128 v[168:171], v248 offset:17408
	ds_read_b128 v[172:175], v248 offset:18432
	ds_read_b128 v[176:179], v248 offset:19456
	s_add_i32 m0, s5, 0xc000
	ds_read_b128 v[180:183], v151
	ds_read_b128 v[184:187], v151 offset:1024
	ds_read_b128 v[188:191], v151 offset:2048
	ds_read_b128 v[192:195], v151 offset:3072
	ds_read_b128 v[196:199], v151 offset:4096
	ds_read_b128 v[200:203], v151 offset:5120
	ds_read_b128 v[204:207], v151 offset:6144
	ds_read_b128 v[208:211], v151 offset:7168
	global_load_lds_dwordx4 v136, s[50:51]
	s_add_i32 m0, s5, 0xe000
	s_nop 0
	global_load_lds_dwordx4 v138, s[50:51]
	s_waitcnt vmcnt(8) lgkmcnt(0)
	s_setprio 1
	s_barrier
	v_mfma_f32_16x16x32_bf16 v[126:129], v[140:143], v[180:183], v[126:129]
	v_mfma_f32_16x16x32_bf16 v[122:125], v[156:159], v[180:183], v[122:125]
	v_mfma_f32_16x16x32_bf16 v[110:113], v[140:143], v[188:191], v[110:113]
	v_mfma_f32_16x16x32_bf16 v[106:109], v[156:159], v[188:191], v[106:109]
	v_mfma_f32_16x16x32_bf16 v[94:97], v[140:143], v[196:199], v[94:97]
	v_mfma_f32_16x16x32_bf16 v[90:93], v[156:159], v[196:199], v[90:93]
	v_mfma_f32_16x16x32_bf16 v[78:81], v[140:143], v[204:207], v[78:81]
	v_mfma_f32_16x16x32_bf16 v[74:77], v[156:159], v[204:207], v[74:77]
	v_mfma_f32_16x16x32_bf16 v[126:129], v[152:155], v[184:187], v[126:129]
	v_mfma_f32_16x16x32_bf16 v[122:125], v[160:163], v[184:187], v[122:125]
	v_mfma_f32_16x16x32_bf16 v[110:113], v[152:155], v[192:195], v[110:113]
	v_mfma_f32_16x16x32_bf16 v[106:109], v[160:163], v[192:195], v[106:109]
	v_mfma_f32_16x16x32_bf16 v[94:97], v[152:155], v[200:203], v[94:97]
	v_mfma_f32_16x16x32_bf16 v[90:93], v[160:163], v[200:203], v[90:93]
	v_mfma_f32_16x16x32_bf16 v[78:81], v[152:155], v[208:211], v[78:81]
	v_mfma_f32_16x16x32_bf16 v[74:77], v[160:163], v[208:211], v[74:77]
	v_mfma_f32_16x16x32_bf16 v[118:121], v[164:167], v[180:183], v[118:121]
	v_mfma_f32_16x16x32_bf16 v[114:117], v[172:175], v[180:183], v[114:117]
	v_mfma_f32_16x16x32_bf16 v[102:105], v[164:167], v[188:191], v[102:105]
	v_mfma_f32_16x16x32_bf16 v[98:101], v[172:175], v[188:191], v[98:101]
	v_mfma_f32_16x16x32_bf16 v[86:89], v[164:167], v[196:199], v[86:89]
	v_mfma_f32_16x16x32_bf16 v[82:85], v[172:175], v[196:199], v[82:85]
	v_mfma_f32_16x16x32_bf16 v[70:73], v[164:167], v[204:207], v[70:73]
	v_mfma_f32_16x16x32_bf16 v[66:69], v[172:175], v[204:207], v[66:69]
	v_mfma_f32_16x16x32_bf16 v[118:121], v[168:171], v[184:187], v[118:121]
	v_mfma_f32_16x16x32_bf16 v[114:117], v[176:179], v[184:187], v[114:117]
	v_mfma_f32_16x16x32_bf16 v[102:105], v[168:171], v[192:195], v[102:105]
	v_mfma_f32_16x16x32_bf16 v[98:101], v[176:179], v[192:195], v[98:101]
	v_mfma_f32_16x16x32_bf16 v[86:89], v[168:171], v[200:203], v[86:89]
	v_mfma_f32_16x16x32_bf16 v[82:85], v[176:179], v[200:203], v[82:85]
	v_mfma_f32_16x16x32_bf16 v[70:73], v[168:171], v[208:211], v[70:73]
	v_mfma_f32_16x16x32_bf16 v[66:69], v[176:179], v[208:211], v[66:69]
	s_barrier
; #define PG8_STAGE(bufoff, gbase, voff) do { _Pragma("unroll") for (int _i = 0; _i < 2; ++_i) \
;         __builtin_amdgcn_global_load_lds((const unsigned*)((const char*)(gbase) + (voff)[_i]), (PG8_LAS unsigned*)(lds + (bufoff) + ldsw + _i * 8192), 16, 0, 0); } while (0)
; #define PG8_LDA(dst, b, h) do { _Pragma("unroll") for (int m = 0; m < 4; ++m) _Pragma("unroll") for (int k = 0; k < 2; ++k) dst[m][k] = *(const PG8_LAS bf16x8*)(lds + PG8_SA(b, h) + aoff + m * 2048 + k * 1024); } while (0)
; #define PG8_LDB(dst, b, h) do { _Pragma("unroll") for (int n = 0; n < 2; ++n) _Pragma("unroll") for (int k = 0; k < 2; ++k) dst[n][k] = *(const PG8_LAS bf16x8*)(lds + PG8_SB(b, h) + boff + n * 2048 + k * 1024); } while (0)
; #define PG8_MMA(ai, bj, At, Bt) do { __builtin_amdgcn_s_setprio(1); _Pragma("unroll") for (int m = 0; m < 4; ++m) _Pragma("unroll") for (int n = 0; n < 2; ++n) _Pragma("unroll") for (int k = 0; k < 2; ++k) \
;         acc[ai][bj][m][n] = __builtin_amdgcn_mfma_f32_16x16x32_bf16(Bt[n][k], At[m][k], acc[ai][bj][m][n], 0, 0, 0); __builtin_amdgcn_s_setprio(0); } while (0)
; #define PG8_WAIT_V(n) asm volatile("s_waitcnt vmcnt(" #n ")" ::: "memory")
; #define PG8_WAIT_L(n) asm volatile("s_waitcnt lgkmcnt(" #n ")" ::: "memory")
; #define PG8_BAR __builtin_amdgcn_s_barrier()
; #define PG8_SCHED __builtin_amdgcn_sched_barrier(0)
; template <class Epi, class Sched, bool ALIGN_EPI = false, bool SP2 = false>
; __device__ __forceinline__ void gemm_phase(PG8_LAS unsigned char* lds, const Gemm g, const Sched& S, const Epi& E) {
;     ...
;             PG8_LDA(At, 0, 1); PG8_STAGE(PG8_SB(0, 0), b2, voffB); PG8_STAGE(PG8_SB(0, 1), b2 + hstep, voffB); PG8_STAGE(PG8_SA(0, 0), a2, voffA);
;             PG8_WAIT_V(8); PG8_WAIT_L(0); PG8_BAR; PG8_MMA(1, 0, At, B0); PG8_MMA(1, 1, At, B1); PG8_BAR; PG8_SCHED;
;             PG8_LDB(B0, 1, 0); PG8_LDB(B1, 1, 1); PG8_SCHED; PG8_LDA(At, 1, 0); PG8_STAGE(PG8_SA(0, 1), a2 + hstep, voffA);
;             PG8_WAIT_V(8); PG8_WAIT_L(0); PG8_BAR; PG8_MMA(0, 0, At, B0); PG8_MMA(0, 1, At, B1); PG8_BAR; PG8_SCHED;
	s_setprio 0
	s_add_i32 s60, s60, s4
	s_add_u32 s100, s10, 0x80
	s_addc_u32 s101, s11, 0
	s_mov_b32 m0, s60
	ds_read_b128 v[180:183], v151 offset:16384
	ds_read_b128 v[184:187], v151 offset:17408
	ds_read_b128 v[188:191], v151 offset:18432
	ds_read_b128 v[192:195], v151 offset:19456
	ds_read_b128 v[196:199], v151 offset:20480
	ds_read_b128 v[200:203], v151 offset:21504
	ds_read_b128 v[204:207], v151 offset:22528
	ds_read_b128 v[208:211], v151 offset:23552
	global_load_lds_dwordx4 v0, s[10:11]
	s_add_i32 m0, s60, 0x2000
	s_add_u32 s60, s10, 0x80000
	s_addc_u32 s61, s11, 0
	s_add_i32 s62, s62, s4
	global_load_lds_dwordx4 v134, s[10:11]
	s_mov_b32 m0, s62
	s_add_u32 s98, s52, 0x80
	s_addc_u32 s99, s53, 0
	global_load_lds_dwordx4 v0, s[60:61]
	s_add_i32 m0, s62, 0x2000
	s_nop 0
	global_load_lds_dwordx4 v134, s[60:61]
	s_mov_b32 m0, s5
	s_nop 0
	global_load_lds_dwordx4 v130, s[52:53]
	s_mov_b32 m0, s6
	s_nop 0
	global_load_lds_dwordx4 v132, s[52:53]
	s_waitcnt vmcnt(8) lgkmcnt(0)
	s_setprio 1
	s_barrier
	v_mfma_f32_16x16x32_bf16 v[62:65], v[140:143], v[180:183], v[62:65]
	v_mfma_f32_16x16x32_bf16 v[58:61], v[156:159], v[180:183], v[58:61]
	v_mfma_f32_16x16x32_bf16 v[46:49], v[140:143], v[188:191], v[46:49]
	v_mfma_f32_16x16x32_bf16 v[42:45], v[156:159], v[188:191], v[42:45]
	v_mfma_f32_16x16x32_bf16 v[30:33], v[140:143], v[196:199], v[30:33]
	v_mfma_f32_16x16x32_bf16 v[26:29], v[156:159], v[196:199], v[26:29]
	v_mfma_f32_16x16x32_bf16 v[14:17], v[140:143], v[204:207], v[14:17]
	v_mfma_f32_16x16x32_bf16 v[10:13], v[156:159], v[204:207], v[10:13]
	v_mfma_f32_16x16x32_bf16 v[62:65], v[152:155], v[184:187], v[62:65]
	v_mfma_f32_16x16x32_bf16 v[58:61], v[160:163], v[184:187], v[58:61]
	v_mfma_f32_16x16x32_bf16 v[46:49], v[152:155], v[192:195], v[46:49]
	v_mfma_f32_16x16x32_bf16 v[42:45], v[160:163], v[192:195], v[42:45]
	v_mfma_f32_16x16x32_bf16 v[30:33], v[152:155], v[200:203], v[30:33]
	v_mfma_f32_16x16x32_bf16 v[26:29], v[160:163], v[200:203], v[26:29]
	v_mfma_f32_16x16x32_bf16 v[14:17], v[152:155], v[208:211], v[14:17]
	v_mfma_f32_16x16x32_bf16 v[10:13], v[160:163], v[208:211], v[10:13]
	v_mfma_f32_16x16x32_bf16 v[54:57], v[164:167], v[180:183], v[54:57]
	v_mfma_f32_16x16x32_bf16 v[50:53], v[172:175], v[180:183], v[50:53]
	v_mfma_f32_16x16x32_bf16 v[38:41], v[164:167], v[188:191], v[38:41]
	v_mfma_f32_16x16x32_bf16 v[34:37], v[172:175], v[188:191], v[34:37]
	v_mfma_f32_16x16x32_bf16 v[22:25], v[164:167], v[196:199], v[22:25]
	v_mfma_f32_16x16x32_bf16 v[18:21], v[172:175], v[196:199], v[18:21]
	v_mfma_f32_16x16x32_bf16 v[6:9], v[164:167], v[204:207], v[6:9]
	v_mfma_f32_16x16x32_bf16 v[2:5], v[172:175], v[204:207], v[2:5]
	v_mfma_f32_16x16x32_bf16 v[54:57], v[168:171], v[184:187], v[54:57]
	v_mfma_f32_16x16x32_bf16 v[50:53], v[176:179], v[184:187], v[50:53]
	v_mfma_f32_16x16x32_bf16 v[38:41], v[168:171], v[192:195], v[38:41]
	v_mfma_f32_16x16x32_bf16 v[34:37], v[176:179], v[192:195], v[34:37]
	v_mfma_f32_16x16x32_bf16 v[22:25], v[168:171], v[200:203], v[22:25]
	v_mfma_f32_16x16x32_bf16 v[18:21], v[176:179], v[200:203], v[18:21]
	v_mfma_f32_16x16x32_bf16 v[6:9], v[168:171], v[208:211], v[6:9]
	v_mfma_f32_16x16x32_bf16 v[2:5], v[176:179], v[208:211], v[2:5]
	s_barrier
	s_setprio 0
	s_add_i32 s60, 0, 0x18000
	s_add_i32 s61, 0, 0x1c000
	ds_read_b128 v[140:143], v248 offset:32768
	ds_read_b128 v[152:155], v248 offset:33792
	ds_read_b128 v[156:159], v248 offset:34816
	ds_read_b128 v[160:163], v248 offset:35840
	ds_read_b128 v[164:167], v248 offset:49152
	ds_read_b128 v[168:171], v248 offset:50176
	ds_read_b128 v[172:175], v248 offset:51200
	ds_read_b128 v[176:179], v248 offset:52224
	s_add_u32 s52, s52, 0x80000
	s_addc_u32 s53, s53, 0
	s_mov_b32 m0, s7
	ds_read_b128 v[180:183], v151 offset:32768
	ds_read_b128 v[184:187], v151 offset:33792
	ds_read_b128 v[188:191], v151 offset:34816
	ds_read_b128 v[192:195], v151 offset:35840
	ds_read_b128 v[196:199], v151 offset:36864
	ds_read_b128 v[200:203], v151 offset:37888
	ds_read_b128 v[204:207], v151 offset:38912
	ds_read_b128 v[208:211], v151 offset:39936
	global_load_lds_dwordx4 v130, s[52:53]
	s_mov_b32 m0, s17
	s_nop 0
	global_load_lds_dwordx4 v132, s[52:53]
	s_waitcnt vmcnt(8) lgkmcnt(0)
	s_setprio 1
	s_barrier
; #define PG8_STAGE(bufoff, gbase, voff) do { _Pragma("unroll") for (int _i = 0; _i < 2; ++_i) \
;         __builtin_amdgcn_global_load_lds((const unsigned*)((const char*)(gbase) + (voff)[_i]), (PG8_LAS unsigned*)(lds + (bufoff) + ldsw + _i * 8192), 16, 0, 0); } while (0)
; #define PG8_LDA(dst, b, h) do { _Pragma("unroll") for (int m = 0; m < 4; ++m) _Pragma("unroll") for (int k = 0; k < 2; ++k) dst[m][k] = *(const PG8_LAS bf16x8*)(lds + PG8_SA(b, h) + aoff + m * 2048 + k * 1024); } while (0)
; #define PG8_MMA(ai, bj, At, Bt) do { __builtin_amdgcn_s_setprio(1); _Pragma("unroll") for (int m = 0; m < 4; ++m) _Pragma("unroll") for (int n = 0; n < 2; ++n) _Pragma("unroll") for (int k = 0; k < 2; ++k) \
;         acc[ai][bj][m][n] = __builtin_amdgcn_mfma_f32_16x16x32_bf16(Bt[n][k], At[m][k], acc[ai][bj][m][n], 0, 0, 0); __builtin_amdgcn_s_setprio(0); } while (0)
; #define PG8_WAIT_V(n) asm volatile("s_waitcnt vmcnt(" #n ")" ::: "memory")
; #define PG8_WAIT_L(n) asm volatile("s_waitcnt lgkmcnt(" #n ")" ::: "memory")
; #define PG8_BAR __builtin_amdgcn_s_barrier()
; #define PG8_SCHED __builtin_amdgcn_sched_barrier(0)
; template <class Epi, class Sched, bool ALIGN_EPI = false, bool SP2 = false>
; __device__ __forceinline__ void gemm_phase(PG8_LAS unsigned char* lds, const Gemm g, const Sched& S, const Epi& E) {
;     ...
;             PG8_WAIT_V(8); PG8_WAIT_L(0); PG8_BAR; PG8_MMA(0, 0, At, B0); PG8_MMA(0, 1, At, B1); PG8_BAR; PG8_SCHED;
;             PG8_LDA(At, 1, 1); PG8_STAGE(PG8_SB(1, 0), b3, voffB); PG8_STAGE(PG8_SB(1, 1), b3 + hstep, voffB); PG8_STAGE(PG8_SA(1, 0), a3, voffA);
;             PG8_WAIT_V(8); PG8_WAIT_L(0); PG8_BAR; PG8_MMA(1, 0, At, B0); PG8_MMA(1, 1, At, B1); PG8_BAR; PG8_SCHED;
;     ...
;         if constexpr (ALIGN_EPI) { if (wr == 0) PG8_BAR; }
	v_mfma_f32_16x16x32_bf16 v[126:129], v[140:143], v[180:183], v[126:129]
	v_mfma_f32_16x16x32_bf16 v[122:125], v[156:159], v[180:183], v[122:125]
	v_mfma_f32_16x16x32_bf16 v[110:113], v[140:143], v[188:191], v[110:113]
	v_mfma_f32_16x16x32_bf16 v[106:109], v[156:159], v[188:191], v[106:109]
	v_mfma_f32_16x16x32_bf16 v[94:97], v[140:143], v[196:199], v[94:97]
	v_mfma_f32_16x16x32_bf16 v[90:93], v[156:159], v[196:199], v[90:93]
	v_mfma_f32_16x16x32_bf16 v[78:81], v[140:143], v[204:207], v[78:81]
	v_mfma_f32_16x16x32_bf16 v[74:77], v[156:159], v[204:207], v[74:77]
	v_mfma_f32_16x16x32_bf16 v[126:129], v[152:155], v[184:187], v[126:129]
	v_mfma_f32_16x16x32_bf16 v[122:125], v[160:163], v[184:187], v[122:125]
	v_mfma_f32_16x16x32_bf16 v[110:113], v[152:155], v[192:195], v[110:113]
	v_mfma_f32_16x16x32_bf16 v[106:109], v[160:163], v[192:195], v[106:109]
	v_mfma_f32_16x16x32_bf16 v[94:97], v[152:155], v[200:203], v[94:97]
	v_mfma_f32_16x16x32_bf16 v[90:93], v[160:163], v[200:203], v[90:93]
	v_mfma_f32_16x16x32_bf16 v[78:81], v[152:155], v[208:211], v[78:81]
	v_mfma_f32_16x16x32_bf16 v[74:77], v[160:163], v[208:211], v[74:77]
	v_mfma_f32_16x16x32_bf16 v[118:121], v[164:167], v[180:183], v[118:121]
	v_mfma_f32_16x16x32_bf16 v[114:117], v[172:175], v[180:183], v[114:117]
	v_mfma_f32_16x16x32_bf16 v[102:105], v[164:167], v[188:191], v[102:105]
	v_mfma_f32_16x16x32_bf16 v[98:101], v[172:175], v[188:191], v[98:101]
	v_mfma_f32_16x16x32_bf16 v[86:89], v[164:167], v[196:199], v[86:89]
	v_mfma_f32_16x16x32_bf16 v[82:85], v[172:175], v[196:199], v[82:85]
	v_mfma_f32_16x16x32_bf16 v[70:73], v[164:167], v[204:207], v[70:73]
	v_mfma_f32_16x16x32_bf16 v[66:69], v[172:175], v[204:207], v[66:69]
	v_mfma_f32_16x16x32_bf16 v[118:121], v[168:171], v[184:187], v[118:121]
	v_mfma_f32_16x16x32_bf16 v[114:117], v[176:179], v[184:187], v[114:117]
	v_mfma_f32_16x16x32_bf16 v[102:105], v[168:171], v[192:195], v[102:105]
	v_mfma_f32_16x16x32_bf16 v[98:101], v[176:179], v[192:195], v[98:101]
	v_mfma_f32_16x16x32_bf16 v[86:89], v[168:171], v[200:203], v[86:89]
	v_mfma_f32_16x16x32_bf16 v[82:85], v[176:179], v[200:203], v[82:85]
	v_mfma_f32_16x16x32_bf16 v[70:73], v[168:171], v[208:211], v[70:73]
	v_mfma_f32_16x16x32_bf16 v[66:69], v[176:179], v[208:211], v[66:69]
	s_barrier
	s_setprio 0
	s_add_i32 s52, s60, s4
	s_mov_b32 m0, s52
	ds_read_b128 v[180:183], v151 offset:49152
	ds_read_b128 v[184:187], v151 offset:50176
	ds_read_b128 v[188:191], v151 offset:51200
	ds_read_b128 v[192:195], v151 offset:52224
	ds_read_b128 v[196:199], v151 offset:53248
	ds_read_b128 v[200:203], v151 offset:54272
	ds_read_b128 v[204:207], v151 offset:55296
	ds_read_b128 v[208:211], v151 offset:56320
	global_load_lds_dwordx4 v0, s[100:101]
	s_add_i32 m0, s52, 0x2000
	s_add_i32 s52, s61, s4
	global_load_lds_dwordx4 v134, s[100:101]
	s_add_u32 s10, s10, 0x80080
	s_addc_u32 s11, s11, 0
	s_mov_b32 m0, s52
	s_nop 0
	global_load_lds_dwordx4 v0, s[10:11]
	s_add_i32 m0, s52, 0x2000
	s_nop 0
	global_load_lds_dwordx4 v134, s[10:11]
	s_mov_b32 m0, s30
	s_nop 0
	global_load_lds_dwordx4 v130, s[98:99]
	s_mov_b32 m0, s47
	s_nop 0
	global_load_lds_dwordx4 v132, s[98:99]
	s_waitcnt vmcnt(8) lgkmcnt(0)
	s_setprio 1
	s_barrier
	v_mfma_f32_16x16x32_bf16 v[62:65], v[140:143], v[180:183], v[62:65]
	v_mfma_f32_16x16x32_bf16 v[58:61], v[156:159], v[180:183], v[58:61]
	v_mfma_f32_16x16x32_bf16 v[46:49], v[140:143], v[188:191], v[46:49]
	v_mfma_f32_16x16x32_bf16 v[42:45], v[156:159], v[188:191], v[42:45]
	v_mfma_f32_16x16x32_bf16 v[30:33], v[140:143], v[196:199], v[30:33]
	v_mfma_f32_16x16x32_bf16 v[26:29], v[156:159], v[196:199], v[26:29]
	v_mfma_f32_16x16x32_bf16 v[14:17], v[140:143], v[204:207], v[14:17]
	v_mfma_f32_16x16x32_bf16 v[10:13], v[156:159], v[204:207], v[10:13]
	v_mfma_f32_16x16x32_bf16 v[62:65], v[152:155], v[184:187], v[62:65]
	v_mfma_f32_16x16x32_bf16 v[58:61], v[160:163], v[184:187], v[58:61]
	v_mfma_f32_16x16x32_bf16 v[46:49], v[152:155], v[192:195], v[46:49]
	v_mfma_f32_16x16x32_bf16 v[42:45], v[160:163], v[192:195], v[42:45]
	v_mfma_f32_16x16x32_bf16 v[30:33], v[152:155], v[200:203], v[30:33]
	v_mfma_f32_16x16x32_bf16 v[26:29], v[160:163], v[200:203], v[26:29]
	v_mfma_f32_16x16x32_bf16 v[14:17], v[152:155], v[208:211], v[14:17]
	v_mfma_f32_16x16x32_bf16 v[10:13], v[160:163], v[208:211], v[10:13]
	v_mfma_f32_16x16x32_bf16 v[54:57], v[164:167], v[180:183], v[54:57]
	v_mfma_f32_16x16x32_bf16 v[50:53], v[172:175], v[180:183], v[50:53]
	v_mfma_f32_16x16x32_bf16 v[38:41], v[164:167], v[188:191], v[38:41]
	v_mfma_f32_16x16x32_bf16 v[34:37], v[172:175], v[188:191], v[34:37]
	v_mfma_f32_16x16x32_bf16 v[22:25], v[164:167], v[196:199], v[22:25]
	v_mfma_f32_16x16x32_bf16 v[18:21], v[172:175], v[196:199], v[18:21]
	v_mfma_f32_16x16x32_bf16 v[6:9], v[164:167], v[204:207], v[6:9]
	v_mfma_f32_16x16x32_bf16 v[2:5], v[172:175], v[204:207], v[2:5]
	v_mfma_f32_16x16x32_bf16 v[54:57], v[168:171], v[184:187], v[54:57]
	v_mfma_f32_16x16x32_bf16 v[50:53], v[176:179], v[184:187], v[50:53]
	v_mfma_f32_16x16x32_bf16 v[38:41], v[168:171], v[192:195], v[38:41]
	v_mfma_f32_16x16x32_bf16 v[34:37], v[176:179], v[192:195], v[34:37]
	v_mfma_f32_16x16x32_bf16 v[22:25], v[168:171], v[200:203], v[22:25]
	v_mfma_f32_16x16x32_bf16 v[18:21], v[176:179], v[200:203], v[18:21]
	v_mfma_f32_16x16x32_bf16 v[6:9], v[168:171], v[208:211], v[6:9]
	v_mfma_f32_16x16x32_bf16 v[2:5], v[176:179], v[208:211], v[2:5]
	s_barrier
	s_setprio 0
	s_add_i32 s59, s59, 2
	s_add_u32 s50, s50, 0x100
	s_addc_u32 s51, s51, 0
	s_add_u32 s57, s57, 0x100
	s_addc_u32 s58, s58, 0
	s_cmp_gt_u32 s59, 29
	s_cbranch_scc0 .LBB0_559
	s_and_b64 vcc, exec, s[14:15]
	s_cbranch_vccz .LBB0_562
	s_barrier

; #define PG8_STAGE(bufoff, gbase, voff) do { _Pragma("unroll") for (int _i = 0; _i < 2; ++_i) \
;         __builtin_amdgcn_global_load_lds((const unsigned*)((const char*)(gbase) + (voff)[_i]), (PG8_LAS unsigned*)(lds + (bufoff) + ldsw + _i * 8192), 16, 0, 0); } while (0)
; #define PG8_LDA(dst, b, h) do { _Pragma("unroll") for (int m = 0; m < 4; ++m) _Pragma("unroll") for (int k = 0; k < 2; ++k) dst[m][k] = *(const PG8_LAS bf16x8*)(lds + PG8_SA(b, h) + aoff + m * 2048 + k * 1024); } while (0)
; #define PG8_LDB(dst, b, h) do { _Pragma("unroll") for (int n = 0; n < 2; ++n) _Pragma("unroll") for (int k = 0; k < 2; ++k) dst[n][k] = *(const PG8_LAS bf16x8*)(lds + PG8_SB(b, h) + boff + n * 2048 + k * 1024); } while (0)
; #define PG8_WAIT_V(n) asm volatile("s_waitcnt vmcnt(" #n ")" ::: "memory")
; #define PG8_WAIT_L(n) asm volatile("s_waitcnt lgkmcnt(" #n ")" ::: "memory")
; #define PG8_BAR __builtin_amdgcn_s_barrier()
; #define PG8_SCHED __builtin_amdgcn_sched_barrier(0)
; template <class Epi, class Sched, bool ALIGN_EPI = false, bool SP2 = false>
; __device__ __forceinline__ void gemm_phase(PG8_LAS unsigned char* lds, const Gemm g, const Sched& S, const Epi& E) {
;     ...
;         const char* nA = has_next ? (const char*)g.A + (size_t)nxt.pm * tstep : cA; const char* nB = has_next ? (const char*)g.Bt + (size_t)nxt.pn * tstep : cB;
;         for (int t = 0; t < nt; t += 2) {
;             const bool last = (t == nt - 2);
;             const char* a1 = cA + (size_t)(t + 1) * kstep;
;             const char* a2 = last ? nA : cA + (size_t)(t + 2) * kstep; const char* b2 = last ? nB : cB + (size_t)(t + 2) * kstep;
;             const char* a3 = a2 + kstep; const char* b3 = b2 + kstep;
;             if (last && has_next) S.a_ready(nxt);
;             if constexpr (SP2) {
;             PG8_LDB(B0, 0, 0); PG8_LDB(B1, 0, 1); PG8_SCHED; PG8_LDA(At, 0, 0); PG8_STAGE(PG8_SA(1, 1), a1 + hstep, voffA);
;             PG8_WAIT_V(8); PG8_WAIT_L(0); PG8_BAR; PG8_MMA(0, 0, At, B0); PG8_MMA(0, 1, At, B1); PG8_BAR; PG8_SCHED;
;             PG8_LDA(At, 0, 1); PG8_STAGE(PG8_SB(0, 0), b2, voffB); PG8_STAGE(PG8_SB(0, 1), b2 + hstep, voffB); PG8_STAGE(PG8_SA(0, 0), a2, voffA);
;             PG8_WAIT_V(8); PG8_WAIT_L(0); PG8_BAR; PG8_MMA(1, 0, At, B0); PG8_MMA(1, 1, At, B1); PG8_BAR; PG8_SCHED;
.LBB0_599:
	s_add_u32 s10, s36, 0xfff80080
	s_addc_u32 s11, s37, -1
	s_add_i32 s55, 0, 0x10000
	s_cmp_eq_u32 s54, 28
	s_cselect_b32 s41, s19, s11
	s_cselect_b32 s40, s50, s10
	v_add_u32_e32 v140, s55, v143
	s_cselect_b32 s11, s17, s53
	s_cselect_b32 s10, s51, s52
	s_add_i32 s58, 0, 0x14000
	ds_read_b128 v[146:149], v140
	ds_read_b128 v[150:153], v140 offset:1024
	ds_read_b128 v[154:157], v140 offset:2048
	ds_read_b128 v[158:161], v140 offset:3072
	v_add_u32_e32 v140, s58, v143
	ds_read_b128 v[162:165], v140
	ds_read_b128 v[166:169], v140 offset:1024
	ds_read_b128 v[170:173], v140 offset:2048
	ds_read_b128 v[174:177], v140 offset:3072
	s_add_i32 m0, s7, 0xc000
	ds_read_b128 v[178:181], v145
	ds_read_b128 v[182:185], v145 offset:1024
	ds_read_b128 v[186:189], v145 offset:2048
	ds_read_b128 v[190:193], v145 offset:3072
	ds_read_b128 v[194:197], v145 offset:4096
	ds_read_b128 v[198:201], v145 offset:5120
	ds_read_b128 v[202:205], v145 offset:6144
	ds_read_b128 v[206:209], v145 offset:7168
	global_load_lds_dwordx4 v136, s[36:37]
	s_add_i32 m0, s7, 0xe000
	s_nop 0
	global_load_lds_dwordx4 v138, s[36:37]
	s_waitcnt vmcnt(8) lgkmcnt(0)
	s_setprio 1
	s_barrier
	v_mfma_f32_16x16x32_bf16 v[126:129], v[146:149], v[178:181], v[126:129]
	v_mfma_f32_16x16x32_bf16 v[122:125], v[154:157], v[178:181], v[122:125]
	v_mfma_f32_16x16x32_bf16 v[118:121], v[146:149], v[186:189], v[118:121]
	v_mfma_f32_16x16x32_bf16 v[110:113], v[154:157], v[186:189], v[110:113]
	v_mfma_f32_16x16x32_bf16 v[102:105], v[146:149], v[194:197], v[102:105]
	v_mfma_f32_16x16x32_bf16 v[94:97], v[154:157], v[194:197], v[94:97]
	v_mfma_f32_16x16x32_bf16 v[86:89], v[146:149], v[202:205], v[86:89]
	v_mfma_f32_16x16x32_bf16 v[78:81], v[154:157], v[202:205], v[78:81]
	v_mfma_f32_16x16x32_bf16 v[126:129], v[150:153], v[182:185], v[126:129]
	v_mfma_f32_16x16x32_bf16 v[122:125], v[158:161], v[182:185], v[122:125]
	v_mfma_f32_16x16x32_bf16 v[118:121], v[150:153], v[190:193], v[118:121]
	v_mfma_f32_16x16x32_bf16 v[110:113], v[158:161], v[190:193], v[110:113]
	v_mfma_f32_16x16x32_bf16 v[102:105], v[150:153], v[198:201], v[102:105]
	v_mfma_f32_16x16x32_bf16 v[94:97], v[158:161], v[198:201], v[94:97]
	v_mfma_f32_16x16x32_bf16 v[86:89], v[150:153], v[206:209], v[86:89]
	v_mfma_f32_16x16x32_bf16 v[78:81], v[158:161], v[206:209], v[78:81]
	v_mfma_f32_16x16x32_bf16 v[114:117], v[162:165], v[178:181], v[114:117]
	v_mfma_f32_16x16x32_bf16 v[106:109], v[170:173], v[178:181], v[106:109]
	v_mfma_f32_16x16x32_bf16 v[98:101], v[162:165], v[186:189], v[98:101]
	v_mfma_f32_16x16x32_bf16 v[90:93], v[170:173], v[186:189], v[90:93]
	v_mfma_f32_16x16x32_bf16 v[82:85], v[162:165], v[194:197], v[82:85]
	v_mfma_f32_16x16x32_bf16 v[74:77], v[170:173], v[194:197], v[74:77]
	v_mfma_f32_16x16x32_bf16 v[70:73], v[162:165], v[202:205], v[70:73]
	v_mfma_f32_16x16x32_bf16 v[66:69], v[170:173], v[202:205], v[66:69]
	v_mfma_f32_16x16x32_bf16 v[114:117], v[166:169], v[182:185], v[114:117]
	v_mfma_f32_16x16x32_bf16 v[106:109], v[174:177], v[182:185], v[106:109]
	v_mfma_f32_16x16x32_bf16 v[98:101], v[166:169], v[190:193], v[98:101]
	v_mfma_f32_16x16x32_bf16 v[90:93], v[174:177], v[190:193], v[90:93]
	v_mfma_f32_16x16x32_bf16 v[82:85], v[166:169], v[198:201], v[82:85]
	v_mfma_f32_16x16x32_bf16 v[74:77], v[174:177], v[198:201], v[74:77]
	v_mfma_f32_16x16x32_bf16 v[70:73], v[166:169], v[206:209], v[70:73]
	v_mfma_f32_16x16x32_bf16 v[66:69], v[174:177], v[206:209], v[66:69]
	s_barrier
	s_setprio 0
	s_add_i32 s55, s55, s4
	s_add_u32 s100, s10, 0x80
	s_addc_u32 s101, s11, 0
	s_mov_b32 m0, s55
	ds_read_b128 v[178:181], v145 offset:16384
	ds_read_b128 v[182:185], v145 offset:17408
	ds_read_b128 v[186:189], v145 offset:18432
	ds_read_b128 v[190:193], v145 offset:19456
	ds_read_b128 v[194:197], v145 offset:20480
	ds_read_b128 v[198:201], v145 offset:21504
	ds_read_b128 v[202:205], v145 offset:22528
	ds_read_b128 v[206:209], v145 offset:23552
	global_load_lds_dwordx4 v0, s[10:11]
	s_add_i32 m0, s55, 0x2000
	s_add_u32 s56, s10, 0x80000
	s_addc_u32 s57, s11, 0
	s_add_i32 s55, s58, s4
	global_load_lds_dwordx4 v134, s[10:11]
	s_mov_b32 m0, s55
	s_add_u32 s98, s40, 0x80
	s_addc_u32 s99, s41, 0
	global_load_lds_dwordx4 v0, s[56:57]
	s_add_i32 m0, s55, 0x2000
	s_nop 0
	global_load_lds_dwordx4 v134, s[56:57]
	s_mov_b32 m0, s7
	s_nop 0
	global_load_lds_dwordx4 v130, s[40:41]
	s_mov_b32 m0, s21
	s_nop 0
	global_load_lds_dwordx4 v132, s[40:41]
	s_waitcnt vmcnt(8) lgkmcnt(0)
	s_setprio 1
	s_barrier
	v_mfma_f32_16x16x32_bf16 v[62:65], v[146:149], v[178:181], v[62:65]
	v_mfma_f32_16x16x32_bf16 v[58:61], v[154:157], v[178:181], v[58:61]
	v_mfma_f32_16x16x32_bf16 v[54:57], v[146:149], v[186:189], v[54:57]
	v_mfma_f32_16x16x32_bf16 v[46:49], v[154:157], v[186:189], v[46:49]
	v_mfma_f32_16x16x32_bf16 v[38:41], v[146:149], v[194:197], v[38:41]
	v_mfma_f32_16x16x32_bf16 v[30:33], v[154:157], v[194:197], v[30:33]
	v_mfma_f32_16x16x32_bf16 v[22:25], v[146:149], v[202:205], v[22:25]
	v_mfma_f32_16x16x32_bf16 v[14:17], v[154:157], v[202:205], v[14:17]
	v_mfma_f32_16x16x32_bf16 v[62:65], v[150:153], v[182:185], v[62:65]
	v_mfma_f32_16x16x32_bf16 v[58:61], v[158:161], v[182:185], v[58:61]
	v_mfma_f32_16x16x32_bf16 v[54:57], v[150:153], v[190:193], v[54:57]
	v_mfma_f32_16x16x32_bf16 v[46:49], v[158:161], v[190:193], v[46:49]
	v_mfma_f32_16x16x32_bf16 v[38:41], v[150:153], v[198:201], v[38:41]
	v_mfma_f32_16x16x32_bf16 v[30:33], v[158:161], v[198:201], v[30:33]
	v_mfma_f32_16x16x32_bf16 v[22:25], v[150:153], v[206:209], v[22:25]
	v_mfma_f32_16x16x32_bf16 v[14:17], v[158:161], v[206:209], v[14:17]
	v_mfma_f32_16x16x32_bf16 v[50:53], v[162:165], v[178:181], v[50:53]
	v_mfma_f32_16x16x32_bf16 v[42:45], v[170:173], v[178:181], v[42:45]
	v_mfma_f32_16x16x32_bf16 v[34:37], v[162:165], v[186:189], v[34:37]
	v_mfma_f32_16x16x32_bf16 v[26:29], v[170:173], v[186:189], v[26:29]
	v_mfma_f32_16x16x32_bf16 v[18:21], v[162:165], v[194:197], v[18:21]
	v_mfma_f32_16x16x32_bf16 v[10:13], v[170:173], v[194:197], v[10:13]
	v_mfma_f32_16x16x32_bf16 v[6:9], v[162:165], v[202:205], v[6:9]
	v_mfma_f32_16x16x32_bf16 v[2:5], v[170:173], v[202:205], v[2:5]
	v_mfma_f32_16x16x32_bf16 v[50:53], v[166:169], v[182:185], v[50:53]
	v_mfma_f32_16x16x32_bf16 v[42:45], v[174:177], v[182:185], v[42:45]
	v_mfma_f32_16x16x32_bf16 v[34:37], v[166:169], v[190:193], v[34:37]
	v_mfma_f32_16x16x32_bf16 v[26:29], v[174:177], v[190:193], v[26:29]
	v_mfma_f32_16x16x32_bf16 v[18:21], v[166:169], v[198:201], v[18:21]
	v_mfma_f32_16x16x32_bf16 v[10:13], v[174:177], v[198:201], v[10:13]
	v_mfma_f32_16x16x32_bf16 v[6:9], v[166:169], v[206:209], v[6:9]
	v_mfma_f32_16x16x32_bf16 v[2:5], v[174:177], v[206:209], v[2:5]
	s_barrier
; #define PG8_STAGE(bufoff, gbase, voff) do { _Pragma("unroll") for (int _i = 0; _i < 2; ++_i) \
;         __builtin_amdgcn_global_load_lds((const unsigned*)((const char*)(gbase) + (voff)[_i]), (PG8_LAS unsigned*)(lds + (bufoff) + ldsw + _i * 8192), 16, 0, 0); } while (0)
; #define PG8_LDA(dst, b, h) do { _Pragma("unroll") for (int m = 0; m < 4; ++m) _Pragma("unroll") for (int k = 0; k < 2; ++k) dst[m][k] = *(const PG8_LAS bf16x8*)(lds + PG8_SA(b, h) + aoff + m * 2048 + k * 1024); } while (0)
; #define PG8_LDB(dst, b, h) do { _Pragma("unroll") for (int n = 0; n < 2; ++n) _Pragma("unroll") for (int k = 0; k < 2; ++k) dst[n][k] = *(const PG8_LAS bf16x8*)(lds + PG8_SB(b, h) + boff + n * 2048 + k * 1024); } while (0)
; #define PG8_MMA(ai, bj, At, Bt) do { __builtin_amdgcn_s_setprio(1); _Pragma("unroll") for (int m = 0; m < 4; ++m) _Pragma("unroll") for (int n = 0; n < 2; ++n) _Pragma("unroll") for (int k = 0; k < 2; ++k) \
;         acc[ai][bj][m][n] = __builtin_amdgcn_mfma_f32_16x16x32_bf16(Bt[n][k], At[m][k], acc[ai][bj][m][n], 0, 0, 0); __builtin_amdgcn_s_setprio(0); } while (0)
; #define PG8_WAIT_V(n) asm volatile("s_waitcnt vmcnt(" #n ")" ::: "memory")
; #define PG8_WAIT_L(n) asm volatile("s_waitcnt lgkmcnt(" #n ")" ::: "memory")
; #define PG8_BAR __builtin_amdgcn_s_barrier()
; #define PG8_SCHED __builtin_amdgcn_sched_barrier(0)
; template <class Epi, class Sched, bool ALIGN_EPI = false, bool SP2 = false>
; __device__ __forceinline__ void gemm_phase(PG8_LAS unsigned char* lds, const Gemm g, const Sched& S, const Epi& E) {
;     ...
;             PG8_LDB(B0, 1, 0); PG8_LDB(B1, 1, 1); PG8_SCHED; PG8_LDA(At, 1, 0); PG8_STAGE(PG8_SA(0, 1), a2 + hstep, voffA);
;             PG8_WAIT_V(8); PG8_WAIT_L(0); PG8_BAR; PG8_MMA(0, 0, At, B0); PG8_MMA(0, 1, At, B1); PG8_BAR; PG8_SCHED;
;             PG8_LDA(At, 1, 1); PG8_STAGE(PG8_SB(1, 0), b3, voffB); PG8_STAGE(PG8_SB(1, 1), b3 + hstep, voffB); PG8_STAGE(PG8_SA(1, 0), a3, voffA);
;             PG8_WAIT_V(8); PG8_WAIT_L(0); PG8_BAR; PG8_MMA(1, 0, At, B0); PG8_MMA(1, 1, At, B1); PG8_BAR; PG8_SCHED;
;     ...
;         if constexpr (ALIGN_EPI) { if (wr == 0) PG8_BAR; }
	s_setprio 0
	s_add_i32 s55, 0, 0x18000
	s_add_i32 s56, 0, 0x1c000
	v_add_u32_e32 v158, s55, v143
	v_add_u32_e32 v174, s56, v143
	ds_read_b128 v[146:149], v158
	ds_read_b128 v[150:153], v158 offset:1024
	ds_read_b128 v[154:157], v158 offset:2048
	ds_read_b128 v[158:161], v158 offset:3072
	ds_read_b128 v[162:165], v174
	ds_read_b128 v[166:169], v174 offset:1024
	ds_read_b128 v[170:173], v174 offset:2048
	ds_read_b128 v[174:177], v174 offset:3072
	s_add_u32 s40, s40, 0x80000
	s_addc_u32 s41, s41, 0
	s_mov_b32 m0, s30
	ds_read_b128 v[178:181], v145 offset:32768
	ds_read_b128 v[182:185], v145 offset:33792
	ds_read_b128 v[186:189], v145 offset:34816
	ds_read_b128 v[190:193], v145 offset:35840
	ds_read_b128 v[194:197], v145 offset:36864
	ds_read_b128 v[198:201], v145 offset:37888
	ds_read_b128 v[202:205], v145 offset:38912
	ds_read_b128 v[206:209], v145 offset:39936
	global_load_lds_dwordx4 v130, s[40:41]
	s_mov_b32 m0, s42
	s_nop 0
	global_load_lds_dwordx4 v132, s[40:41]
	s_waitcnt vmcnt(8) lgkmcnt(0)
	s_setprio 1
	s_barrier
	v_mfma_f32_16x16x32_bf16 v[126:129], v[146:149], v[178:181], v[126:129]
	v_mfma_f32_16x16x32_bf16 v[122:125], v[154:157], v[178:181], v[122:125]
	v_mfma_f32_16x16x32_bf16 v[118:121], v[146:149], v[186:189], v[118:121]
	v_mfma_f32_16x16x32_bf16 v[110:113], v[154:157], v[186:189], v[110:113]
	v_mfma_f32_16x16x32_bf16 v[102:105], v[146:149], v[194:197], v[102:105]
	v_mfma_f32_16x16x32_bf16 v[94:97], v[154:157], v[194:197], v[94:97]
	v_mfma_f32_16x16x32_bf16 v[86:89], v[146:149], v[202:205], v[86:89]
	v_mfma_f32_16x16x32_bf16 v[78:81], v[154:157], v[202:205], v[78:81]
	v_mfma_f32_16x16x32_bf16 v[126:129], v[150:153], v[182:185], v[126:129]
	v_mfma_f32_16x16x32_bf16 v[122:125], v[158:161], v[182:185], v[122:125]
	v_mfma_f32_16x16x32_bf16 v[118:121], v[150:153], v[190:193], v[118:121]
	v_mfma_f32_16x16x32_bf16 v[110:113], v[158:161], v[190:193], v[110:113]
	v_mfma_f32_16x16x32_bf16 v[102:105], v[150:153], v[198:201], v[102:105]
	v_mfma_f32_16x16x32_bf16 v[94:97], v[158:161], v[198:201], v[94:97]
	v_mfma_f32_16x16x32_bf16 v[86:89], v[150:153], v[206:209], v[86:89]
	v_mfma_f32_16x16x32_bf16 v[78:81], v[158:161], v[206:209], v[78:81]
	v_mfma_f32_16x16x32_bf16 v[114:117], v[162:165], v[178:181], v[114:117]
	v_mfma_f32_16x16x32_bf16 v[106:109], v[170:173], v[178:181], v[106:109]
	v_mfma_f32_16x16x32_bf16 v[98:101], v[162:165], v[186:189], v[98:101]
	v_mfma_f32_16x16x32_bf16 v[90:93], v[170:173], v[186:189], v[90:93]
	v_mfma_f32_16x16x32_bf16 v[82:85], v[162:165], v[194:197], v[82:85]
	v_mfma_f32_16x16x32_bf16 v[74:77], v[170:173], v[194:197], v[74:77]
	v_mfma_f32_16x16x32_bf16 v[70:73], v[162:165], v[202:205], v[70:73]
	v_mfma_f32_16x16x32_bf16 v[66:69], v[170:173], v[202:205], v[66:69]
	v_mfma_f32_16x16x32_bf16 v[114:117], v[166:169], v[182:185], v[114:117]
	v_mfma_f32_16x16x32_bf16 v[106:109], v[174:177], v[182:185], v[106:109]
	v_mfma_f32_16x16x32_bf16 v[98:101], v[166:169], v[190:193], v[98:101]
	v_mfma_f32_16x16x32_bf16 v[90:93], v[174:177], v[190:193], v[90:93]
	v_mfma_f32_16x16x32_bf16 v[82:85], v[166:169], v[198:201], v[82:85]
	v_mfma_f32_16x16x32_bf16 v[74:77], v[174:177], v[198:201], v[74:77]
	v_mfma_f32_16x16x32_bf16 v[70:73], v[166:169], v[206:209], v[70:73]
	v_mfma_f32_16x16x32_bf16 v[66:69], v[174:177], v[206:209], v[66:69]
	s_barrier
	s_setprio 0
	s_add_i32 s40, s55, s4
	s_mov_b32 m0, s40
	ds_read_b128 v[178:181], v145 offset:49152
	ds_read_b128 v[182:185], v145 offset:50176
	ds_read_b128 v[186:189], v145 offset:51200
	ds_read_b128 v[190:193], v145 offset:52224
	ds_read_b128 v[194:197], v145 offset:53248
	ds_read_b128 v[198:201], v145 offset:54272
	ds_read_b128 v[202:205], v145 offset:55296
	ds_read_b128 v[206:209], v145 offset:56320
	global_load_lds_dwordx4 v0, s[100:101]
	s_add_i32 m0, s40, 0x2000
	s_add_i32 s40, s56, s4
	global_load_lds_dwordx4 v134, s[100:101]
	s_add_u32 s10, s10, 0x80080
	s_addc_u32 s11, s11, 0
	s_mov_b32 m0, s40
	s_nop 0
	global_load_lds_dwordx4 v0, s[10:11]
	s_add_i32 m0, s40, 0x2000
	s_nop 0
	global_load_lds_dwordx4 v134, s[10:11]
	s_mov_b32 m0, s43
	s_nop 0
	global_load_lds_dwordx4 v130, s[98:99]
	s_mov_b32 m0, s44
	s_nop 0
	global_load_lds_dwordx4 v132, s[98:99]
	s_waitcnt vmcnt(8) lgkmcnt(0)
	s_setprio 1
	s_barrier
	v_mfma_f32_16x16x32_bf16 v[62:65], v[146:149], v[178:181], v[62:65]
	v_mfma_f32_16x16x32_bf16 v[58:61], v[154:157], v[178:181], v[58:61]
	v_mfma_f32_16x16x32_bf16 v[54:57], v[146:149], v[186:189], v[54:57]
	v_mfma_f32_16x16x32_bf16 v[46:49], v[154:157], v[186:189], v[46:49]
	v_mfma_f32_16x16x32_bf16 v[38:41], v[146:149], v[194:197], v[38:41]
	v_mfma_f32_16x16x32_bf16 v[30:33], v[154:157], v[194:197], v[30:33]
	v_mfma_f32_16x16x32_bf16 v[22:25], v[146:149], v[202:205], v[22:25]
	v_mfma_f32_16x16x32_bf16 v[14:17], v[154:157], v[202:205], v[14:17]
	v_mfma_f32_16x16x32_bf16 v[62:65], v[150:153], v[182:185], v[62:65]
	v_mfma_f32_16x16x32_bf16 v[58:61], v[158:161], v[182:185], v[58:61]
	v_mfma_f32_16x16x32_bf16 v[54:57], v[150:153], v[190:193], v[54:57]
	v_mfma_f32_16x16x32_bf16 v[46:49], v[158:161], v[190:193], v[46:49]
	v_mfma_f32_16x16x32_bf16 v[38:41], v[150:153], v[198:201], v[38:41]
	v_mfma_f32_16x16x32_bf16 v[30:33], v[158:161], v[198:201], v[30:33]
	v_mfma_f32_16x16x32_bf16 v[22:25], v[150:153], v[206:209], v[22:25]
	v_mfma_f32_16x16x32_bf16 v[14:17], v[158:161], v[206:209], v[14:17]
	v_mfma_f32_16x16x32_bf16 v[50:53], v[162:165], v[178:181], v[50:53]
	v_mfma_f32_16x16x32_bf16 v[42:45], v[170:173], v[178:181], v[42:45]
	v_mfma_f32_16x16x32_bf16 v[34:37], v[162:165], v[186:189], v[34:37]
	v_mfma_f32_16x16x32_bf16 v[26:29], v[170:173], v[186:189], v[26:29]
	v_mfma_f32_16x16x32_bf16 v[18:21], v[162:165], v[194:197], v[18:21]
	v_mfma_f32_16x16x32_bf16 v[10:13], v[170:173], v[194:197], v[10:13]
	v_mfma_f32_16x16x32_bf16 v[6:9], v[162:165], v[202:205], v[6:9]
	v_mfma_f32_16x16x32_bf16 v[2:5], v[170:173], v[202:205], v[2:5]
	v_mfma_f32_16x16x32_bf16 v[50:53], v[166:169], v[182:185], v[50:53]
	v_mfma_f32_16x16x32_bf16 v[42:45], v[174:177], v[182:185], v[42:45]
	v_mfma_f32_16x16x32_bf16 v[34:37], v[166:169], v[190:193], v[34:37]
	v_mfma_f32_16x16x32_bf16 v[26:29], v[174:177], v[190:193], v[26:29]
	v_mfma_f32_16x16x32_bf16 v[18:21], v[166:169], v[198:201], v[18:21]
	v_mfma_f32_16x16x32_bf16 v[10:13], v[174:177], v[198:201], v[10:13]
	v_mfma_f32_16x16x32_bf16 v[6:9], v[166:169], v[206:209], v[6:9]
	v_mfma_f32_16x16x32_bf16 v[2:5], v[174:177], v[206:209], v[2:5]
	s_barrier
	s_setprio 0
	s_add_i32 s54, s54, 2
	s_add_u32 s36, s36, 0x100
	s_addc_u32 s37, s37, 0
	s_add_u32 s52, s52, 0x100
	s_addc_u32 s53, s53, 0
	s_cmp_gt_u32 s54, 29
	s_cbranch_scc0 .LBB0_599
	s_and_b64 vcc, exec, s[12:13]
	s_cbranch_vccz .LBB0_602
	s_barrier

; __device__ __forceinline__ unsigned xb_add(unsigned* p, unsigned v) { return __hip_atomic_fetch_add(p, v, __ATOMIC_RELAXED, __HIP_MEMORY_SCOPE_AGENT); }
; __device__ __forceinline__ void xcd_barrier(const XcdBarrier& b) {
;     asm volatile("s_waitcnt vmcnt(0)" ::: "memory");
;     __syncthreads();
;     if (threadIdx.x == 0) {
;         unsigned* bar = b.bar;
;         __builtin_amdgcn_s_waitcnt(0);
;         unsigned nloc = b.st[0], nx = b.st[1];
;         if (nloc == 0u) { xcd_barrier_complete(bar, b.x, nloc, nx); b.st[0] = nloc; b.st[1] = nx; }
;         const unsigned old = xb_add(&bar[XB_XSUB(b.x)], 1u);
;         const unsigned gen = old / nloc;
; __global__ void __launch_bounds__(NTHR, 2) fwd_mega(Args args) {
;     ...
;         in_rep = 0;
;         if (ph + 1 < ph_hi) { if (ph == ph_lo) grid.sync(); else xcd_barrier(bar); }
.LBB0_697:
	s_setprio 0
	s_cmp_lg_u32 s95, -1
	v_readlane_b32 s1, v253, 55
	s_cselect_b64 s[4:5], -1, 0
	s_cmp_lg_u32 s1, 0
	s_cselect_b64 s[6:7], -1, 0
	s_or_b64 s[4:5], s[4:5], s[6:7]
	s_and_b64 vcc, exec, s[4:5]
	s_cbranch_vccnz .LBB0_709
	s_waitcnt vmcnt(0)
	s_waitcnt vmcnt(0) lgkmcnt(0)
	s_barrier
	s_mov_b64 s[4:5], exec
	v_readlane_b32 s6, v253, 8
	v_readlane_b32 s7, v253, 9
	v_readlane_b32 s20, v253, 58
	v_readlane_b32 s22, v253, 60
	v_readlane_b32 s26, v253, 62
	v_readlane_b32 s36, v254, 0
	v_readlane_b32 s40, v254, 2
	v_readlane_b32 s42, v254, 4
	v_readlane_b32 s44, v254, 6
	v_readlane_b32 s46, v254, 8
	v_readlane_b32 s48, v254, 10
	s_and_b64 s[6:7], s[4:5], s[6:7]
	v_readlane_b32 s21, v253, 59
	v_readlane_b32 s23, v253, 61
	v_readlane_b32 s27, v253, 63
	v_readlane_b32 s37, v254, 1
	v_readlane_b32 s41, v254, 3
	v_readlane_b32 s43, v254, 5
	v_readlane_b32 s45, v254, 7
	v_readlane_b32 s47, v254, 9
	v_readlane_b32 s49, v254, 11
	s_mov_b64 exec, s[6:7]
	s_cbranch_execz .LBB0_752
	v_readlane_b32 s1, v253, 53
	s_waitcnt vmcnt(0) expcnt(0) lgkmcnt(0)
	s_nop 0
	v_mov_b32_e32 v0, s1
	ds_read_b32 v3, v0
	v_readlane_b32 s1, v253, 54
	s_waitcnt lgkmcnt(0)
	v_cmp_ne_u32_e32 vcc, 0, v3
	v_mov_b32_e32 v0, s1
	ds_read_b32 v2, v0
	s_cbranch_vccnz .LBB0_716
	s_mov_b32 s1, 1
	s_branch .LBB0_702
